# plus GEMM phase head: s_setprio 1 in front of the opening barrier, redundant second lgkmcnt(0) and the cancelling mid-phase priority flip removed
# speedup vs baseline: 1.0035x; 1.0007x over previous
.LBB0_298:
	s_lshl_b64 s[4:5], s[20:21], 17
	s_add_u32 s24, s2, s4
	s_addc_u32 s25, s19, s5
	s_and_b64 s[4:5], s[36:37], exec
	s_cselect_b32 s37, s25, s31
	s_cselect_b32 s36, s24, s30
	s_add_u32 s56, s30, 0x100
	s_addc_u32 s57, s31, 0
	s_add_u32 s80, s34, 0x100
	s_addc_u32 s81, s35, 0
	s_add_u32 s38, s30, 0x180
	s_addc_u32 s39, s31, 0
	s_add_i32 s4, 0, 0x10000
	s_add_i32 s17, 0, 0x14000
	v_add_u32_e32 v128, s4, v134
	v_add_u32_e32 v129, s17, v134
	ds_read_b128 v[0:3], v128
	ds_read_b128 v[4:7], v128 offset:1024
	ds_read_b128 v[8:11], v128 offset:2048
	ds_read_b128 v[12:15], v128 offset:3072
	ds_read_b128 v[16:19], v129
	ds_read_b128 v[20:23], v129 offset:1024
	ds_read_b128 v[24:27], v129 offset:2048
	ds_read_b128 v[28:31], v129 offset:3072
	s_add_u32 s70, s30, 0x10080
	s_addc_u32 s71, s31, 0
	s_add_i32 s5, s13, 0xc000
	s_mov_b32 m0, s5
	s_add_i32 s15, s13, 0xe000
	ds_read_b128 v[32:35], v135
	ds_read_b128 v[36:39], v135 offset:1024
	ds_read_b128 v[40:43], v135 offset:2048
	ds_read_b128 v[44:47], v135 offset:3072
	ds_read_b128 v[48:51], v135 offset:4096
	ds_read_b128 v[52:55], v135 offset:5120
	ds_read_b128 v[56:59], v135 offset:6144
	ds_read_b128 v[60:63], v135 offset:7168
	s_nop 0
	global_load_lds_dwordx4 v130, s[70:71]
	s_mov_b32 m0, s15
	s_nop 0
	global_load_lds_dwordx4 v132, s[70:71]
	s_waitcnt vmcnt(8)
	s_waitcnt lgkmcnt(0)
	s_setprio 1
	s_barrier
	v_mfma_f32_16x16x32_bf16 v[64:67], v[0:3], v[32:35], 0
	v_mfma_f32_16x16x32_bf16 v[68:71], v[8:11], v[32:35], 0
	v_mfma_f32_16x16x32_bf16 v[72:75], v[0:3], v[40:43], 0
	v_mfma_f32_16x16x32_bf16 v[76:79], v[8:11], v[40:43], 0
	v_mfma_f32_16x16x32_bf16 v[80:83], v[0:3], v[48:51], 0
	v_mfma_f32_16x16x32_bf16 v[84:87], v[8:11], v[48:51], 0
	v_mfma_f32_16x16x32_bf16 v[88:91], v[0:3], v[56:59], 0
	v_mfma_f32_16x16x32_bf16 v[92:95], v[8:11], v[56:59], 0
	v_mfma_f32_16x16x32_bf16 v[64:67], v[4:7], v[36:39], v[64:67]
	v_mfma_f32_16x16x32_bf16 v[68:71], v[12:15], v[36:39], v[68:71]
	v_mfma_f32_16x16x32_bf16 v[72:75], v[4:7], v[44:47], v[72:75]
	v_mfma_f32_16x16x32_bf16 v[76:79], v[12:15], v[44:47], v[76:79]
	v_mfma_f32_16x16x32_bf16 v[80:83], v[4:7], v[52:55], v[80:83]
	v_mfma_f32_16x16x32_bf16 v[84:87], v[12:15], v[52:55], v[84:87]
	v_mfma_f32_16x16x32_bf16 v[88:91], v[4:7], v[60:63], v[88:91]
	v_mfma_f32_16x16x32_bf16 v[92:95], v[12:15], v[60:63], v[92:95]
	v_mfma_f32_16x16x32_bf16 v[96:99], v[16:19], v[32:35], 0
	v_mfma_f32_16x16x32_bf16 v[32:35], v[24:27], v[32:35], 0
	v_mfma_f32_16x16x32_bf16 v[96:99], v[20:23], v[36:39], v[96:99]
	v_mfma_f32_16x16x32_bf16 v[32:35], v[28:31], v[36:39], v[32:35]
	v_mfma_f32_16x16x32_bf16 v[36:39], v[16:19], v[40:43], 0
	v_mfma_f32_16x16x32_bf16 v[40:43], v[24:27], v[40:43], 0
	v_mfma_f32_16x16x32_bf16 v[36:39], v[20:23], v[44:47], v[36:39]
	v_mfma_f32_16x16x32_bf16 v[40:43], v[28:31], v[44:47], v[40:43]
	v_mfma_f32_16x16x32_bf16 v[44:47], v[16:19], v[48:51], 0
	v_mfma_f32_16x16x32_bf16 v[48:51], v[24:27], v[48:51], 0
	v_mfma_f32_16x16x32_bf16 v[44:47], v[20:23], v[52:55], v[44:47]
	v_mfma_f32_16x16x32_bf16 v[48:51], v[28:31], v[52:55], v[48:51]
	v_mfma_f32_16x16x32_bf16 v[52:55], v[16:19], v[56:59], 0
	v_mfma_f32_16x16x32_bf16 v[56:59], v[24:27], v[56:59], 0
	v_mfma_f32_16x16x32_bf16 v[52:55], v[20:23], v[60:63], v[52:55]
	v_mfma_f32_16x16x32_bf16 v[56:59], v[28:31], v[60:63], v[56:59]
	s_setprio 0
	s_barrier
	s_add_i32 s70, s4, s97
	s_add_i32 s4, s70, 0x2000
	s_mov_b32 m0, s70
	s_add_u32 s74, s34, 0x80100
	ds_read_b128 v[60:63], v135 offset:16384
	ds_read_b128 v[100:103], v135 offset:17408
	ds_read_b128 v[104:107], v135 offset:18432
	ds_read_b128 v[108:111], v135 offset:19456
	ds_read_b128 v[112:115], v135 offset:20480
	ds_read_b128 v[116:119], v135 offset:21504
	ds_read_b128 v[120:123], v135 offset:22528
	ds_read_b128 v[124:127], v135 offset:23552
	s_addc_u32 s75, s35, 0
	global_load_lds_dwordx4 v131, s[80:81]
	s_mov_b32 m0, s4
	s_add_i32 s17, s17, s97
	s_add_i32 s21, s17, 0x2000
	global_load_lds_dwordx4 v133, s[80:81]
	s_mov_b32 m0, s17
	s_nop 0
	global_load_lds_dwordx4 v131, s[74:75]
	s_mov_b32 m0, s21
	s_nop 0
	global_load_lds_dwordx4 v133, s[74:75]
	s_mov_b32 m0, s13
	s_nop 0
	global_load_lds_dwordx4 v130, s[56:57]
	s_mov_b32 m0, s27
	s_nop 0
	global_load_lds_dwordx4 v132, s[56:57]
	s_waitcnt vmcnt(8)
	s_waitcnt lgkmcnt(0)
	s_setprio 1
	s_barrier
	v_mfma_f32_16x16x32_bf16 v[136:139], v[0:3], v[60:63], 0
	v_mfma_f32_16x16x32_bf16 v[144:147], v[0:3], v[104:107], 0
	v_mfma_f32_16x16x32_bf16 v[152:155], v[0:3], v[112:115], 0
	v_mfma_f32_16x16x32_bf16 v[0:3], v[0:3], v[120:123], 0
	v_mfma_f32_16x16x32_bf16 v[136:139], v[4:7], v[100:103], v[136:139]
	v_mfma_f32_16x16x32_bf16 v[144:147], v[4:7], v[108:111], v[144:147]
	v_mfma_f32_16x16x32_bf16 v[152:155], v[4:7], v[116:119], v[152:155]
	v_mfma_f32_16x16x32_bf16 v[0:3], v[4:7], v[124:127], v[0:3]
	v_mfma_f32_16x16x32_bf16 v[4:7], v[8:11], v[120:123], 0
	v_mfma_f32_16x16x32_bf16 v[140:143], v[8:11], v[60:63], 0
	v_mfma_f32_16x16x32_bf16 v[148:151], v[8:11], v[104:107], 0
	v_mfma_f32_16x16x32_bf16 v[156:159], v[8:11], v[112:115], 0
	v_mfma_f32_16x16x32_bf16 v[4:7], v[12:15], v[124:127], v[4:7]
	v_mfma_f32_16x16x32_bf16 v[140:143], v[12:15], v[100:103], v[140:143]
	v_mfma_f32_16x16x32_bf16 v[148:151], v[12:15], v[108:111], v[148:151]
	v_mfma_f32_16x16x32_bf16 v[156:159], v[12:15], v[116:119], v[156:159]
	v_mfma_f32_16x16x32_bf16 v[8:11], v[16:19], v[60:63], 0
	v_mfma_f32_16x16x32_bf16 v[12:15], v[24:27], v[60:63], 0
	v_mfma_f32_16x16x32_bf16 v[8:11], v[20:23], v[100:103], v[8:11]
	v_mfma_f32_16x16x32_bf16 v[12:15], v[28:31], v[100:103], v[12:15]
	v_mfma_f32_16x16x32_bf16 v[60:63], v[16:19], v[104:107], 0
	v_mfma_f32_16x16x32_bf16 v[100:103], v[24:27], v[104:107], 0
	v_mfma_f32_16x16x32_bf16 v[104:107], v[16:19], v[112:115], 0
	v_mfma_f32_16x16x32_bf16 v[16:19], v[16:19], v[120:123], 0
	v_mfma_f32_16x16x32_bf16 v[60:63], v[20:23], v[108:111], v[60:63]
	v_mfma_f32_16x16x32_bf16 v[100:103], v[28:31], v[108:111], v[100:103]
	v_mfma_f32_16x16x32_bf16 v[104:107], v[20:23], v[116:119], v[104:107]
	v_mfma_f32_16x16x32_bf16 v[108:111], v[24:27], v[112:115], 0
	v_mfma_f32_16x16x32_bf16 v[16:19], v[20:23], v[124:127], v[16:19]
	v_mfma_f32_16x16x32_bf16 v[20:23], v[24:27], v[120:123], 0
	v_mfma_f32_16x16x32_bf16 v[108:111], v[28:31], v[116:119], v[108:111]
	v_mfma_f32_16x16x32_bf16 v[20:23], v[28:31], v[124:127], v[20:23]
	s_setprio 0
	s_barrier
	s_add_i32 s71, 0, 0x18000
	s_add_i32 s69, 0, 0x1c000
	v_add_u32_e32 v196, s71, v134
	v_add_u32_e32 v198, s69, v134
	ds_read_b128 v[24:27], v196
	ds_read_b128 v[28:31], v196 offset:1024
	ds_read_b128 v[112:115], v196 offset:2048
	ds_read_b128 v[116:119], v196 offset:3072
	ds_read_b128 v[120:123], v198
	ds_read_b128 v[124:127], v198 offset:1024
	ds_read_b128 v[160:163], v198 offset:2048
	ds_read_b128 v[164:167], v198 offset:3072
	s_add_u32 s56, s30, 0x10100
	s_addc_u32 s57, s31, 0
	s_mov_b32 m0, s29
	ds_read_b128 v[168:171], v135 offset:32768
	ds_read_b128 v[172:175], v135 offset:33792
	ds_read_b128 v[176:179], v135 offset:34816
	ds_read_b128 v[180:183], v135 offset:35840
	ds_read_b128 v[184:187], v135 offset:36864
	ds_read_b128 v[188:191], v135 offset:37888
	ds_read_b128 v[192:195], v135 offset:38912
	ds_read_b128 v[200:203], v135 offset:39936
	s_nop 0
	global_load_lds_dwordx4 v130, s[56:57]
	s_mov_b32 m0, s47
	s_nop 0
	global_load_lds_dwordx4 v132, s[56:57]
	s_waitcnt vmcnt(8)
	s_waitcnt lgkmcnt(0)
	s_setprio 1
	s_barrier
	v_mfma_f32_16x16x32_bf16 v[64:67], v[24:27], v[168:171], v[64:67]
	v_mfma_f32_16x16x32_bf16 v[64:67], v[28:31], v[172:175], v[64:67]
	v_mfma_f32_16x16x32_bf16 v[68:71], v[112:115], v[168:171], v[68:71]
	v_mfma_f32_16x16x32_bf16 v[68:71], v[116:119], v[172:175], v[68:71]
	v_mfma_f32_16x16x32_bf16 v[72:75], v[24:27], v[176:179], v[72:75]
	v_mfma_f32_16x16x32_bf16 v[72:75], v[28:31], v[180:183], v[72:75]
	v_mfma_f32_16x16x32_bf16 v[76:79], v[112:115], v[176:179], v[76:79]
	v_mfma_f32_16x16x32_bf16 v[76:79], v[116:119], v[180:183], v[76:79]
	v_mfma_f32_16x16x32_bf16 v[80:83], v[24:27], v[184:187], v[80:83]
	v_mfma_f32_16x16x32_bf16 v[80:83], v[28:31], v[188:191], v[80:83]
	v_mfma_f32_16x16x32_bf16 v[84:87], v[112:115], v[184:187], v[84:87]
	v_mfma_f32_16x16x32_bf16 v[84:87], v[116:119], v[188:191], v[84:87]
	v_mfma_f32_16x16x32_bf16 v[88:91], v[24:27], v[192:195], v[88:91]
	v_mfma_f32_16x16x32_bf16 v[88:91], v[28:31], v[200:203], v[88:91]
	v_mfma_f32_16x16x32_bf16 v[92:95], v[112:115], v[192:195], v[92:95]
	v_mfma_f32_16x16x32_bf16 v[92:95], v[116:119], v[200:203], v[92:95]
	v_mfma_f32_16x16x32_bf16 v[96:99], v[120:123], v[168:171], v[96:99]
	v_mfma_f32_16x16x32_bf16 v[96:99], v[124:127], v[172:175], v[96:99]
	v_mfma_f32_16x16x32_bf16 v[32:35], v[160:163], v[168:171], v[32:35]
	v_mfma_f32_16x16x32_bf16 v[32:35], v[164:167], v[172:175], v[32:35]
	v_mfma_f32_16x16x32_bf16 v[36:39], v[120:123], v[176:179], v[36:39]
	v_mfma_f32_16x16x32_bf16 v[36:39], v[124:127], v[180:183], v[36:39]
	v_mfma_f32_16x16x32_bf16 v[40:43], v[160:163], v[176:179], v[40:43]
	v_mfma_f32_16x16x32_bf16 v[40:43], v[164:167], v[180:183], v[40:43]
	v_mfma_f32_16x16x32_bf16 v[44:47], v[120:123], v[184:187], v[44:47]
	v_mfma_f32_16x16x32_bf16 v[44:47], v[124:127], v[188:191], v[44:47]
	v_mfma_f32_16x16x32_bf16 v[48:51], v[160:163], v[184:187], v[48:51]
	v_mfma_f32_16x16x32_bf16 v[48:51], v[164:167], v[188:191], v[48:51]
	v_mfma_f32_16x16x32_bf16 v[52:55], v[120:123], v[192:195], v[52:55]
	v_mfma_f32_16x16x32_bf16 v[52:55], v[124:127], v[200:203], v[52:55]
	v_mfma_f32_16x16x32_bf16 v[56:59], v[160:163], v[192:195], v[56:59]
	v_mfma_f32_16x16x32_bf16 v[56:59], v[164:167], v[200:203], v[56:59]
	s_setprio 0
	s_barrier
	s_add_u32 s74, s34, 0x180
	s_addc_u32 s75, s35, 0
	s_add_i32 s71, s71, s97
	s_add_i32 s56, s71, 0x2000
	s_mov_b32 m0, s71
	s_add_u32 s34, s34, 0x80180
	ds_read_b128 v[168:171], v135 offset:49152
	ds_read_b128 v[172:175], v135 offset:50176
	ds_read_b128 v[176:179], v135 offset:51200
	ds_read_b128 v[180:183], v135 offset:52224
	ds_read_b128 v[184:187], v135 offset:53248
	ds_read_b128 v[188:191], v135 offset:54272
	ds_read_b128 v[192:195], v135 offset:55296
	ds_read_b128 v[200:203], v135 offset:56320
	s_addc_u32 s35, s35, 0
	global_load_lds_dwordx4 v131, s[74:75]
	s_mov_b32 m0, s56
	s_add_i32 s57, s69, s97
	s_add_i32 s69, s57, 0x2000
	global_load_lds_dwordx4 v133, s[74:75]
	s_mov_b32 m0, s57
	s_nop 0
	global_load_lds_dwordx4 v131, s[34:35]
	s_mov_b32 m0, s69
	s_nop 0
	global_load_lds_dwordx4 v133, s[34:35]
	s_mov_b32 m0, s48
	s_nop 0
	global_load_lds_dwordx4 v130, s[38:39]
	s_mov_b32 m0, s49
	s_nop 0
	global_load_lds_dwordx4 v132, s[38:39]
	s_waitcnt vmcnt(8)
	s_waitcnt lgkmcnt(0)
	s_setprio 1
	s_barrier
	v_mfma_f32_16x16x32_bf16 v[0:3], v[24:27], v[192:195], v[0:3]
	v_mfma_f32_16x16x32_bf16 v[0:3], v[28:31], v[200:203], v[0:3]
	v_mfma_f32_16x16x32_bf16 v[4:7], v[112:115], v[192:195], v[4:7]
	v_mfma_f32_16x16x32_bf16 v[4:7], v[116:119], v[200:203], v[4:7]
	v_mfma_f32_16x16x32_bf16 v[136:139], v[24:27], v[168:171], v[136:139]
	v_mfma_f32_16x16x32_bf16 v[136:139], v[28:31], v[172:175], v[136:139]
	v_mfma_f32_16x16x32_bf16 v[140:143], v[112:115], v[168:171], v[140:143]
	v_mfma_f32_16x16x32_bf16 v[140:143], v[116:119], v[172:175], v[140:143]
	v_mfma_f32_16x16x32_bf16 v[144:147], v[24:27], v[176:179], v[144:147]
	v_mfma_f32_16x16x32_bf16 v[144:147], v[28:31], v[180:183], v[144:147]
	v_mfma_f32_16x16x32_bf16 v[148:151], v[112:115], v[176:179], v[148:151]
	v_mfma_f32_16x16x32_bf16 v[148:151], v[116:119], v[180:183], v[148:151]
	v_mfma_f32_16x16x32_bf16 v[152:155], v[24:27], v[184:187], v[152:155]
	v_mfma_f32_16x16x32_bf16 v[152:155], v[28:31], v[188:191], v[152:155]
	v_mfma_f32_16x16x32_bf16 v[156:159], v[112:115], v[184:187], v[156:159]
	v_mfma_f32_16x16x32_bf16 v[156:159], v[116:119], v[188:191], v[156:159]
	v_mfma_f32_16x16x32_bf16 v[8:11], v[120:123], v[168:171], v[8:11]
	v_mfma_f32_16x16x32_bf16 v[12:15], v[160:163], v[168:171], v[12:15]
	v_mfma_f32_16x16x32_bf16 v[24:27], v[120:123], v[176:179], v[60:63]
	v_mfma_f32_16x16x32_bf16 v[28:31], v[160:163], v[176:179], v[100:103]
	v_mfma_f32_16x16x32_bf16 v[60:63], v[120:123], v[184:187], v[104:107]
	v_mfma_f32_16x16x32_bf16 v[100:103], v[160:163], v[184:187], v[108:111]
	v_mfma_f32_16x16x32_bf16 v[16:19], v[120:123], v[192:195], v[16:19]
	v_mfma_f32_16x16x32_bf16 v[20:23], v[160:163], v[192:195], v[20:23]
	v_mfma_f32_16x16x32_bf16 v[8:11], v[124:127], v[172:175], v[8:11]
	v_mfma_f32_16x16x32_bf16 v[12:15], v[164:167], v[172:175], v[12:15]
	v_mfma_f32_16x16x32_bf16 v[24:27], v[124:127], v[180:183], v[24:27]
	v_mfma_f32_16x16x32_bf16 v[28:31], v[164:167], v[180:183], v[28:31]
	v_mfma_f32_16x16x32_bf16 v[60:63], v[124:127], v[188:191], v[60:63]
	v_mfma_f32_16x16x32_bf16 v[100:103], v[164:167], v[188:191], v[100:103]
	v_mfma_f32_16x16x32_bf16 v[16:19], v[124:127], v[200:203], v[16:19]
	v_mfma_f32_16x16x32_bf16 v[20:23], v[164:167], v[200:203], v[20:23]
	s_setprio 0
	s_barrier
	ds_read_b128 v[104:107], v128
	ds_read_b128 v[108:111], v128 offset:1024
	ds_read_b128 v[112:115], v128 offset:2048
	ds_read_b128 v[116:119], v128 offset:3072
	ds_read_b128 v[120:123], v129
	ds_read_b128 v[124:127], v129 offset:1024
	ds_read_b128 v[160:163], v129 offset:2048
	ds_read_b128 v[164:167], v129 offset:3072
	s_add_u32 s34, s36, 0x80
	s_addc_u32 s35, s37, 0
	s_add_u32 s30, s30, 0x10180
	s_addc_u32 s31, s31, 0
	s_mov_b32 m0, s5
	ds_read_b128 v[168:171], v135
	ds_read_b128 v[172:175], v135 offset:1024
	ds_read_b128 v[176:179], v135 offset:2048
	ds_read_b128 v[180:183], v135 offset:3072
	ds_read_b128 v[184:187], v135 offset:4096
	ds_read_b128 v[188:191], v135 offset:5120
	ds_read_b128 v[192:195], v135 offset:6144
	ds_read_b128 v[200:203], v135 offset:7168
	s_nop 0
	global_load_lds_dwordx4 v130, s[30:31]
	s_mov_b32 m0, s15
	s_nop 0
	global_load_lds_dwordx4 v132, s[30:31]
	s_waitcnt vmcnt(8)
	s_waitcnt lgkmcnt(0)
	s_setprio 1
	s_barrier
	v_mfma_f32_16x16x32_bf16 v[64:67], v[104:107], v[168:171], v[64:67]
	v_mfma_f32_16x16x32_bf16 v[64:67], v[108:111], v[172:175], v[64:67]
	v_mfma_f32_16x16x32_bf16 v[68:71], v[112:115], v[168:171], v[68:71]
	v_mfma_f32_16x16x32_bf16 v[68:71], v[116:119], v[172:175], v[68:71]
	v_mfma_f32_16x16x32_bf16 v[72:75], v[104:107], v[176:179], v[72:75]
	v_mfma_f32_16x16x32_bf16 v[72:75], v[108:111], v[180:183], v[72:75]
	v_mfma_f32_16x16x32_bf16 v[76:79], v[112:115], v[176:179], v[76:79]
	v_mfma_f32_16x16x32_bf16 v[76:79], v[116:119], v[180:183], v[76:79]
	v_mfma_f32_16x16x32_bf16 v[80:83], v[104:107], v[184:187], v[80:83]
	v_mfma_f32_16x16x32_bf16 v[80:83], v[108:111], v[188:191], v[80:83]
	v_mfma_f32_16x16x32_bf16 v[84:87], v[112:115], v[184:187], v[84:87]
	v_mfma_f32_16x16x32_bf16 v[84:87], v[116:119], v[188:191], v[84:87]
	v_mfma_f32_16x16x32_bf16 v[88:91], v[104:107], v[192:195], v[88:91]
	v_mfma_f32_16x16x32_bf16 v[88:91], v[108:111], v[200:203], v[88:91]
	v_mfma_f32_16x16x32_bf16 v[92:95], v[112:115], v[192:195], v[92:95]
	v_mfma_f32_16x16x32_bf16 v[92:95], v[116:119], v[200:203], v[92:95]
	v_mfma_f32_16x16x32_bf16 v[32:35], v[160:163], v[168:171], v[32:35]
	v_mfma_f32_16x16x32_bf16 v[96:99], v[120:123], v[168:171], v[96:99]
	v_mfma_f32_16x16x32_bf16 v[168:171], v[164:167], v[172:175], v[32:35]
	v_mfma_f32_16x16x32_bf16 v[32:35], v[120:123], v[176:179], v[36:39]
	v_mfma_f32_16x16x32_bf16 v[36:39], v[124:127], v[180:183], v[32:35]
	v_mfma_f32_16x16x32_bf16 v[32:35], v[160:163], v[176:179], v[40:43]
	v_mfma_f32_16x16x32_bf16 v[204:207], v[124:127], v[172:175], v[96:99]
	v_mfma_f32_16x16x32_bf16 v[172:175], v[164:167], v[180:183], v[32:35]
	v_mfma_f32_16x16x32_bf16 v[32:35], v[120:123], v[184:187], v[44:47]
	v_mfma_f32_16x16x32_bf16 v[44:47], v[124:127], v[188:191], v[32:35]
	v_mfma_f32_16x16x32_bf16 v[32:35], v[160:163], v[184:187], v[48:51]
	v_mfma_f32_16x16x32_bf16 v[48:51], v[164:167], v[188:191], v[32:35]
	v_mfma_f32_16x16x32_bf16 v[32:35], v[120:123], v[192:195], v[52:55]
	v_mfma_f32_16x16x32_bf16 v[52:55], v[124:127], v[200:203], v[32:35]
	v_mfma_f32_16x16x32_bf16 v[32:35], v[160:163], v[192:195], v[56:59]
	v_mfma_f32_16x16x32_bf16 v[56:59], v[164:167], v[200:203], v[32:35]
	s_setprio 0
	s_barrier
	s_mov_b32 m0, s70
	s_mov_b64 s[30:31], s[22:23]
	s_nop 2
	ds_read_b128 v[32:35], v135 offset:16384
	ds_read_b128 v[40:43], v135 offset:17408
	ds_read_b128 v[96:99], v135 offset:18432
	ds_read_b128 v[176:179], v135 offset:19456
	ds_read_b128 v[180:183], v135 offset:20480
	ds_read_b128 v[184:187], v135 offset:21504
	ds_read_b128 v[188:191], v135 offset:22528
	ds_read_b128 v[192:195], v135 offset:23552
	s_nop 0
	global_load_lds_dwordx4 v131, s[30:31]
	s_mov_b32 m0, s4
	s_add_u32 s4, s22, 0x80000
	s_addc_u32 s5, s23, 0
	global_load_lds_dwordx4 v133, s[30:31]
	s_mov_b32 m0, s17
	s_nop 0
	global_load_lds_dwordx4 v131, s[4:5]
	s_mov_b32 m0, s21
	s_nop 0
	global_load_lds_dwordx4 v133, s[4:5]
	s_mov_b64 s[4:5], s[36:37]
	s_mov_b32 m0, s13
	s_nop 0
	global_load_lds_dwordx4 v130, s[4:5]
	s_mov_b32 m0, s27
	s_nop 0
	global_load_lds_dwordx4 v132, s[4:5]
	s_waitcnt vmcnt(8)
	s_waitcnt lgkmcnt(0)
	s_setprio 1
	s_barrier
	v_mfma_f32_16x16x32_bf16 v[0:3], v[104:107], v[188:191], v[0:3]
	v_mfma_f32_16x16x32_bf16 v[0:3], v[108:111], v[192:195], v[0:3]
	v_mfma_f32_16x16x32_bf16 v[4:7], v[112:115], v[188:191], v[4:7]
	v_mfma_f32_16x16x32_bf16 v[4:7], v[116:119], v[192:195], v[4:7]
	v_mfma_f32_16x16x32_bf16 v[136:139], v[104:107], v[32:35], v[136:139]
	v_mfma_f32_16x16x32_bf16 v[136:139], v[108:111], v[40:43], v[136:139]
	v_mfma_f32_16x16x32_bf16 v[140:143], v[112:115], v[32:35], v[140:143]
	v_mfma_f32_16x16x32_bf16 v[140:143], v[116:119], v[40:43], v[140:143]
	v_mfma_f32_16x16x32_bf16 v[144:147], v[104:107], v[96:99], v[144:147]
	v_mfma_f32_16x16x32_bf16 v[144:147], v[108:111], v[176:179], v[144:147]
	v_mfma_f32_16x16x32_bf16 v[148:151], v[112:115], v[96:99], v[148:151]
	v_mfma_f32_16x16x32_bf16 v[148:151], v[116:119], v[176:179], v[148:151]
	v_mfma_f32_16x16x32_bf16 v[152:155], v[104:107], v[180:183], v[152:155]
	v_mfma_f32_16x16x32_bf16 v[152:155], v[108:111], v[184:187], v[152:155]
	v_mfma_f32_16x16x32_bf16 v[156:159], v[112:115], v[180:183], v[156:159]
	v_mfma_f32_16x16x32_bf16 v[156:159], v[116:119], v[184:187], v[156:159]
	v_mfma_f32_16x16x32_bf16 v[12:15], v[160:163], v[32:35], v[12:15]
	v_mfma_f32_16x16x32_bf16 v[200:203], v[164:167], v[40:43], v[12:15]
	v_mfma_f32_16x16x32_bf16 v[12:15], v[120:123], v[96:99], v[24:27]
	v_mfma_f32_16x16x32_bf16 v[24:27], v[124:127], v[176:179], v[12:15]
	v_mfma_f32_16x16x32_bf16 v[12:15], v[160:163], v[96:99], v[28:31]
	v_mfma_f32_16x16x32_bf16 v[176:179], v[164:167], v[176:179], v[12:15]
	v_mfma_f32_16x16x32_bf16 v[12:15], v[120:123], v[180:183], v[60:63]
	v_mfma_f32_16x16x32_bf16 v[208:211], v[124:127], v[184:187], v[12:15]
	v_mfma_f32_16x16x32_bf16 v[12:15], v[160:163], v[180:183], v[100:103]
	v_mfma_f32_16x16x32_bf16 v[8:11], v[120:123], v[32:35], v[8:11]
	v_mfma_f32_16x16x32_bf16 v[180:183], v[164:167], v[184:187], v[12:15]
	v_mfma_f32_16x16x32_bf16 v[12:15], v[120:123], v[188:191], v[16:19]
	v_mfma_f32_16x16x32_bf16 v[8:11], v[124:127], v[40:43], v[8:11]
	v_mfma_f32_16x16x32_bf16 v[184:187], v[124:127], v[192:195], v[12:15]
	v_mfma_f32_16x16x32_bf16 v[12:15], v[160:163], v[188:191], v[20:23]
	v_mfma_f32_16x16x32_bf16 v[160:163], v[164:167], v[192:195], v[12:15]
	s_setprio 0
	s_barrier
	s_nop 4
	ds_read_b128 v[12:15], v196
	ds_read_b128 v[16:19], v196 offset:1024
	ds_read_b128 v[164:167], v196 offset:2048
	ds_read_b128 v[188:191], v196 offset:3072
	ds_read_b128 v[192:195], v198
	ds_read_b128 v[220:223], v198 offset:1024
	ds_read_b128 v[224:227], v198 offset:2048
	ds_read_b128 v[228:231], v198 offset:3072
	s_add_u32 s4, s36, 0x10000
	s_addc_u32 s5, s37, 0
	s_mov_b32 m0, s29
	ds_read_b128 v[20:23], v135 offset:32768
	ds_read_b128 v[28:31], v135 offset:33792
	ds_read_b128 v[60:63], v135 offset:34816
	ds_read_b128 v[100:103], v135 offset:35840
	ds_read_b128 v[232:235], v135 offset:36864
	ds_read_b128 v[236:239], v135 offset:37888
	ds_read_b128 v[240:243], v135 offset:38912
	ds_read_b128 v[244:247], v135 offset:39936
	s_nop 0
	global_load_lds_dwordx4 v130, s[4:5]
	s_mov_b32 m0, s47
	s_nop 0
	global_load_lds_dwordx4 v132, s[4:5]
	s_waitcnt vmcnt(8)
	s_waitcnt lgkmcnt(0)
	s_setprio 1
	s_barrier
	v_mfma_f32_16x16x32_bf16 v[32:35], v[12:15], v[20:23], v[64:67]
	v_mfma_f32_16x16x32_bf16 v[120:123], v[16:19], v[28:31], v[32:35]
	v_mfma_f32_16x16x32_bf16 v[32:35], v[164:167], v[20:23], v[68:71]
	v_mfma_f32_16x16x32_bf16 v[112:115], v[188:191], v[28:31], v[32:35]
	v_mfma_f32_16x16x32_bf16 v[32:35], v[12:15], v[60:63], v[72:75]
	v_mfma_f32_16x16x32_bf16 v[104:107], v[16:19], v[100:103], v[32:35]
	v_mfma_f32_16x16x32_bf16 v[32:35], v[164:167], v[60:63], v[76:79]
	v_mfma_f32_16x16x32_bf16 v[96:99], v[188:191], v[100:103], v[32:35]
	v_mfma_f32_16x16x32_bf16 v[32:35], v[12:15], v[232:235], v[80:83]
	v_mfma_f32_16x16x32_bf16 v[72:75], v[16:19], v[236:239], v[32:35]
	v_mfma_f32_16x16x32_bf16 v[32:35], v[164:167], v[232:235], v[84:87]
	v_mfma_f32_16x16x32_bf16 v[64:67], v[188:191], v[236:239], v[32:35]
	v_mfma_f32_16x16x32_bf16 v[32:35], v[12:15], v[240:243], v[88:91]
	v_mfma_f32_16x16x32_bf16 v[40:43], v[16:19], v[244:247], v[32:35]
	v_mfma_f32_16x16x32_bf16 v[32:35], v[164:167], v[240:243], v[92:95]
	v_mfma_f32_16x16x32_bf16 v[32:35], v[188:191], v[244:247], v[32:35]
	v_mfma_f32_16x16x32_bf16 v[68:71], v[192:195], v[20:23], v[204:207]
	v_mfma_f32_16x16x32_bf16 v[20:23], v[224:227], v[20:23], v[168:171]
	v_mfma_f32_16x16x32_bf16 v[116:119], v[228:231], v[28:31], v[20:23]
	v_mfma_f32_16x16x32_bf16 v[20:23], v[192:195], v[60:63], v[36:39]
	v_mfma_f32_16x16x32_bf16 v[108:111], v[220:223], v[100:103], v[20:23]
	v_mfma_f32_16x16x32_bf16 v[20:23], v[224:227], v[60:63], v[172:175]
	v_mfma_f32_16x16x32_bf16 v[100:103], v[228:231], v[100:103], v[20:23]
	v_mfma_f32_16x16x32_bf16 v[20:23], v[192:195], v[232:235], v[44:47]
	v_mfma_f32_16x16x32_bf16 v[76:79], v[220:223], v[236:239], v[20:23]
	v_mfma_f32_16x16x32_bf16 v[20:23], v[224:227], v[232:235], v[48:51]
	v_mfma_f32_16x16x32_bf16 v[124:127], v[220:223], v[28:31], v[68:71]
	v_mfma_f32_16x16x32_bf16 v[68:71], v[228:231], v[236:239], v[20:23]
	v_mfma_f32_16x16x32_bf16 v[20:23], v[192:195], v[240:243], v[52:55]
	v_mfma_f32_16x16x32_bf16 v[44:47], v[220:223], v[244:247], v[20:23]
	v_mfma_f32_16x16x32_bf16 v[20:23], v[224:227], v[240:243], v[56:59]
	v_mfma_f32_16x16x32_bf16 v[36:39], v[228:231], v[244:247], v[20:23]
	s_setprio 0
	s_barrier
	s_add_u32 s4, s22, 0x80
	s_mov_b32 m0, s71
	s_addc_u32 s5, s23, 0
	ds_read_b128 v[48:51], v135 offset:49152
	ds_read_b128 v[56:59], v135 offset:50176
	ds_read_b128 v[168:171], v135 offset:51200
	ds_read_b128 v[172:175], v135 offset:52224
	ds_read_b128 v[204:207], v135 offset:53248
	ds_read_b128 v[232:235], v135 offset:54272
	ds_read_b128 v[236:239], v135 offset:55296
	ds_read_b128 v[240:243], v135 offset:56320
	s_nop 0
	global_load_lds_dwordx4 v131, s[4:5]
	s_mov_b32 m0, s56
	s_nop 0
	global_load_lds_dwordx4 v133, s[4:5]
	s_add_u32 s4, s22, 0x80080
	s_addc_u32 s5, s23, 0
	s_mov_b32 m0, s57
	s_nop 0
	global_load_lds_dwordx4 v131, s[4:5]
	s_mov_b32 m0, s69
	s_nop 0
	global_load_lds_dwordx4 v133, s[4:5]
	s_mov_b32 m0, s48
	s_nop 0
	global_load_lds_dwordx4 v130, s[34:35]
	s_mov_b32 m0, s49
	s_nop 0
	global_load_lds_dwordx4 v132, s[34:35]
	s_waitcnt vmcnt(8)
	s_waitcnt lgkmcnt(0)
	s_setprio 1
	s_barrier
	v_mfma_f32_16x16x32_bf16 v[20:23], v[12:15], v[48:51], v[136:139]
	v_mfma_f32_16x16x32_bf16 v[92:95], v[16:19], v[56:59], v[20:23]
	v_mfma_f32_16x16x32_bf16 v[20:23], v[164:167], v[48:51], v[140:143]
	v_mfma_f32_16x16x32_bf16 v[84:87], v[188:191], v[56:59], v[20:23]
	v_mfma_f32_16x16x32_bf16 v[20:23], v[12:15], v[168:171], v[144:147]
	v_mfma_f32_16x16x32_bf16 v[60:63], v[16:19], v[172:175], v[20:23]
	v_mfma_f32_16x16x32_bf16 v[20:23], v[164:167], v[168:171], v[148:151]
	v_mfma_f32_16x16x32_bf16 v[52:55], v[188:191], v[172:175], v[20:23]
	v_mfma_f32_16x16x32_bf16 v[20:23], v[12:15], v[204:207], v[152:155]
	v_mfma_f32_16x16x32_bf16 v[0:3], v[12:15], v[236:239], v[0:3]
	v_mfma_f32_16x16x32_bf16 v[28:31], v[16:19], v[232:235], v[20:23]
	v_mfma_f32_16x16x32_bf16 v[20:23], v[164:167], v[204:207], v[156:159]
	v_mfma_f32_16x16x32_bf16 v[12:15], v[16:19], v[240:243], v[0:3]
	v_mfma_f32_16x16x32_bf16 v[0:3], v[164:167], v[236:239], v[4:7]
	v_mfma_f32_16x16x32_bf16 v[20:23], v[188:191], v[232:235], v[20:23]
	v_mfma_f32_16x16x32_bf16 v[4:7], v[188:191], v[240:243], v[0:3]
	v_mfma_f32_16x16x32_bf16 v[0:3], v[192:195], v[48:51], v[8:11]
	v_mfma_f32_16x16x32_bf16 v[88:91], v[220:223], v[56:59], v[0:3]
	v_mfma_f32_16x16x32_bf16 v[0:3], v[224:227], v[48:51], v[200:203]
	v_mfma_f32_16x16x32_bf16 v[80:83], v[228:231], v[56:59], v[0:3]
	v_mfma_f32_16x16x32_bf16 v[0:3], v[192:195], v[168:171], v[24:27]
	v_mfma_f32_16x16x32_bf16 v[56:59], v[220:223], v[172:175], v[0:3]
	v_mfma_f32_16x16x32_bf16 v[0:3], v[224:227], v[168:171], v[176:179]
	v_mfma_f32_16x16x32_bf16 v[48:51], v[228:231], v[172:175], v[0:3]
	v_mfma_f32_16x16x32_bf16 v[0:3], v[192:195], v[204:207], v[208:211]
	v_mfma_f32_16x16x32_bf16 v[24:27], v[220:223], v[232:235], v[0:3]
	v_mfma_f32_16x16x32_bf16 v[0:3], v[224:227], v[204:207], v[180:183]
	v_mfma_f32_16x16x32_bf16 v[16:19], v[228:231], v[232:235], v[0:3]
	v_mfma_f32_16x16x32_bf16 v[0:3], v[192:195], v[236:239], v[184:187]
	v_mfma_f32_16x16x32_bf16 v[8:11], v[220:223], v[240:243], v[0:3]
	v_mfma_f32_16x16x32_bf16 v[0:3], v[224:227], v[236:239], v[160:163]
	v_mfma_f32_16x16x32_bf16 v[0:3], v[228:231], v[240:243], v[0:3]
	s_setprio 0
	s_barrier
	s_andn2_b64 vcc, exec, s[60:61]
	s_cbranch_vccnz .LBB0_300
	s_barrier

.LBB0_313:
	s_ashr_i32 s15, s14, 31
	s_lshl_b64 s[4:5], s[14:15], 17
	s_add_u32 s20, s2, s4
	s_addc_u32 s21, s19, s5
	s_and_b64 s[4:5], s[16:17], exec
	s_cselect_b32 s39, s21, s31
	s_cselect_b32 s38, s20, s30
	s_ashr_i32 s11, s10, 31
	s_lshl_b64 s[4:5], s[10:11], 9
	s_add_u32 s11, s44, s4
	s_addc_u32 s15, s46, s5
	s_ashr_i32 s13, s12, 31
	s_lshl_b64 s[4:5], s[12:13], 20
	s_add_u32 s22, s11, s4
	s_addc_u32 s23, s15, s5
	s_and_b64 s[4:5], s[16:17], exec
	s_cselect_b32 s35, s23, s37
	s_cselect_b32 s34, s22, s36
	s_add_u32 s56, s30, 0x100
	s_addc_u32 s57, s31, 0
	s_add_u32 s82, s36, 0x100
	s_addc_u32 s83, s37, 0
	s_add_u32 s80, s30, 0x180
	s_addc_u32 s81, s31, 0
	s_add_i32 s4, 0, 0x10000
	s_add_i32 s13, 0, 0x14000
	v_add_u32_e32 v128, s4, v134
	v_add_u32_e32 v129, s13, v134
	ds_read_b128 v[0:3], v128
	ds_read_b128 v[4:7], v128 offset:1024
	ds_read_b128 v[8:11], v128 offset:2048
	ds_read_b128 v[12:15], v128 offset:3072
	ds_read_b128 v[16:19], v129
	ds_read_b128 v[20:23], v129 offset:1024
	ds_read_b128 v[24:27], v129 offset:2048
	ds_read_b128 v[28:31], v129 offset:3072
	s_add_u32 s70, s30, 0x10080
	s_addc_u32 s71, s31, 0
	s_add_i32 s5, s25, 0xc000
	s_mov_b32 m0, s5
	s_add_i32 s11, s25, 0xe000
	ds_read_b128 v[32:35], v135
	ds_read_b128 v[36:39], v135 offset:1024
	ds_read_b128 v[40:43], v135 offset:2048
	ds_read_b128 v[44:47], v135 offset:3072
	ds_read_b128 v[48:51], v135 offset:4096
	ds_read_b128 v[52:55], v135 offset:5120
	ds_read_b128 v[56:59], v135 offset:6144
	ds_read_b128 v[60:63], v135 offset:7168
	s_nop 0
	global_load_lds_dwordx4 v133, s[70:71]
	s_mov_b32 m0, s11
	s_nop 0
	global_load_lds_dwordx4 v131, s[70:71]
	s_waitcnt vmcnt(8)
	s_waitcnt lgkmcnt(0)
	s_setprio 1
	s_barrier
	v_mfma_f32_16x16x32_bf16 v[64:67], v[0:3], v[32:35], 0
	v_mfma_f32_16x16x32_bf16 v[68:71], v[8:11], v[32:35], 0
	v_mfma_f32_16x16x32_bf16 v[72:75], v[0:3], v[40:43], 0
	v_mfma_f32_16x16x32_bf16 v[76:79], v[8:11], v[40:43], 0
	v_mfma_f32_16x16x32_bf16 v[80:83], v[0:3], v[48:51], 0
	v_mfma_f32_16x16x32_bf16 v[84:87], v[8:11], v[48:51], 0
	v_mfma_f32_16x16x32_bf16 v[88:91], v[0:3], v[56:59], 0
	v_mfma_f32_16x16x32_bf16 v[92:95], v[8:11], v[56:59], 0
	v_mfma_f32_16x16x32_bf16 v[64:67], v[4:7], v[36:39], v[64:67]
	v_mfma_f32_16x16x32_bf16 v[68:71], v[12:15], v[36:39], v[68:71]
	v_mfma_f32_16x16x32_bf16 v[72:75], v[4:7], v[44:47], v[72:75]
	v_mfma_f32_16x16x32_bf16 v[76:79], v[12:15], v[44:47], v[76:79]
	v_mfma_f32_16x16x32_bf16 v[80:83], v[4:7], v[52:55], v[80:83]
	v_mfma_f32_16x16x32_bf16 v[84:87], v[12:15], v[52:55], v[84:87]
	v_mfma_f32_16x16x32_bf16 v[88:91], v[4:7], v[60:63], v[88:91]
	v_mfma_f32_16x16x32_bf16 v[92:95], v[12:15], v[60:63], v[92:95]
	v_mfma_f32_16x16x32_bf16 v[96:99], v[16:19], v[32:35], 0
	v_mfma_f32_16x16x32_bf16 v[32:35], v[24:27], v[32:35], 0
	v_mfma_f32_16x16x32_bf16 v[96:99], v[20:23], v[36:39], v[96:99]
	v_mfma_f32_16x16x32_bf16 v[32:35], v[28:31], v[36:39], v[32:35]
	v_mfma_f32_16x16x32_bf16 v[36:39], v[16:19], v[40:43], 0
	v_mfma_f32_16x16x32_bf16 v[40:43], v[24:27], v[40:43], 0
	v_mfma_f32_16x16x32_bf16 v[36:39], v[20:23], v[44:47], v[36:39]
	v_mfma_f32_16x16x32_bf16 v[40:43], v[28:31], v[44:47], v[40:43]
	v_mfma_f32_16x16x32_bf16 v[44:47], v[16:19], v[48:51], 0
	v_mfma_f32_16x16x32_bf16 v[48:51], v[24:27], v[48:51], 0
	v_mfma_f32_16x16x32_bf16 v[44:47], v[20:23], v[52:55], v[44:47]
	v_mfma_f32_16x16x32_bf16 v[48:51], v[28:31], v[52:55], v[48:51]
	v_mfma_f32_16x16x32_bf16 v[52:55], v[16:19], v[56:59], 0
	v_mfma_f32_16x16x32_bf16 v[56:59], v[24:27], v[56:59], 0
	v_mfma_f32_16x16x32_bf16 v[52:55], v[20:23], v[60:63], v[52:55]
	v_mfma_f32_16x16x32_bf16 v[56:59], v[28:31], v[60:63], v[56:59]
	s_setprio 0
	s_barrier
	s_add_i32 s70, s4, s97
	s_add_i32 s4, s70, 0x2000
	s_mov_b32 m0, s70
	s_add_u32 s74, s36, 0x80100
	ds_read_b128 v[60:63], v135 offset:16384
	ds_read_b128 v[100:103], v135 offset:17408
	ds_read_b128 v[104:107], v135 offset:18432
	ds_read_b128 v[108:111], v135 offset:19456
	ds_read_b128 v[112:115], v135 offset:20480
	ds_read_b128 v[116:119], v135 offset:21504
	ds_read_b128 v[120:123], v135 offset:22528
	ds_read_b128 v[124:127], v135 offset:23552
	s_addc_u32 s75, s37, 0
	global_load_lds_dwordx4 v132, s[82:83]
	s_mov_b32 m0, s4
	s_add_i32 s13, s13, s97
	s_add_i32 s15, s13, 0x2000
	global_load_lds_dwordx4 v130, s[82:83]
	s_mov_b32 m0, s13
	s_nop 0
	global_load_lds_dwordx4 v132, s[74:75]
	s_mov_b32 m0, s15
	s_nop 0
	global_load_lds_dwordx4 v130, s[74:75]
	s_mov_b32 m0, s25
	s_nop 0
	global_load_lds_dwordx4 v133, s[56:57]
	s_mov_b32 m0, s27
	s_nop 0
	global_load_lds_dwordx4 v131, s[56:57]
	s_waitcnt vmcnt(8)
	s_waitcnt lgkmcnt(0)
	s_setprio 1
	s_barrier
	v_mfma_f32_16x16x32_bf16 v[136:139], v[0:3], v[60:63], 0
	v_mfma_f32_16x16x32_bf16 v[144:147], v[0:3], v[104:107], 0
	v_mfma_f32_16x16x32_bf16 v[152:155], v[0:3], v[112:115], 0
	v_mfma_f32_16x16x32_bf16 v[0:3], v[0:3], v[120:123], 0
	v_mfma_f32_16x16x32_bf16 v[136:139], v[4:7], v[100:103], v[136:139]
	v_mfma_f32_16x16x32_bf16 v[144:147], v[4:7], v[108:111], v[144:147]
	v_mfma_f32_16x16x32_bf16 v[152:155], v[4:7], v[116:119], v[152:155]
	v_mfma_f32_16x16x32_bf16 v[0:3], v[4:7], v[124:127], v[0:3]
	v_mfma_f32_16x16x32_bf16 v[4:7], v[8:11], v[120:123], 0
	v_mfma_f32_16x16x32_bf16 v[140:143], v[8:11], v[60:63], 0
	v_mfma_f32_16x16x32_bf16 v[148:151], v[8:11], v[104:107], 0
	v_mfma_f32_16x16x32_bf16 v[156:159], v[8:11], v[112:115], 0
	v_mfma_f32_16x16x32_bf16 v[4:7], v[12:15], v[124:127], v[4:7]
	v_mfma_f32_16x16x32_bf16 v[140:143], v[12:15], v[100:103], v[140:143]
	v_mfma_f32_16x16x32_bf16 v[148:151], v[12:15], v[108:111], v[148:151]
	v_mfma_f32_16x16x32_bf16 v[156:159], v[12:15], v[116:119], v[156:159]
	v_mfma_f32_16x16x32_bf16 v[8:11], v[16:19], v[60:63], 0
	v_mfma_f32_16x16x32_bf16 v[12:15], v[24:27], v[60:63], 0
	v_mfma_f32_16x16x32_bf16 v[8:11], v[20:23], v[100:103], v[8:11]
	v_mfma_f32_16x16x32_bf16 v[12:15], v[28:31], v[100:103], v[12:15]
	v_mfma_f32_16x16x32_bf16 v[60:63], v[16:19], v[104:107], 0
	v_mfma_f32_16x16x32_bf16 v[100:103], v[24:27], v[104:107], 0
	v_mfma_f32_16x16x32_bf16 v[104:107], v[16:19], v[112:115], 0
	v_mfma_f32_16x16x32_bf16 v[16:19], v[16:19], v[120:123], 0
	v_mfma_f32_16x16x32_bf16 v[60:63], v[20:23], v[108:111], v[60:63]
	v_mfma_f32_16x16x32_bf16 v[100:103], v[28:31], v[108:111], v[100:103]
	v_mfma_f32_16x16x32_bf16 v[104:107], v[20:23], v[116:119], v[104:107]
	v_mfma_f32_16x16x32_bf16 v[108:111], v[24:27], v[112:115], 0
	v_mfma_f32_16x16x32_bf16 v[16:19], v[20:23], v[124:127], v[16:19]
	v_mfma_f32_16x16x32_bf16 v[20:23], v[24:27], v[120:123], 0
	v_mfma_f32_16x16x32_bf16 v[108:111], v[28:31], v[116:119], v[108:111]
	v_mfma_f32_16x16x32_bf16 v[20:23], v[28:31], v[124:127], v[20:23]
	s_setprio 0
	s_barrier
	s_add_i32 s71, 0, 0x18000
	s_add_i32 s69, 0, 0x1c000
	v_add_u32_e32 v196, s71, v134
	v_add_u32_e32 v198, s69, v134
	ds_read_b128 v[24:27], v196
	ds_read_b128 v[28:31], v196 offset:1024
	ds_read_b128 v[112:115], v196 offset:2048
	ds_read_b128 v[116:119], v196 offset:3072
	ds_read_b128 v[120:123], v198
	ds_read_b128 v[124:127], v198 offset:1024
	ds_read_b128 v[160:163], v198 offset:2048
	ds_read_b128 v[164:167], v198 offset:3072
	s_add_u32 s56, s30, 0x10100
	s_addc_u32 s57, s31, 0
	s_mov_b32 m0, s29
	ds_read_b128 v[168:171], v135 offset:32768
	ds_read_b128 v[172:175], v135 offset:33792
	ds_read_b128 v[176:179], v135 offset:34816
	ds_read_b128 v[180:183], v135 offset:35840
	ds_read_b128 v[184:187], v135 offset:36864
	ds_read_b128 v[188:191], v135 offset:37888
	ds_read_b128 v[192:195], v135 offset:38912
	ds_read_b128 v[200:203], v135 offset:39936
	s_nop 0
	global_load_lds_dwordx4 v133, s[56:57]
	s_mov_b32 m0, s47
	s_nop 0
	global_load_lds_dwordx4 v131, s[56:57]
	s_waitcnt vmcnt(8)
	s_waitcnt lgkmcnt(0)
	s_setprio 1
	s_barrier
	v_mfma_f32_16x16x32_bf16 v[64:67], v[24:27], v[168:171], v[64:67]
	v_mfma_f32_16x16x32_bf16 v[64:67], v[28:31], v[172:175], v[64:67]
	v_mfma_f32_16x16x32_bf16 v[68:71], v[112:115], v[168:171], v[68:71]
	v_mfma_f32_16x16x32_bf16 v[68:71], v[116:119], v[172:175], v[68:71]
	v_mfma_f32_16x16x32_bf16 v[72:75], v[24:27], v[176:179], v[72:75]
	v_mfma_f32_16x16x32_bf16 v[72:75], v[28:31], v[180:183], v[72:75]
	v_mfma_f32_16x16x32_bf16 v[76:79], v[112:115], v[176:179], v[76:79]
	v_mfma_f32_16x16x32_bf16 v[76:79], v[116:119], v[180:183], v[76:79]
	v_mfma_f32_16x16x32_bf16 v[80:83], v[24:27], v[184:187], v[80:83]
	v_mfma_f32_16x16x32_bf16 v[80:83], v[28:31], v[188:191], v[80:83]
	v_mfma_f32_16x16x32_bf16 v[84:87], v[112:115], v[184:187], v[84:87]
	v_mfma_f32_16x16x32_bf16 v[84:87], v[116:119], v[188:191], v[84:87]
	v_mfma_f32_16x16x32_bf16 v[88:91], v[24:27], v[192:195], v[88:91]
	v_mfma_f32_16x16x32_bf16 v[88:91], v[28:31], v[200:203], v[88:91]
	v_mfma_f32_16x16x32_bf16 v[92:95], v[112:115], v[192:195], v[92:95]
	v_mfma_f32_16x16x32_bf16 v[92:95], v[116:119], v[200:203], v[92:95]
	v_mfma_f32_16x16x32_bf16 v[96:99], v[120:123], v[168:171], v[96:99]
	v_mfma_f32_16x16x32_bf16 v[96:99], v[124:127], v[172:175], v[96:99]
	v_mfma_f32_16x16x32_bf16 v[32:35], v[160:163], v[168:171], v[32:35]
	v_mfma_f32_16x16x32_bf16 v[32:35], v[164:167], v[172:175], v[32:35]
	v_mfma_f32_16x16x32_bf16 v[36:39], v[120:123], v[176:179], v[36:39]
	v_mfma_f32_16x16x32_bf16 v[36:39], v[124:127], v[180:183], v[36:39]
	v_mfma_f32_16x16x32_bf16 v[40:43], v[160:163], v[176:179], v[40:43]
	v_mfma_f32_16x16x32_bf16 v[40:43], v[164:167], v[180:183], v[40:43]
	v_mfma_f32_16x16x32_bf16 v[44:47], v[120:123], v[184:187], v[44:47]
	v_mfma_f32_16x16x32_bf16 v[44:47], v[124:127], v[188:191], v[44:47]
	v_mfma_f32_16x16x32_bf16 v[48:51], v[160:163], v[184:187], v[48:51]
	v_mfma_f32_16x16x32_bf16 v[48:51], v[164:167], v[188:191], v[48:51]
	v_mfma_f32_16x16x32_bf16 v[52:55], v[120:123], v[192:195], v[52:55]
	v_mfma_f32_16x16x32_bf16 v[52:55], v[124:127], v[200:203], v[52:55]
	v_mfma_f32_16x16x32_bf16 v[56:59], v[160:163], v[192:195], v[56:59]
	v_mfma_f32_16x16x32_bf16 v[56:59], v[164:167], v[200:203], v[56:59]
	s_setprio 0
	s_barrier
	s_add_u32 s74, s36, 0x180
	s_addc_u32 s75, s37, 0
	s_add_i32 s71, s71, s97
	s_add_i32 s56, s71, 0x2000
	s_mov_b32 m0, s71
	s_add_u32 s36, s36, 0x80180
	ds_read_b128 v[168:171], v135 offset:49152
	ds_read_b128 v[172:175], v135 offset:50176
	ds_read_b128 v[176:179], v135 offset:51200
	ds_read_b128 v[180:183], v135 offset:52224
	ds_read_b128 v[184:187], v135 offset:53248
	ds_read_b128 v[188:191], v135 offset:54272
	ds_read_b128 v[192:195], v135 offset:55296
	ds_read_b128 v[200:203], v135 offset:56320
	s_addc_u32 s37, s37, 0
	global_load_lds_dwordx4 v132, s[74:75]
	s_mov_b32 m0, s56
	s_add_i32 s57, s69, s97
	s_add_i32 s69, s57, 0x2000
	global_load_lds_dwordx4 v130, s[74:75]
	s_mov_b32 m0, s57
	s_nop 0
	global_load_lds_dwordx4 v132, s[36:37]
	s_mov_b32 m0, s69
	s_nop 0
	global_load_lds_dwordx4 v130, s[36:37]
	s_mov_b32 m0, s48
	s_nop 0
	global_load_lds_dwordx4 v133, s[80:81]
	s_mov_b32 m0, s49
	s_nop 0
	global_load_lds_dwordx4 v131, s[80:81]
	s_waitcnt vmcnt(8)
	s_waitcnt lgkmcnt(0)
	s_setprio 1
	s_barrier
	v_mfma_f32_16x16x32_bf16 v[0:3], v[24:27], v[192:195], v[0:3]
	v_mfma_f32_16x16x32_bf16 v[0:3], v[28:31], v[200:203], v[0:3]
	v_mfma_f32_16x16x32_bf16 v[4:7], v[112:115], v[192:195], v[4:7]
	v_mfma_f32_16x16x32_bf16 v[4:7], v[116:119], v[200:203], v[4:7]
	v_mfma_f32_16x16x32_bf16 v[136:139], v[24:27], v[168:171], v[136:139]
	v_mfma_f32_16x16x32_bf16 v[136:139], v[28:31], v[172:175], v[136:139]
	v_mfma_f32_16x16x32_bf16 v[140:143], v[112:115], v[168:171], v[140:143]
	v_mfma_f32_16x16x32_bf16 v[140:143], v[116:119], v[172:175], v[140:143]
	v_mfma_f32_16x16x32_bf16 v[144:147], v[24:27], v[176:179], v[144:147]
	v_mfma_f32_16x16x32_bf16 v[144:147], v[28:31], v[180:183], v[144:147]
	v_mfma_f32_16x16x32_bf16 v[148:151], v[112:115], v[176:179], v[148:151]
	v_mfma_f32_16x16x32_bf16 v[148:151], v[116:119], v[180:183], v[148:151]
	v_mfma_f32_16x16x32_bf16 v[152:155], v[24:27], v[184:187], v[152:155]
	v_mfma_f32_16x16x32_bf16 v[152:155], v[28:31], v[188:191], v[152:155]
	v_mfma_f32_16x16x32_bf16 v[156:159], v[112:115], v[184:187], v[156:159]
	v_mfma_f32_16x16x32_bf16 v[156:159], v[116:119], v[188:191], v[156:159]
	v_mfma_f32_16x16x32_bf16 v[8:11], v[120:123], v[168:171], v[8:11]
	v_mfma_f32_16x16x32_bf16 v[12:15], v[160:163], v[168:171], v[12:15]
	v_mfma_f32_16x16x32_bf16 v[24:27], v[120:123], v[176:179], v[60:63]
	v_mfma_f32_16x16x32_bf16 v[28:31], v[160:163], v[176:179], v[100:103]
	v_mfma_f32_16x16x32_bf16 v[60:63], v[120:123], v[184:187], v[104:107]
	v_mfma_f32_16x16x32_bf16 v[100:103], v[160:163], v[184:187], v[108:111]
	v_mfma_f32_16x16x32_bf16 v[16:19], v[120:123], v[192:195], v[16:19]
	v_mfma_f32_16x16x32_bf16 v[20:23], v[160:163], v[192:195], v[20:23]
	v_mfma_f32_16x16x32_bf16 v[8:11], v[124:127], v[172:175], v[8:11]
	v_mfma_f32_16x16x32_bf16 v[12:15], v[164:167], v[172:175], v[12:15]
	v_mfma_f32_16x16x32_bf16 v[24:27], v[124:127], v[180:183], v[24:27]
	v_mfma_f32_16x16x32_bf16 v[28:31], v[164:167], v[180:183], v[28:31]
	v_mfma_f32_16x16x32_bf16 v[60:63], v[124:127], v[188:191], v[60:63]
	v_mfma_f32_16x16x32_bf16 v[100:103], v[164:167], v[188:191], v[100:103]
	v_mfma_f32_16x16x32_bf16 v[16:19], v[124:127], v[200:203], v[16:19]
	v_mfma_f32_16x16x32_bf16 v[20:23], v[164:167], v[200:203], v[20:23]
	s_setprio 0
	s_barrier
	ds_read_b128 v[104:107], v128
	ds_read_b128 v[108:111], v128 offset:1024
	ds_read_b128 v[112:115], v128 offset:2048
	ds_read_b128 v[116:119], v128 offset:3072
	ds_read_b128 v[120:123], v129
	ds_read_b128 v[124:127], v129 offset:1024
	ds_read_b128 v[160:163], v129 offset:2048
	ds_read_b128 v[164:167], v129 offset:3072
	s_add_u32 s36, s38, 0x80
	s_addc_u32 s37, s39, 0
	s_add_u32 s30, s30, 0x10180
	s_addc_u32 s31, s31, 0
	s_mov_b32 m0, s5
	ds_read_b128 v[168:171], v135
	ds_read_b128 v[172:175], v135 offset:1024
	ds_read_b128 v[176:179], v135 offset:2048
	ds_read_b128 v[180:183], v135 offset:3072
	ds_read_b128 v[184:187], v135 offset:4096
	ds_read_b128 v[188:191], v135 offset:5120
	ds_read_b128 v[192:195], v135 offset:6144
	ds_read_b128 v[200:203], v135 offset:7168
	s_nop 0
	global_load_lds_dwordx4 v133, s[30:31]
	s_mov_b32 m0, s11
	s_nop 0
	global_load_lds_dwordx4 v131, s[30:31]
	s_waitcnt vmcnt(8)
	s_waitcnt lgkmcnt(0)
	s_setprio 1
	s_barrier
	v_mfma_f32_16x16x32_bf16 v[64:67], v[104:107], v[168:171], v[64:67]
	v_mfma_f32_16x16x32_bf16 v[64:67], v[108:111], v[172:175], v[64:67]
	v_mfma_f32_16x16x32_bf16 v[68:71], v[112:115], v[168:171], v[68:71]
	v_mfma_f32_16x16x32_bf16 v[68:71], v[116:119], v[172:175], v[68:71]
	v_mfma_f32_16x16x32_bf16 v[72:75], v[104:107], v[176:179], v[72:75]
	v_mfma_f32_16x16x32_bf16 v[72:75], v[108:111], v[180:183], v[72:75]
	v_mfma_f32_16x16x32_bf16 v[76:79], v[112:115], v[176:179], v[76:79]
	v_mfma_f32_16x16x32_bf16 v[76:79], v[116:119], v[180:183], v[76:79]
	v_mfma_f32_16x16x32_bf16 v[80:83], v[104:107], v[184:187], v[80:83]
	v_mfma_f32_16x16x32_bf16 v[80:83], v[108:111], v[188:191], v[80:83]
	v_mfma_f32_16x16x32_bf16 v[84:87], v[112:115], v[184:187], v[84:87]
	v_mfma_f32_16x16x32_bf16 v[84:87], v[116:119], v[188:191], v[84:87]
	v_mfma_f32_16x16x32_bf16 v[88:91], v[104:107], v[192:195], v[88:91]
	v_mfma_f32_16x16x32_bf16 v[88:91], v[108:111], v[200:203], v[88:91]
	v_mfma_f32_16x16x32_bf16 v[92:95], v[112:115], v[192:195], v[92:95]
	v_mfma_f32_16x16x32_bf16 v[92:95], v[116:119], v[200:203], v[92:95]
	v_mfma_f32_16x16x32_bf16 v[32:35], v[160:163], v[168:171], v[32:35]
	v_mfma_f32_16x16x32_bf16 v[96:99], v[120:123], v[168:171], v[96:99]
	v_mfma_f32_16x16x32_bf16 v[168:171], v[164:167], v[172:175], v[32:35]
	v_mfma_f32_16x16x32_bf16 v[32:35], v[120:123], v[176:179], v[36:39]
	v_mfma_f32_16x16x32_bf16 v[36:39], v[124:127], v[180:183], v[32:35]
	v_mfma_f32_16x16x32_bf16 v[32:35], v[160:163], v[176:179], v[40:43]
	v_mfma_f32_16x16x32_bf16 v[204:207], v[124:127], v[172:175], v[96:99]
	v_mfma_f32_16x16x32_bf16 v[172:175], v[164:167], v[180:183], v[32:35]
	v_mfma_f32_16x16x32_bf16 v[32:35], v[120:123], v[184:187], v[44:47]
	v_mfma_f32_16x16x32_bf16 v[44:47], v[124:127], v[188:191], v[32:35]
	v_mfma_f32_16x16x32_bf16 v[32:35], v[160:163], v[184:187], v[48:51]
	v_mfma_f32_16x16x32_bf16 v[48:51], v[164:167], v[188:191], v[32:35]
	v_mfma_f32_16x16x32_bf16 v[32:35], v[120:123], v[192:195], v[52:55]
	v_mfma_f32_16x16x32_bf16 v[52:55], v[124:127], v[200:203], v[32:35]
	v_mfma_f32_16x16x32_bf16 v[32:35], v[160:163], v[192:195], v[56:59]
	v_mfma_f32_16x16x32_bf16 v[56:59], v[164:167], v[200:203], v[32:35]
	s_setprio 0
	s_barrier
	s_mov_b32 m0, s70
	s_mov_b64 s[30:31], s[34:35]
	s_nop 2
	ds_read_b128 v[32:35], v135 offset:16384
	ds_read_b128 v[40:43], v135 offset:17408
	ds_read_b128 v[96:99], v135 offset:18432
	ds_read_b128 v[176:179], v135 offset:19456
	ds_read_b128 v[180:183], v135 offset:20480
	ds_read_b128 v[184:187], v135 offset:21504
	ds_read_b128 v[188:191], v135 offset:22528
	ds_read_b128 v[192:195], v135 offset:23552
	s_nop 0
	global_load_lds_dwordx4 v132, s[30:31]
	s_mov_b32 m0, s4
	s_add_u32 s4, s34, 0x80000
	s_addc_u32 s5, s35, 0
	global_load_lds_dwordx4 v130, s[30:31]
	s_mov_b32 m0, s13
	s_nop 0
	global_load_lds_dwordx4 v132, s[4:5]
	s_mov_b32 m0, s15
	s_nop 0
	global_load_lds_dwordx4 v130, s[4:5]
	s_mov_b64 s[4:5], s[38:39]
	s_mov_b32 m0, s25
	s_nop 0
	global_load_lds_dwordx4 v133, s[4:5]
	s_mov_b32 m0, s27
	s_nop 0
	global_load_lds_dwordx4 v131, s[4:5]
	s_waitcnt vmcnt(8)
	s_waitcnt lgkmcnt(0)
	s_setprio 1
	s_barrier
	v_mfma_f32_16x16x32_bf16 v[0:3], v[104:107], v[188:191], v[0:3]
	v_mfma_f32_16x16x32_bf16 v[0:3], v[108:111], v[192:195], v[0:3]
	v_mfma_f32_16x16x32_bf16 v[4:7], v[112:115], v[188:191], v[4:7]
	v_mfma_f32_16x16x32_bf16 v[4:7], v[116:119], v[192:195], v[4:7]
	v_mfma_f32_16x16x32_bf16 v[136:139], v[104:107], v[32:35], v[136:139]
	v_mfma_f32_16x16x32_bf16 v[136:139], v[108:111], v[40:43], v[136:139]
	v_mfma_f32_16x16x32_bf16 v[140:143], v[112:115], v[32:35], v[140:143]
	v_mfma_f32_16x16x32_bf16 v[140:143], v[116:119], v[40:43], v[140:143]
	v_mfma_f32_16x16x32_bf16 v[144:147], v[104:107], v[96:99], v[144:147]
	v_mfma_f32_16x16x32_bf16 v[144:147], v[108:111], v[176:179], v[144:147]
	v_mfma_f32_16x16x32_bf16 v[148:151], v[112:115], v[96:99], v[148:151]
	v_mfma_f32_16x16x32_bf16 v[148:151], v[116:119], v[176:179], v[148:151]
	v_mfma_f32_16x16x32_bf16 v[152:155], v[104:107], v[180:183], v[152:155]
	v_mfma_f32_16x16x32_bf16 v[152:155], v[108:111], v[184:187], v[152:155]
	v_mfma_f32_16x16x32_bf16 v[156:159], v[112:115], v[180:183], v[156:159]
	v_mfma_f32_16x16x32_bf16 v[156:159], v[116:119], v[184:187], v[156:159]
	v_mfma_f32_16x16x32_bf16 v[12:15], v[160:163], v[32:35], v[12:15]
	v_mfma_f32_16x16x32_bf16 v[200:203], v[164:167], v[40:43], v[12:15]
	v_mfma_f32_16x16x32_bf16 v[12:15], v[120:123], v[96:99], v[24:27]
	v_mfma_f32_16x16x32_bf16 v[24:27], v[124:127], v[176:179], v[12:15]
	v_mfma_f32_16x16x32_bf16 v[12:15], v[160:163], v[96:99], v[28:31]
	v_mfma_f32_16x16x32_bf16 v[176:179], v[164:167], v[176:179], v[12:15]
	v_mfma_f32_16x16x32_bf16 v[12:15], v[120:123], v[180:183], v[60:63]
	v_mfma_f32_16x16x32_bf16 v[208:211], v[124:127], v[184:187], v[12:15]
	v_mfma_f32_16x16x32_bf16 v[12:15], v[160:163], v[180:183], v[100:103]
	v_mfma_f32_16x16x32_bf16 v[8:11], v[120:123], v[32:35], v[8:11]
	v_mfma_f32_16x16x32_bf16 v[180:183], v[164:167], v[184:187], v[12:15]
	v_mfma_f32_16x16x32_bf16 v[12:15], v[120:123], v[188:191], v[16:19]
	v_mfma_f32_16x16x32_bf16 v[8:11], v[124:127], v[40:43], v[8:11]
	v_mfma_f32_16x16x32_bf16 v[184:187], v[124:127], v[192:195], v[12:15]
	v_mfma_f32_16x16x32_bf16 v[12:15], v[160:163], v[188:191], v[20:23]
	v_mfma_f32_16x16x32_bf16 v[160:163], v[164:167], v[192:195], v[12:15]
	s_setprio 0
	s_barrier
	s_nop 4
	ds_read_b128 v[12:15], v196
	ds_read_b128 v[16:19], v196 offset:1024
	ds_read_b128 v[164:167], v196 offset:2048
	ds_read_b128 v[188:191], v196 offset:3072
	ds_read_b128 v[192:195], v198
	ds_read_b128 v[220:223], v198 offset:1024
	ds_read_b128 v[224:227], v198 offset:2048
	ds_read_b128 v[228:231], v198 offset:3072
	s_add_u32 s4, s38, 0x10000
	s_addc_u32 s5, s39, 0
	s_mov_b32 m0, s29
	ds_read_b128 v[20:23], v135 offset:32768
	ds_read_b128 v[28:31], v135 offset:33792
	ds_read_b128 v[60:63], v135 offset:34816
	ds_read_b128 v[100:103], v135 offset:35840
	ds_read_b128 v[232:235], v135 offset:36864
	ds_read_b128 v[236:239], v135 offset:37888
	ds_read_b128 v[240:243], v135 offset:38912
	ds_read_b128 v[244:247], v135 offset:39936
	s_nop 0
	global_load_lds_dwordx4 v133, s[4:5]
	s_mov_b32 m0, s47
	s_nop 0
	global_load_lds_dwordx4 v131, s[4:5]
	s_waitcnt vmcnt(8)
	s_waitcnt lgkmcnt(0)
	s_setprio 1
	s_barrier
	v_mfma_f32_16x16x32_bf16 v[32:35], v[12:15], v[20:23], v[64:67]
	v_mfma_f32_16x16x32_bf16 v[120:123], v[16:19], v[28:31], v[32:35]
	v_mfma_f32_16x16x32_bf16 v[32:35], v[164:167], v[20:23], v[68:71]
	v_mfma_f32_16x16x32_bf16 v[112:115], v[188:191], v[28:31], v[32:35]
	v_mfma_f32_16x16x32_bf16 v[32:35], v[12:15], v[60:63], v[72:75]
	v_mfma_f32_16x16x32_bf16 v[104:107], v[16:19], v[100:103], v[32:35]
	v_mfma_f32_16x16x32_bf16 v[32:35], v[164:167], v[60:63], v[76:79]
	v_mfma_f32_16x16x32_bf16 v[96:99], v[188:191], v[100:103], v[32:35]
	v_mfma_f32_16x16x32_bf16 v[32:35], v[12:15], v[232:235], v[80:83]
	v_mfma_f32_16x16x32_bf16 v[72:75], v[16:19], v[236:239], v[32:35]
	v_mfma_f32_16x16x32_bf16 v[32:35], v[164:167], v[232:235], v[84:87]
	v_mfma_f32_16x16x32_bf16 v[64:67], v[188:191], v[236:239], v[32:35]
	v_mfma_f32_16x16x32_bf16 v[32:35], v[12:15], v[240:243], v[88:91]
	v_mfma_f32_16x16x32_bf16 v[40:43], v[16:19], v[244:247], v[32:35]
	v_mfma_f32_16x16x32_bf16 v[32:35], v[164:167], v[240:243], v[92:95]
	v_mfma_f32_16x16x32_bf16 v[32:35], v[188:191], v[244:247], v[32:35]
	v_mfma_f32_16x16x32_bf16 v[68:71], v[192:195], v[20:23], v[204:207]
	v_mfma_f32_16x16x32_bf16 v[20:23], v[224:227], v[20:23], v[168:171]
	v_mfma_f32_16x16x32_bf16 v[116:119], v[228:231], v[28:31], v[20:23]
	v_mfma_f32_16x16x32_bf16 v[20:23], v[192:195], v[60:63], v[36:39]
	v_mfma_f32_16x16x32_bf16 v[108:111], v[220:223], v[100:103], v[20:23]
	v_mfma_f32_16x16x32_bf16 v[20:23], v[224:227], v[60:63], v[172:175]
	v_mfma_f32_16x16x32_bf16 v[100:103], v[228:231], v[100:103], v[20:23]
	v_mfma_f32_16x16x32_bf16 v[20:23], v[192:195], v[232:235], v[44:47]
	v_mfma_f32_16x16x32_bf16 v[76:79], v[220:223], v[236:239], v[20:23]
	v_mfma_f32_16x16x32_bf16 v[20:23], v[224:227], v[232:235], v[48:51]
	v_mfma_f32_16x16x32_bf16 v[124:127], v[220:223], v[28:31], v[68:71]
	v_mfma_f32_16x16x32_bf16 v[68:71], v[228:231], v[236:239], v[20:23]
	v_mfma_f32_16x16x32_bf16 v[20:23], v[192:195], v[240:243], v[52:55]
	v_mfma_f32_16x16x32_bf16 v[44:47], v[220:223], v[244:247], v[20:23]
	v_mfma_f32_16x16x32_bf16 v[20:23], v[224:227], v[240:243], v[56:59]
	v_mfma_f32_16x16x32_bf16 v[36:39], v[228:231], v[244:247], v[20:23]
	s_setprio 0
	s_barrier
	s_add_u32 s4, s34, 0x80
	s_mov_b32 m0, s71
	s_addc_u32 s5, s35, 0
	ds_read_b128 v[48:51], v135 offset:49152
	ds_read_b128 v[56:59], v135 offset:50176
	ds_read_b128 v[168:171], v135 offset:51200
	ds_read_b128 v[172:175], v135 offset:52224
	ds_read_b128 v[204:207], v135 offset:53248
	ds_read_b128 v[232:235], v135 offset:54272
	ds_read_b128 v[236:239], v135 offset:55296
	ds_read_b128 v[240:243], v135 offset:56320
	s_nop 0
	global_load_lds_dwordx4 v132, s[4:5]
	s_mov_b32 m0, s56
	s_nop 0
	global_load_lds_dwordx4 v130, s[4:5]
	s_add_u32 s4, s34, 0x80080
	s_addc_u32 s5, s35, 0
	s_mov_b32 m0, s57
	s_nop 0
	global_load_lds_dwordx4 v132, s[4:5]
	s_mov_b32 m0, s69
	s_nop 0
	global_load_lds_dwordx4 v130, s[4:5]
	s_mov_b32 m0, s48
	s_nop 0
	global_load_lds_dwordx4 v133, s[36:37]
	s_mov_b32 m0, s49
	s_nop 0
	global_load_lds_dwordx4 v131, s[36:37]
	s_waitcnt vmcnt(8)
	s_waitcnt lgkmcnt(0)
	s_setprio 1
	s_barrier
	v_mfma_f32_16x16x32_bf16 v[20:23], v[12:15], v[48:51], v[136:139]
	v_mfma_f32_16x16x32_bf16 v[92:95], v[16:19], v[56:59], v[20:23]
	v_mfma_f32_16x16x32_bf16 v[20:23], v[164:167], v[48:51], v[140:143]
	v_mfma_f32_16x16x32_bf16 v[84:87], v[188:191], v[56:59], v[20:23]
	v_mfma_f32_16x16x32_bf16 v[20:23], v[12:15], v[168:171], v[144:147]
	v_mfma_f32_16x16x32_bf16 v[60:63], v[16:19], v[172:175], v[20:23]
	v_mfma_f32_16x16x32_bf16 v[20:23], v[164:167], v[168:171], v[148:151]
	v_mfma_f32_16x16x32_bf16 v[52:55], v[188:191], v[172:175], v[20:23]
	v_mfma_f32_16x16x32_bf16 v[20:23], v[12:15], v[204:207], v[152:155]
	v_mfma_f32_16x16x32_bf16 v[0:3], v[12:15], v[236:239], v[0:3]
	v_mfma_f32_16x16x32_bf16 v[28:31], v[16:19], v[232:235], v[20:23]
	v_mfma_f32_16x16x32_bf16 v[20:23], v[164:167], v[204:207], v[156:159]
	v_mfma_f32_16x16x32_bf16 v[12:15], v[16:19], v[240:243], v[0:3]
	v_mfma_f32_16x16x32_bf16 v[0:3], v[164:167], v[236:239], v[4:7]
	v_mfma_f32_16x16x32_bf16 v[20:23], v[188:191], v[232:235], v[20:23]
	v_mfma_f32_16x16x32_bf16 v[4:7], v[188:191], v[240:243], v[0:3]
	v_mfma_f32_16x16x32_bf16 v[0:3], v[192:195], v[48:51], v[8:11]
	v_mfma_f32_16x16x32_bf16 v[88:91], v[220:223], v[56:59], v[0:3]
	v_mfma_f32_16x16x32_bf16 v[0:3], v[224:227], v[48:51], v[200:203]
	v_mfma_f32_16x16x32_bf16 v[80:83], v[228:231], v[56:59], v[0:3]
	v_mfma_f32_16x16x32_bf16 v[0:3], v[192:195], v[168:171], v[24:27]
	v_mfma_f32_16x16x32_bf16 v[56:59], v[220:223], v[172:175], v[0:3]
	v_mfma_f32_16x16x32_bf16 v[0:3], v[224:227], v[168:171], v[176:179]
	v_mfma_f32_16x16x32_bf16 v[48:51], v[228:231], v[172:175], v[0:3]
	v_mfma_f32_16x16x32_bf16 v[0:3], v[192:195], v[204:207], v[208:211]
	v_mfma_f32_16x16x32_bf16 v[24:27], v[220:223], v[232:235], v[0:3]
	v_mfma_f32_16x16x32_bf16 v[0:3], v[224:227], v[204:207], v[180:183]
	v_mfma_f32_16x16x32_bf16 v[16:19], v[228:231], v[232:235], v[0:3]
	v_mfma_f32_16x16x32_bf16 v[0:3], v[192:195], v[236:239], v[184:187]
	v_mfma_f32_16x16x32_bf16 v[8:11], v[220:223], v[240:243], v[0:3]
	v_mfma_f32_16x16x32_bf16 v[0:3], v[224:227], v[236:239], v[160:163]
	v_mfma_f32_16x16x32_bf16 v[0:3], v[228:231], v[240:243], v[0:3]
	s_setprio 0
	s_barrier
	s_andn2_b64 vcc, exec, s[60:61]
	s_cbranch_vccnz .LBB0_315
	s_barrier

.LBB0_380:
	s_cmp_eq_u32 s15, 28
	s_cselect_b32 s36, s20, s4
	s_cselect_b32 s37, s21, s5
	s_cselect_b32 s34, s26, s11
	s_cselect_b32 s35, s27, s13
	s_add_u32 s30, s36, 0x80
	s_addc_u32 s31, s37, 0
	s_add_i32 s17, 0, 0x10000
	v_add_u32_e32 v128, s17, v134
	s_add_i32 s69, 0, 0x14000
	ds_read_b128 v[136:139], v128
	ds_read_b128 v[140:143], v128 offset:1024
	ds_read_b128 v[144:147], v128 offset:2048
	ds_read_b128 v[148:151], v128 offset:3072
	v_add_u32_e32 v128, s69, v134
	ds_read_b128 v[152:155], v128
	ds_read_b128 v[156:159], v128 offset:1024
	ds_read_b128 v[160:163], v128 offset:2048
	ds_read_b128 v[164:167], v128 offset:3072
	s_mov_b64 s[70:71], s[28:29]
	s_add_i32 m0, s23, 0xc000
	ds_read_b128 v[168:171], v135
	ds_read_b128 v[172:175], v135 offset:1024
	ds_read_b128 v[176:179], v135 offset:2048
	ds_read_b128 v[180:183], v135 offset:3072
	ds_read_b128 v[184:187], v135 offset:4096
	ds_read_b128 v[188:191], v135 offset:5120
	ds_read_b128 v[192:195], v135 offset:6144
	ds_read_b128 v[200:203], v135 offset:7168
	s_nop 0
	global_load_lds_dwordx4 v133, s[70:71]
	s_add_i32 m0, s23, 0xe000
	s_nop 0
	global_load_lds_dwordx4 v131, s[70:71]
	s_waitcnt vmcnt(8)
	s_waitcnt lgkmcnt(0)
	s_setprio 1
	s_barrier
	v_mfma_f32_16x16x32_bf16 v[124:127], v[136:139], v[168:171], v[124:127]
	v_mfma_f32_16x16x32_bf16 v[124:127], v[140:143], v[172:175], v[124:127]
	v_mfma_f32_16x16x32_bf16 v[120:123], v[144:147], v[168:171], v[120:123]
	v_mfma_f32_16x16x32_bf16 v[120:123], v[148:151], v[172:175], v[120:123]
	v_mfma_f32_16x16x32_bf16 v[116:119], v[136:139], v[176:179], v[116:119]
	v_mfma_f32_16x16x32_bf16 v[116:119], v[140:143], v[180:183], v[116:119]
	v_mfma_f32_16x16x32_bf16 v[108:111], v[144:147], v[176:179], v[108:111]
	v_mfma_f32_16x16x32_bf16 v[108:111], v[148:151], v[180:183], v[108:111]
	v_mfma_f32_16x16x32_bf16 v[100:103], v[136:139], v[184:187], v[100:103]
	v_mfma_f32_16x16x32_bf16 v[100:103], v[140:143], v[188:191], v[100:103]
	v_mfma_f32_16x16x32_bf16 v[92:95], v[144:147], v[184:187], v[92:95]
	v_mfma_f32_16x16x32_bf16 v[92:95], v[148:151], v[188:191], v[92:95]
	v_mfma_f32_16x16x32_bf16 v[84:87], v[136:139], v[192:195], v[84:87]
	v_mfma_f32_16x16x32_bf16 v[84:87], v[140:143], v[200:203], v[84:87]
	v_mfma_f32_16x16x32_bf16 v[76:79], v[144:147], v[192:195], v[76:79]
	v_mfma_f32_16x16x32_bf16 v[76:79], v[148:151], v[200:203], v[76:79]
	v_mfma_f32_16x16x32_bf16 v[112:115], v[152:155], v[168:171], v[112:115]
	v_mfma_f32_16x16x32_bf16 v[112:115], v[156:159], v[172:175], v[112:115]
	v_mfma_f32_16x16x32_bf16 v[104:107], v[160:163], v[168:171], v[104:107]
	v_mfma_f32_16x16x32_bf16 v[104:107], v[164:167], v[172:175], v[104:107]
	v_mfma_f32_16x16x32_bf16 v[96:99], v[152:155], v[176:179], v[96:99]
	v_mfma_f32_16x16x32_bf16 v[96:99], v[156:159], v[180:183], v[96:99]
	v_mfma_f32_16x16x32_bf16 v[88:91], v[160:163], v[176:179], v[88:91]
	v_mfma_f32_16x16x32_bf16 v[88:91], v[164:167], v[180:183], v[88:91]
	v_mfma_f32_16x16x32_bf16 v[80:83], v[152:155], v[184:187], v[80:83]
	v_mfma_f32_16x16x32_bf16 v[80:83], v[156:159], v[188:191], v[80:83]
	v_mfma_f32_16x16x32_bf16 v[72:75], v[160:163], v[184:187], v[72:75]
	v_mfma_f32_16x16x32_bf16 v[72:75], v[164:167], v[188:191], v[72:75]
	v_mfma_f32_16x16x32_bf16 v[68:71], v[152:155], v[192:195], v[68:71]
	v_mfma_f32_16x16x32_bf16 v[68:71], v[156:159], v[200:203], v[68:71]
	v_mfma_f32_16x16x32_bf16 v[64:67], v[160:163], v[192:195], v[64:67]
	v_mfma_f32_16x16x32_bf16 v[64:67], v[164:167], v[200:203], v[64:67]
	s_setprio 0
	s_barrier
	s_add_i32 s17, s17, s97
	s_mov_b64 s[70:71], s[34:35]
	s_mov_b32 m0, s17
	ds_read_b128 v[168:171], v135 offset:16384
	ds_read_b128 v[172:175], v135 offset:17408
	ds_read_b128 v[176:179], v135 offset:18432
	ds_read_b128 v[180:183], v135 offset:19456
	ds_read_b128 v[184:187], v135 offset:20480
	ds_read_b128 v[188:191], v135 offset:21504
	ds_read_b128 v[192:195], v135 offset:22528
	ds_read_b128 v[200:203], v135 offset:23552
	s_nop 0
	global_load_lds_dwordx4 v132, s[70:71]
	s_add_i32 m0, s17, 0x2000
	s_nop 0
	global_load_lds_dwordx4 v130, s[70:71]
	s_add_u32 s70, s34, 0x200000
	s_addc_u32 s71, s35, 0
	s_add_i32 s17, s69, s97
	s_mov_b32 m0, s17
	s_nop 0
	global_load_lds_dwordx4 v132, s[70:71]
	s_add_i32 m0, s17, 0x2000
	s_nop 0
	global_load_lds_dwordx4 v130, s[70:71]
	s_mov_b64 s[70:71], s[36:37]
	s_mov_b32 m0, s23
	s_nop 0
	global_load_lds_dwordx4 v133, s[70:71]
	s_mov_b32 m0, s25
	s_nop 0
	global_load_lds_dwordx4 v131, s[70:71]
	s_waitcnt vmcnt(8)
	s_waitcnt lgkmcnt(0)
	s_setprio 1
	s_barrier
	v_mfma_f32_16x16x32_bf16 v[60:63], v[136:139], v[168:171], v[60:63]
	v_mfma_f32_16x16x32_bf16 v[60:63], v[140:143], v[172:175], v[60:63]
	v_mfma_f32_16x16x32_bf16 v[56:59], v[144:147], v[168:171], v[56:59]
	v_mfma_f32_16x16x32_bf16 v[56:59], v[148:151], v[172:175], v[56:59]
	v_mfma_f32_16x16x32_bf16 v[52:55], v[136:139], v[176:179], v[52:55]
	v_mfma_f32_16x16x32_bf16 v[52:55], v[140:143], v[180:183], v[52:55]
	v_mfma_f32_16x16x32_bf16 v[44:47], v[144:147], v[176:179], v[44:47]
	v_mfma_f32_16x16x32_bf16 v[44:47], v[148:151], v[180:183], v[44:47]
	v_mfma_f32_16x16x32_bf16 v[36:39], v[136:139], v[184:187], v[36:39]
	v_mfma_f32_16x16x32_bf16 v[36:39], v[140:143], v[188:191], v[36:39]
	v_mfma_f32_16x16x32_bf16 v[28:31], v[144:147], v[184:187], v[28:31]
	v_mfma_f32_16x16x32_bf16 v[28:31], v[148:151], v[188:191], v[28:31]
	v_mfma_f32_16x16x32_bf16 v[20:23], v[136:139], v[192:195], v[20:23]
	v_mfma_f32_16x16x32_bf16 v[20:23], v[140:143], v[200:203], v[20:23]
	v_mfma_f32_16x16x32_bf16 v[12:15], v[144:147], v[192:195], v[12:15]
	v_mfma_f32_16x16x32_bf16 v[12:15], v[148:151], v[200:203], v[12:15]
	v_mfma_f32_16x16x32_bf16 v[48:51], v[152:155], v[168:171], v[48:51]
	v_mfma_f32_16x16x32_bf16 v[48:51], v[156:159], v[172:175], v[48:51]
	v_mfma_f32_16x16x32_bf16 v[40:43], v[160:163], v[168:171], v[40:43]
	v_mfma_f32_16x16x32_bf16 v[40:43], v[164:167], v[172:175], v[40:43]
	v_mfma_f32_16x16x32_bf16 v[32:35], v[152:155], v[176:179], v[32:35]
	v_mfma_f32_16x16x32_bf16 v[32:35], v[156:159], v[180:183], v[32:35]
	v_mfma_f32_16x16x32_bf16 v[24:27], v[160:163], v[176:179], v[24:27]
	v_mfma_f32_16x16x32_bf16 v[24:27], v[164:167], v[180:183], v[24:27]
	v_mfma_f32_16x16x32_bf16 v[16:19], v[152:155], v[184:187], v[16:19]
	v_mfma_f32_16x16x32_bf16 v[16:19], v[156:159], v[188:191], v[16:19]
	v_mfma_f32_16x16x32_bf16 v[8:11], v[160:163], v[184:187], v[8:11]
	v_mfma_f32_16x16x32_bf16 v[8:11], v[164:167], v[188:191], v[8:11]
	v_mfma_f32_16x16x32_bf16 v[4:7], v[152:155], v[192:195], v[4:7]
	v_mfma_f32_16x16x32_bf16 v[4:7], v[156:159], v[200:203], v[4:7]
	v_mfma_f32_16x16x32_bf16 v[0:3], v[160:163], v[192:195], v[0:3]
	v_mfma_f32_16x16x32_bf16 v[0:3], v[164:167], v[200:203], v[0:3]
	s_setprio 0
	s_barrier
	s_add_i32 s17, 0, 0x18000
	v_add_u32_e32 v128, s17, v134
	s_add_i32 s69, 0, 0x1c000
	ds_read_b128 v[136:139], v128
	ds_read_b128 v[140:143], v128 offset:1024
	ds_read_b128 v[144:147], v128 offset:2048
	ds_read_b128 v[148:151], v128 offset:3072
	v_add_u32_e32 v128, s69, v134
	ds_read_b128 v[152:155], v128
	ds_read_b128 v[156:159], v128 offset:1024
	ds_read_b128 v[160:163], v128 offset:2048
	ds_read_b128 v[164:167], v128 offset:3072
	s_add_u32 s36, s36, 0x80000
	s_addc_u32 s37, s37, 0
	s_mov_b32 m0, s46
	ds_read_b128 v[168:171], v135 offset:32768
	ds_read_b128 v[172:175], v135 offset:33792
	ds_read_b128 v[176:179], v135 offset:34816
	ds_read_b128 v[180:183], v135 offset:35840
	ds_read_b128 v[184:187], v135 offset:36864
	ds_read_b128 v[188:191], v135 offset:37888
	ds_read_b128 v[192:195], v135 offset:38912
	ds_read_b128 v[200:203], v135 offset:39936
	s_nop 0
	global_load_lds_dwordx4 v133, s[36:37]
	s_mov_b32 m0, s47
	s_nop 0
	global_load_lds_dwordx4 v131, s[36:37]
	s_waitcnt vmcnt(8)
	s_waitcnt lgkmcnt(0)
	s_setprio 1
	s_barrier
	v_mfma_f32_16x16x32_bf16 v[124:127], v[136:139], v[168:171], v[124:127]
	v_mfma_f32_16x16x32_bf16 v[124:127], v[140:143], v[172:175], v[124:127]
	v_mfma_f32_16x16x32_bf16 v[120:123], v[144:147], v[168:171], v[120:123]
	v_mfma_f32_16x16x32_bf16 v[120:123], v[148:151], v[172:175], v[120:123]
	v_mfma_f32_16x16x32_bf16 v[116:119], v[136:139], v[176:179], v[116:119]
	v_mfma_f32_16x16x32_bf16 v[116:119], v[140:143], v[180:183], v[116:119]
	v_mfma_f32_16x16x32_bf16 v[108:111], v[144:147], v[176:179], v[108:111]
	v_mfma_f32_16x16x32_bf16 v[108:111], v[148:151], v[180:183], v[108:111]
	v_mfma_f32_16x16x32_bf16 v[100:103], v[136:139], v[184:187], v[100:103]
	v_mfma_f32_16x16x32_bf16 v[100:103], v[140:143], v[188:191], v[100:103]
	v_mfma_f32_16x16x32_bf16 v[92:95], v[144:147], v[184:187], v[92:95]
	v_mfma_f32_16x16x32_bf16 v[92:95], v[148:151], v[188:191], v[92:95]
	v_mfma_f32_16x16x32_bf16 v[84:87], v[136:139], v[192:195], v[84:87]
	v_mfma_f32_16x16x32_bf16 v[84:87], v[140:143], v[200:203], v[84:87]
	v_mfma_f32_16x16x32_bf16 v[76:79], v[144:147], v[192:195], v[76:79]
	v_mfma_f32_16x16x32_bf16 v[76:79], v[148:151], v[200:203], v[76:79]
	v_mfma_f32_16x16x32_bf16 v[112:115], v[152:155], v[168:171], v[112:115]
	v_mfma_f32_16x16x32_bf16 v[112:115], v[156:159], v[172:175], v[112:115]
	v_mfma_f32_16x16x32_bf16 v[104:107], v[160:163], v[168:171], v[104:107]
	v_mfma_f32_16x16x32_bf16 v[104:107], v[164:167], v[172:175], v[104:107]
	v_mfma_f32_16x16x32_bf16 v[96:99], v[152:155], v[176:179], v[96:99]
	v_mfma_f32_16x16x32_bf16 v[96:99], v[156:159], v[180:183], v[96:99]
	v_mfma_f32_16x16x32_bf16 v[88:91], v[160:163], v[176:179], v[88:91]
	v_mfma_f32_16x16x32_bf16 v[88:91], v[164:167], v[180:183], v[88:91]
	v_mfma_f32_16x16x32_bf16 v[80:83], v[152:155], v[184:187], v[80:83]
	v_mfma_f32_16x16x32_bf16 v[80:83], v[156:159], v[188:191], v[80:83]
	v_mfma_f32_16x16x32_bf16 v[72:75], v[160:163], v[184:187], v[72:75]
	v_mfma_f32_16x16x32_bf16 v[72:75], v[164:167], v[188:191], v[72:75]
	v_mfma_f32_16x16x32_bf16 v[68:71], v[152:155], v[192:195], v[68:71]
	v_mfma_f32_16x16x32_bf16 v[68:71], v[156:159], v[200:203], v[68:71]
	v_mfma_f32_16x16x32_bf16 v[64:67], v[160:163], v[192:195], v[64:67]
	v_mfma_f32_16x16x32_bf16 v[64:67], v[164:167], v[200:203], v[64:67]
	s_setprio 0
	s_barrier
	s_add_u32 s36, s34, 0x80
	s_addc_u32 s37, s35, 0
	s_add_i32 s17, s17, s97
	s_mov_b32 m0, s17
	ds_read_b128 v[168:171], v135 offset:49152
	ds_read_b128 v[172:175], v135 offset:50176
	ds_read_b128 v[176:179], v135 offset:51200
	ds_read_b128 v[180:183], v135 offset:52224
	ds_read_b128 v[184:187], v135 offset:53248
	ds_read_b128 v[188:191], v135 offset:54272
	ds_read_b128 v[192:195], v135 offset:55296
	ds_read_b128 v[200:203], v135 offset:56320
	s_nop 0
	global_load_lds_dwordx4 v132, s[36:37]
	s_add_i32 m0, s17, 0x2000
	s_add_u32 s34, s34, 0x200080
	s_addc_u32 s35, s35, 0
	s_add_i32 s17, s69, s97
	s_nop 0
	global_load_lds_dwordx4 v130, s[36:37]
	s_mov_b32 m0, s17
	s_nop 0
	global_load_lds_dwordx4 v132, s[34:35]
	s_add_i32 m0, s17, 0x2000
	s_nop 0
	global_load_lds_dwordx4 v130, s[34:35]
	s_mov_b32 m0, s56
	s_nop 0
	global_load_lds_dwordx4 v133, s[30:31]
	s_mov_b32 m0, s57
	s_nop 0
	global_load_lds_dwordx4 v131, s[30:31]
	s_waitcnt vmcnt(8)
	s_waitcnt lgkmcnt(0)
	s_setprio 1
	s_barrier
	v_mfma_f32_16x16x32_bf16 v[60:63], v[136:139], v[168:171], v[60:63]
	v_mfma_f32_16x16x32_bf16 v[60:63], v[140:143], v[172:175], v[60:63]
	v_mfma_f32_16x16x32_bf16 v[56:59], v[144:147], v[168:171], v[56:59]
	v_mfma_f32_16x16x32_bf16 v[56:59], v[148:151], v[172:175], v[56:59]
	v_mfma_f32_16x16x32_bf16 v[52:55], v[136:139], v[176:179], v[52:55]
	v_mfma_f32_16x16x32_bf16 v[52:55], v[140:143], v[180:183], v[52:55]
	v_mfma_f32_16x16x32_bf16 v[44:47], v[144:147], v[176:179], v[44:47]
	v_mfma_f32_16x16x32_bf16 v[44:47], v[148:151], v[180:183], v[44:47]
	v_mfma_f32_16x16x32_bf16 v[36:39], v[136:139], v[184:187], v[36:39]
	v_mfma_f32_16x16x32_bf16 v[36:39], v[140:143], v[188:191], v[36:39]
	v_mfma_f32_16x16x32_bf16 v[28:31], v[144:147], v[184:187], v[28:31]
	v_mfma_f32_16x16x32_bf16 v[28:31], v[148:151], v[188:191], v[28:31]
	v_mfma_f32_16x16x32_bf16 v[20:23], v[136:139], v[192:195], v[20:23]
	v_mfma_f32_16x16x32_bf16 v[20:23], v[140:143], v[200:203], v[20:23]
	v_mfma_f32_16x16x32_bf16 v[12:15], v[144:147], v[192:195], v[12:15]
	v_mfma_f32_16x16x32_bf16 v[12:15], v[148:151], v[200:203], v[12:15]
	v_mfma_f32_16x16x32_bf16 v[48:51], v[152:155], v[168:171], v[48:51]
	v_mfma_f32_16x16x32_bf16 v[48:51], v[156:159], v[172:175], v[48:51]
	v_mfma_f32_16x16x32_bf16 v[40:43], v[160:163], v[168:171], v[40:43]
	v_mfma_f32_16x16x32_bf16 v[40:43], v[164:167], v[172:175], v[40:43]
	v_mfma_f32_16x16x32_bf16 v[32:35], v[152:155], v[176:179], v[32:35]
	v_mfma_f32_16x16x32_bf16 v[32:35], v[156:159], v[180:183], v[32:35]
	v_mfma_f32_16x16x32_bf16 v[24:27], v[160:163], v[176:179], v[24:27]
	v_mfma_f32_16x16x32_bf16 v[24:27], v[164:167], v[180:183], v[24:27]
	v_mfma_f32_16x16x32_bf16 v[16:19], v[152:155], v[184:187], v[16:19]
	v_mfma_f32_16x16x32_bf16 v[16:19], v[156:159], v[188:191], v[16:19]
	v_mfma_f32_16x16x32_bf16 v[8:11], v[160:163], v[184:187], v[8:11]
	v_mfma_f32_16x16x32_bf16 v[8:11], v[164:167], v[188:191], v[8:11]
	v_mfma_f32_16x16x32_bf16 v[4:7], v[152:155], v[192:195], v[4:7]
	v_mfma_f32_16x16x32_bf16 v[4:7], v[156:159], v[200:203], v[4:7]
	v_mfma_f32_16x16x32_bf16 v[0:3], v[160:163], v[192:195], v[0:3]
	v_mfma_f32_16x16x32_bf16 v[0:3], v[164:167], v[200:203], v[0:3]
	s_setprio 0
	s_barrier
	s_add_i32 s15, s15, 2
	s_add_u32 s4, s4, 0x100
	s_addc_u32 s5, s5, 0
	s_add_u32 s11, s11, 0x100
	s_addc_u32 s13, s13, 0
	s_add_u32 s28, s28, 0x100
	s_addc_u32 s29, s29, 0
	s_cmp_gt_u32 s15, 29
	s_cbranch_scc0 .LBB0_380
	s_and_b64 vcc, exec, s[60:61]
	s_cbranch_vccz .LBB0_383
	s_barrier

.LBB0_397:
	s_cmp_eq_u32 s69, 4
	s_cselect_b32 s34, s15, s49
	s_cselect_b32 s35, s5, s56
	s_cselect_b32 s30, s48, s57
	s_cselect_b32 s31, s13, s65
	s_add_u32 s28, s34, 0x80
	s_addc_u32 s29, s35, 0
	s_add_i32 s72, 0, 0x10000
	v_add_u32_e32 v128, s72, v134
	s_add_i32 s74, 0, 0x14000
	ds_read_b128 v[136:139], v128
	ds_read_b128 v[140:143], v128 offset:1024
	ds_read_b128 v[144:147], v128 offset:2048
	ds_read_b128 v[148:151], v128 offset:3072
	v_add_u32_e32 v128, s74, v134
	ds_read_b128 v[152:155], v128
	ds_read_b128 v[156:159], v128 offset:1024
	ds_read_b128 v[160:163], v128 offset:2048
	ds_read_b128 v[164:167], v128 offset:3072
	s_mov_b64 s[70:71], s[26:27]
	s_add_i32 m0, s25, 0xc000
	ds_read_b128 v[168:171], v135
	ds_read_b128 v[172:175], v135 offset:1024
	ds_read_b128 v[176:179], v135 offset:2048
	ds_read_b128 v[180:183], v135 offset:3072
	ds_read_b128 v[184:187], v135 offset:4096
	ds_read_b128 v[188:191], v135 offset:5120
	ds_read_b128 v[192:195], v135 offset:6144
	ds_read_b128 v[200:203], v135 offset:7168
	s_nop 0
	global_load_lds_dwordx4 v133, s[70:71]
	s_add_i32 m0, s25, 0xe000
	s_nop 0
	global_load_lds_dwordx4 v131, s[70:71]
	s_waitcnt vmcnt(8)
	s_waitcnt lgkmcnt(0)
	s_setprio 1
	s_barrier
	v_mfma_f32_16x16x32_bf16 v[124:127], v[136:139], v[168:171], v[124:127]
	v_mfma_f32_16x16x32_bf16 v[124:127], v[140:143], v[172:175], v[124:127]
	v_mfma_f32_16x16x32_bf16 v[120:123], v[144:147], v[168:171], v[120:123]
	v_mfma_f32_16x16x32_bf16 v[120:123], v[148:151], v[172:175], v[120:123]
	v_mfma_f32_16x16x32_bf16 v[116:119], v[136:139], v[176:179], v[116:119]
	v_mfma_f32_16x16x32_bf16 v[116:119], v[140:143], v[180:183], v[116:119]
	v_mfma_f32_16x16x32_bf16 v[108:111], v[144:147], v[176:179], v[108:111]
	v_mfma_f32_16x16x32_bf16 v[108:111], v[148:151], v[180:183], v[108:111]
	v_mfma_f32_16x16x32_bf16 v[100:103], v[136:139], v[184:187], v[100:103]
	v_mfma_f32_16x16x32_bf16 v[100:103], v[140:143], v[188:191], v[100:103]
	v_mfma_f32_16x16x32_bf16 v[92:95], v[144:147], v[184:187], v[92:95]
	v_mfma_f32_16x16x32_bf16 v[92:95], v[148:151], v[188:191], v[92:95]
	v_mfma_f32_16x16x32_bf16 v[84:87], v[136:139], v[192:195], v[84:87]
	v_mfma_f32_16x16x32_bf16 v[84:87], v[140:143], v[200:203], v[84:87]
	v_mfma_f32_16x16x32_bf16 v[76:79], v[144:147], v[192:195], v[76:79]
	v_mfma_f32_16x16x32_bf16 v[76:79], v[148:151], v[200:203], v[76:79]
	v_mfma_f32_16x16x32_bf16 v[112:115], v[152:155], v[168:171], v[112:115]
	v_mfma_f32_16x16x32_bf16 v[112:115], v[156:159], v[172:175], v[112:115]
	v_mfma_f32_16x16x32_bf16 v[104:107], v[160:163], v[168:171], v[104:107]
	v_mfma_f32_16x16x32_bf16 v[104:107], v[164:167], v[172:175], v[104:107]
	v_mfma_f32_16x16x32_bf16 v[96:99], v[152:155], v[176:179], v[96:99]
	v_mfma_f32_16x16x32_bf16 v[96:99], v[156:159], v[180:183], v[96:99]
	v_mfma_f32_16x16x32_bf16 v[88:91], v[160:163], v[176:179], v[88:91]
	v_mfma_f32_16x16x32_bf16 v[88:91], v[164:167], v[180:183], v[88:91]
	v_mfma_f32_16x16x32_bf16 v[80:83], v[152:155], v[184:187], v[80:83]
	v_mfma_f32_16x16x32_bf16 v[80:83], v[156:159], v[188:191], v[80:83]
	v_mfma_f32_16x16x32_bf16 v[72:75], v[160:163], v[184:187], v[72:75]
	v_mfma_f32_16x16x32_bf16 v[72:75], v[164:167], v[188:191], v[72:75]
	v_mfma_f32_16x16x32_bf16 v[68:71], v[152:155], v[192:195], v[68:71]
	v_mfma_f32_16x16x32_bf16 v[68:71], v[156:159], v[200:203], v[68:71]
	v_mfma_f32_16x16x32_bf16 v[64:67], v[160:163], v[192:195], v[64:67]
	v_mfma_f32_16x16x32_bf16 v[64:67], v[164:167], v[200:203], v[64:67]
	s_setprio 0
	s_barrier
	s_add_i32 s72, s72, s97
	s_mov_b64 s[70:71], s[30:31]
	s_mov_b32 m0, s72
	ds_read_b128 v[168:171], v135 offset:16384
	ds_read_b128 v[172:175], v135 offset:17408
	ds_read_b128 v[176:179], v135 offset:18432
	ds_read_b128 v[180:183], v135 offset:19456
	ds_read_b128 v[184:187], v135 offset:20480
	ds_read_b128 v[188:191], v135 offset:21504
	ds_read_b128 v[192:195], v135 offset:22528
	ds_read_b128 v[200:203], v135 offset:23552
	s_nop 0
	global_load_lds_dwordx4 v132, s[70:71]
	s_add_i32 m0, s72, 0x2000
	s_nop 0
	global_load_lds_dwordx4 v130, s[70:71]
	s_add_u32 s70, s30, 0x20000
	s_addc_u32 s71, s31, 0
	s_add_i32 s72, s74, s97
	s_mov_b32 m0, s72
	s_nop 0
	global_load_lds_dwordx4 v132, s[70:71]
	s_add_i32 m0, s72, 0x2000
	s_nop 0
	global_load_lds_dwordx4 v130, s[70:71]
	s_mov_b64 s[70:71], s[34:35]
	s_mov_b32 m0, s25
	s_nop 0
	global_load_lds_dwordx4 v133, s[70:71]
	s_mov_b32 m0, s37
	s_nop 0
	global_load_lds_dwordx4 v131, s[70:71]
	s_waitcnt vmcnt(8)
	s_waitcnt lgkmcnt(0)
	s_setprio 1
	s_barrier
	v_mfma_f32_16x16x32_bf16 v[60:63], v[136:139], v[168:171], v[60:63]
	v_mfma_f32_16x16x32_bf16 v[60:63], v[140:143], v[172:175], v[60:63]
	v_mfma_f32_16x16x32_bf16 v[56:59], v[144:147], v[168:171], v[56:59]
	v_mfma_f32_16x16x32_bf16 v[56:59], v[148:151], v[172:175], v[56:59]
	v_mfma_f32_16x16x32_bf16 v[52:55], v[136:139], v[176:179], v[52:55]
	v_mfma_f32_16x16x32_bf16 v[52:55], v[140:143], v[180:183], v[52:55]
	v_mfma_f32_16x16x32_bf16 v[44:47], v[144:147], v[176:179], v[44:47]
	v_mfma_f32_16x16x32_bf16 v[44:47], v[148:151], v[180:183], v[44:47]
	v_mfma_f32_16x16x32_bf16 v[36:39], v[136:139], v[184:187], v[36:39]
	v_mfma_f32_16x16x32_bf16 v[36:39], v[140:143], v[188:191], v[36:39]
	v_mfma_f32_16x16x32_bf16 v[28:31], v[144:147], v[184:187], v[28:31]
	v_mfma_f32_16x16x32_bf16 v[28:31], v[148:151], v[188:191], v[28:31]
	v_mfma_f32_16x16x32_bf16 v[20:23], v[136:139], v[192:195], v[20:23]
	v_mfma_f32_16x16x32_bf16 v[20:23], v[140:143], v[200:203], v[20:23]
	v_mfma_f32_16x16x32_bf16 v[12:15], v[144:147], v[192:195], v[12:15]
	v_mfma_f32_16x16x32_bf16 v[12:15], v[148:151], v[200:203], v[12:15]
	v_mfma_f32_16x16x32_bf16 v[48:51], v[152:155], v[168:171], v[48:51]
	v_mfma_f32_16x16x32_bf16 v[48:51], v[156:159], v[172:175], v[48:51]
	v_mfma_f32_16x16x32_bf16 v[40:43], v[160:163], v[168:171], v[40:43]
	v_mfma_f32_16x16x32_bf16 v[40:43], v[164:167], v[172:175], v[40:43]
	v_mfma_f32_16x16x32_bf16 v[32:35], v[152:155], v[176:179], v[32:35]
	v_mfma_f32_16x16x32_bf16 v[32:35], v[156:159], v[180:183], v[32:35]
	v_mfma_f32_16x16x32_bf16 v[24:27], v[160:163], v[176:179], v[24:27]
	v_mfma_f32_16x16x32_bf16 v[24:27], v[164:167], v[180:183], v[24:27]
	v_mfma_f32_16x16x32_bf16 v[16:19], v[152:155], v[184:187], v[16:19]
	v_mfma_f32_16x16x32_bf16 v[16:19], v[156:159], v[188:191], v[16:19]
	v_mfma_f32_16x16x32_bf16 v[8:11], v[160:163], v[184:187], v[8:11]
	v_mfma_f32_16x16x32_bf16 v[8:11], v[164:167], v[188:191], v[8:11]
	v_mfma_f32_16x16x32_bf16 v[4:7], v[152:155], v[192:195], v[4:7]
	v_mfma_f32_16x16x32_bf16 v[4:7], v[156:159], v[200:203], v[4:7]
	v_mfma_f32_16x16x32_bf16 v[0:3], v[160:163], v[192:195], v[0:3]
	v_mfma_f32_16x16x32_bf16 v[0:3], v[164:167], v[200:203], v[0:3]
	s_setprio 0
	s_barrier
	s_add_i32 s70, 0, 0x18000
	v_add_u32_e32 v128, s70, v134
	s_add_i32 s71, 0, 0x1c000
	ds_read_b128 v[136:139], v128
	ds_read_b128 v[140:143], v128 offset:1024
	ds_read_b128 v[144:147], v128 offset:2048
	ds_read_b128 v[148:151], v128 offset:3072
	v_add_u32_e32 v128, s71, v134
	ds_read_b128 v[152:155], v128
	ds_read_b128 v[156:159], v128 offset:1024
	ds_read_b128 v[160:163], v128 offset:2048
	ds_read_b128 v[164:167], v128 offset:3072
	s_add_u32 s34, s34, 0x20000
	s_addc_u32 s35, s35, 0
	s_mov_b32 m0, s38
	ds_read_b128 v[168:171], v135 offset:32768
	ds_read_b128 v[172:175], v135 offset:33792
	ds_read_b128 v[176:179], v135 offset:34816
	ds_read_b128 v[180:183], v135 offset:35840
	ds_read_b128 v[184:187], v135 offset:36864
	ds_read_b128 v[188:191], v135 offset:37888
	ds_read_b128 v[192:195], v135 offset:38912
	ds_read_b128 v[200:203], v135 offset:39936
	s_nop 0
	global_load_lds_dwordx4 v133, s[34:35]
	s_mov_b32 m0, s39
	s_nop 0
	global_load_lds_dwordx4 v131, s[34:35]
	s_waitcnt vmcnt(8)
	s_waitcnt lgkmcnt(0)
	s_setprio 1
	s_barrier
	v_mfma_f32_16x16x32_bf16 v[124:127], v[136:139], v[168:171], v[124:127]
	v_mfma_f32_16x16x32_bf16 v[124:127], v[140:143], v[172:175], v[124:127]
	v_mfma_f32_16x16x32_bf16 v[120:123], v[144:147], v[168:171], v[120:123]
	v_mfma_f32_16x16x32_bf16 v[120:123], v[148:151], v[172:175], v[120:123]
	v_mfma_f32_16x16x32_bf16 v[116:119], v[136:139], v[176:179], v[116:119]
	v_mfma_f32_16x16x32_bf16 v[116:119], v[140:143], v[180:183], v[116:119]
	v_mfma_f32_16x16x32_bf16 v[108:111], v[144:147], v[176:179], v[108:111]
	v_mfma_f32_16x16x32_bf16 v[108:111], v[148:151], v[180:183], v[108:111]
	v_mfma_f32_16x16x32_bf16 v[100:103], v[136:139], v[184:187], v[100:103]
	v_mfma_f32_16x16x32_bf16 v[100:103], v[140:143], v[188:191], v[100:103]
	v_mfma_f32_16x16x32_bf16 v[92:95], v[144:147], v[184:187], v[92:95]
	v_mfma_f32_16x16x32_bf16 v[92:95], v[148:151], v[188:191], v[92:95]
	v_mfma_f32_16x16x32_bf16 v[84:87], v[136:139], v[192:195], v[84:87]
	v_mfma_f32_16x16x32_bf16 v[84:87], v[140:143], v[200:203], v[84:87]
	v_mfma_f32_16x16x32_bf16 v[76:79], v[144:147], v[192:195], v[76:79]
	v_mfma_f32_16x16x32_bf16 v[76:79], v[148:151], v[200:203], v[76:79]
	v_mfma_f32_16x16x32_bf16 v[112:115], v[152:155], v[168:171], v[112:115]
	v_mfma_f32_16x16x32_bf16 v[112:115], v[156:159], v[172:175], v[112:115]
	v_mfma_f32_16x16x32_bf16 v[104:107], v[160:163], v[168:171], v[104:107]
	v_mfma_f32_16x16x32_bf16 v[104:107], v[164:167], v[172:175], v[104:107]
	v_mfma_f32_16x16x32_bf16 v[96:99], v[152:155], v[176:179], v[96:99]
	v_mfma_f32_16x16x32_bf16 v[96:99], v[156:159], v[180:183], v[96:99]
	v_mfma_f32_16x16x32_bf16 v[88:91], v[160:163], v[176:179], v[88:91]
	v_mfma_f32_16x16x32_bf16 v[88:91], v[164:167], v[180:183], v[88:91]
	v_mfma_f32_16x16x32_bf16 v[80:83], v[152:155], v[184:187], v[80:83]
	v_mfma_f32_16x16x32_bf16 v[80:83], v[156:159], v[188:191], v[80:83]
	v_mfma_f32_16x16x32_bf16 v[72:75], v[160:163], v[184:187], v[72:75]
	v_mfma_f32_16x16x32_bf16 v[72:75], v[164:167], v[188:191], v[72:75]
	v_mfma_f32_16x16x32_bf16 v[68:71], v[152:155], v[192:195], v[68:71]
	v_mfma_f32_16x16x32_bf16 v[68:71], v[156:159], v[200:203], v[68:71]
	v_mfma_f32_16x16x32_bf16 v[64:67], v[160:163], v[192:195], v[64:67]
	v_mfma_f32_16x16x32_bf16 v[64:67], v[164:167], v[200:203], v[64:67]
	s_setprio 0
	s_barrier
	s_add_u32 s34, s30, 0x80
	s_addc_u32 s35, s31, 0
	s_add_i32 s70, s70, s97
	s_mov_b32 m0, s70
	ds_read_b128 v[168:171], v135 offset:49152
	ds_read_b128 v[172:175], v135 offset:50176
	ds_read_b128 v[176:179], v135 offset:51200
	ds_read_b128 v[180:183], v135 offset:52224
	ds_read_b128 v[184:187], v135 offset:53248
	ds_read_b128 v[188:191], v135 offset:54272
	ds_read_b128 v[192:195], v135 offset:55296
	ds_read_b128 v[200:203], v135 offset:56320
	s_nop 0
	global_load_lds_dwordx4 v132, s[34:35]
	s_add_i32 m0, s70, 0x2000
	s_add_u32 s30, s30, 0x20080
	s_addc_u32 s31, s31, 0
	global_load_lds_dwordx4 v130, s[34:35]
	s_add_i32 s34, s71, s97
	s_mov_b32 m0, s34
	s_nop 0
	global_load_lds_dwordx4 v132, s[30:31]
	s_add_i32 m0, s34, 0x2000
	s_nop 0
	global_load_lds_dwordx4 v130, s[30:31]
	s_mov_b32 m0, s44
	s_nop 0
	global_load_lds_dwordx4 v133, s[28:29]
	s_mov_b32 m0, s46
	s_nop 0
	global_load_lds_dwordx4 v131, s[28:29]
	s_waitcnt vmcnt(8)
	s_waitcnt lgkmcnt(0)
	s_setprio 1
	s_barrier
	v_mfma_f32_16x16x32_bf16 v[60:63], v[136:139], v[168:171], v[60:63]
	v_mfma_f32_16x16x32_bf16 v[60:63], v[140:143], v[172:175], v[60:63]
	v_mfma_f32_16x16x32_bf16 v[56:59], v[144:147], v[168:171], v[56:59]
	v_mfma_f32_16x16x32_bf16 v[56:59], v[148:151], v[172:175], v[56:59]
	v_mfma_f32_16x16x32_bf16 v[52:55], v[136:139], v[176:179], v[52:55]
	v_mfma_f32_16x16x32_bf16 v[52:55], v[140:143], v[180:183], v[52:55]
	v_mfma_f32_16x16x32_bf16 v[44:47], v[144:147], v[176:179], v[44:47]
	v_mfma_f32_16x16x32_bf16 v[44:47], v[148:151], v[180:183], v[44:47]
	v_mfma_f32_16x16x32_bf16 v[36:39], v[136:139], v[184:187], v[36:39]
	v_mfma_f32_16x16x32_bf16 v[36:39], v[140:143], v[188:191], v[36:39]
	v_mfma_f32_16x16x32_bf16 v[28:31], v[144:147], v[184:187], v[28:31]
	v_mfma_f32_16x16x32_bf16 v[28:31], v[148:151], v[188:191], v[28:31]
	v_mfma_f32_16x16x32_bf16 v[20:23], v[136:139], v[192:195], v[20:23]
	v_mfma_f32_16x16x32_bf16 v[20:23], v[140:143], v[200:203], v[20:23]
	v_mfma_f32_16x16x32_bf16 v[12:15], v[144:147], v[192:195], v[12:15]
	v_mfma_f32_16x16x32_bf16 v[12:15], v[148:151], v[200:203], v[12:15]
	v_mfma_f32_16x16x32_bf16 v[48:51], v[152:155], v[168:171], v[48:51]
	v_mfma_f32_16x16x32_bf16 v[48:51], v[156:159], v[172:175], v[48:51]
	v_mfma_f32_16x16x32_bf16 v[40:43], v[160:163], v[168:171], v[40:43]
	v_mfma_f32_16x16x32_bf16 v[40:43], v[164:167], v[172:175], v[40:43]
	v_mfma_f32_16x16x32_bf16 v[32:35], v[152:155], v[176:179], v[32:35]
	v_mfma_f32_16x16x32_bf16 v[32:35], v[156:159], v[180:183], v[32:35]
	v_mfma_f32_16x16x32_bf16 v[24:27], v[160:163], v[176:179], v[24:27]
	v_mfma_f32_16x16x32_bf16 v[24:27], v[164:167], v[180:183], v[24:27]
	v_mfma_f32_16x16x32_bf16 v[16:19], v[152:155], v[184:187], v[16:19]
	v_mfma_f32_16x16x32_bf16 v[16:19], v[156:159], v[188:191], v[16:19]
	v_mfma_f32_16x16x32_bf16 v[8:11], v[160:163], v[184:187], v[8:11]
	v_mfma_f32_16x16x32_bf16 v[8:11], v[164:167], v[188:191], v[8:11]
	v_mfma_f32_16x16x32_bf16 v[4:7], v[152:155], v[192:195], v[4:7]
	v_mfma_f32_16x16x32_bf16 v[4:7], v[156:159], v[200:203], v[4:7]
	v_mfma_f32_16x16x32_bf16 v[0:3], v[160:163], v[192:195], v[0:3]
	v_mfma_f32_16x16x32_bf16 v[0:3], v[164:167], v[200:203], v[0:3]
	s_setprio 0
	s_barrier
	s_add_i32 s69, s69, 2
	s_add_u32 s49, s49, 0x100
	s_addc_u32 s56, s56, 0
	s_add_u32 s57, s57, 0x100
	s_addc_u32 s65, s65, 0
	s_add_u32 s26, s26, 0x100
	s_addc_u32 s27, s27, 0
	s_cmp_gt_u32 s69, 5
	s_cbranch_scc0 .LBB0_397
	s_and_b64 vcc, exec, s[60:61]
	s_cbranch_vccz .LBB0_400
	s_barrier

.LBB0_527:
	s_cmp_eq_u32 s85, 28
	s_cselect_b32 s56, s5, s39
	s_cselect_b32 s57, s4, s69
	s_cselect_b32 s86, s37, s72
	s_cselect_b32 s87, s11, s74
	s_add_u32 s12, s56, 0x80
	s_addc_u32 s13, s57, 0
	s_add_i32 vcc_lo, 0, 0x10000
	s_add_i32 vcc_hi, 0, 0x14000
	v_add_u32_e32 v136, vcc_lo, v184
	v_add_u32_e32 v156, vcc_hi, v184
	ds_read_b128 v[104:107], v136
	ds_read_b128 v[108:111], v136 offset:1024
	ds_read_b128 v[132:135], v136 offset:2048
	ds_read_b128 v[136:139], v136 offset:3072
	ds_read_b128 v[144:147], v156
	ds_read_b128 v[148:151], v156 offset:1024
	ds_read_b128 v[152:155], v156 offset:2048
	ds_read_b128 v[156:159], v156 offset:3072
	s_mov_b64 s[8:9], s[16:17]
	s_add_i32 m0, s89, 0xc000
	ds_read_b128 v[160:163], v185
	ds_read_b128 v[164:167], v185 offset:1024
	ds_read_b128 v[168:171], v185 offset:2048
	ds_read_b128 v[172:175], v185 offset:3072
	ds_read_b128 v[186:189], v185 offset:4096
	ds_read_b128 v[190:193], v185 offset:5120
	ds_read_b128 v[200:203], v185 offset:6144
	ds_read_b128 v[204:207], v185 offset:7168
	s_nop 0
	global_load_lds_dwordx4 v179, s[8:9]
	s_add_i32 m0, s89, 0xe000
	s_nop 0
	global_load_lds_dwordx4 v182, s[8:9]
	s_waitcnt vmcnt(8)
	s_waitcnt lgkmcnt(0)
	s_setprio 1
	s_barrier
	v_mfma_f32_16x16x32_bf16 v[140:143], v[104:107], v[160:163], v[140:143]
	v_mfma_f32_16x16x32_bf16 v[140:143], v[108:111], v[164:167], v[140:143]
	v_mfma_f32_16x16x32_bf16 v[128:131], v[132:135], v[160:163], v[128:131]
	v_mfma_f32_16x16x32_bf16 v[128:131], v[136:139], v[164:167], v[128:131]
	v_mfma_f32_16x16x32_bf16 v[124:127], v[104:107], v[168:171], v[124:127]
	v_mfma_f32_16x16x32_bf16 v[124:127], v[108:111], v[172:175], v[124:127]
	v_mfma_f32_16x16x32_bf16 v[112:115], v[132:135], v[168:171], v[112:115]
	v_mfma_f32_16x16x32_bf16 v[112:115], v[136:139], v[172:175], v[112:115]
	v_mfma_f32_16x16x32_bf16 v[96:99], v[104:107], v[186:189], v[96:99]
	v_mfma_f32_16x16x32_bf16 v[96:99], v[108:111], v[190:193], v[96:99]
	v_mfma_f32_16x16x32_bf16 v[88:91], v[132:135], v[186:189], v[88:91]
	v_mfma_f32_16x16x32_bf16 v[88:91], v[136:139], v[190:193], v[88:91]
	v_mfma_f32_16x16x32_bf16 v[84:87], v[104:107], v[200:203], v[84:87]
	v_mfma_f32_16x16x32_bf16 v[84:87], v[108:111], v[204:207], v[84:87]
	v_mfma_f32_16x16x32_bf16 v[72:75], v[132:135], v[200:203], v[72:75]
	v_mfma_f32_16x16x32_bf16 v[72:75], v[136:139], v[204:207], v[72:75]
	v_mfma_f32_16x16x32_bf16 v[120:123], v[144:147], v[160:163], v[120:123]
	v_mfma_f32_16x16x32_bf16 v[120:123], v[148:151], v[164:167], v[120:123]
	v_mfma_f32_16x16x32_bf16 v[116:119], v[152:155], v[160:163], v[116:119]
	v_mfma_f32_16x16x32_bf16 v[116:119], v[156:159], v[164:167], v[116:119]
	v_mfma_f32_16x16x32_bf16 v[100:103], v[144:147], v[168:171], v[100:103]
	v_mfma_f32_16x16x32_bf16 v[100:103], v[148:151], v[172:175], v[100:103]
	v_mfma_f32_16x16x32_bf16 v[92:95], v[152:155], v[168:171], v[92:95]
	v_mfma_f32_16x16x32_bf16 v[92:95], v[156:159], v[172:175], v[92:95]
	v_mfma_f32_16x16x32_bf16 v[80:83], v[144:147], v[186:189], v[80:83]
	v_mfma_f32_16x16x32_bf16 v[80:83], v[148:151], v[190:193], v[80:83]
	v_mfma_f32_16x16x32_bf16 v[76:79], v[152:155], v[186:189], v[76:79]
	v_mfma_f32_16x16x32_bf16 v[76:79], v[156:159], v[190:193], v[76:79]
	v_mfma_f32_16x16x32_bf16 v[68:71], v[144:147], v[200:203], v[68:71]
	v_mfma_f32_16x16x32_bf16 v[68:71], v[148:151], v[204:207], v[68:71]
	v_mfma_f32_16x16x32_bf16 v[64:67], v[152:155], v[200:203], v[64:67]
	v_mfma_f32_16x16x32_bf16 v[64:67], v[156:159], v[204:207], v[64:67]
	s_setprio 0
	s_barrier
	s_add_i32 vcc_lo, vcc_lo, s97
	s_mov_b64 s[8:9], s[86:87]
	s_mov_b32 m0, vcc_lo
	ds_read_b128 v[160:163], v185 offset:16384
	ds_read_b128 v[164:167], v185 offset:17408
	ds_read_b128 v[168:171], v185 offset:18432
	ds_read_b128 v[172:175], v185 offset:19456
	ds_read_b128 v[186:189], v185 offset:20480
	ds_read_b128 v[190:193], v185 offset:21504
	ds_read_b128 v[200:203], v185 offset:22528
	ds_read_b128 v[204:207], v185 offset:23552
	s_nop 0
	global_load_lds_dwordx4 v181, s[8:9]
	s_add_i32 m0, vcc_lo, 0x2000
	s_nop 0
	global_load_lds_dwordx4 v183, s[8:9]
	s_add_u32 s8, s86, 0x80000
	s_addc_u32 s9, s87, 0
	s_add_i32 vcc_lo, vcc_hi, s97
	s_mov_b32 m0, vcc_lo
	s_nop 0
	global_load_lds_dwordx4 v181, s[8:9]
	s_add_i32 m0, vcc_lo, 0x2000
	s_nop 0
	global_load_lds_dwordx4 v183, s[8:9]
	s_mov_b64 s[8:9], s[56:57]
	s_mov_b32 m0, s89
	s_nop 0
	global_load_lds_dwordx4 v179, s[8:9]
	s_mov_b32 m0, s92
	s_nop 0
	global_load_lds_dwordx4 v182, s[8:9]
	s_waitcnt vmcnt(8)
	s_waitcnt lgkmcnt(0)
	s_setprio 1
	s_barrier
	v_mfma_f32_16x16x32_bf16 v[60:63], v[104:107], v[160:163], v[60:63]
	v_mfma_f32_16x16x32_bf16 v[60:63], v[108:111], v[164:167], v[60:63]
	v_mfma_f32_16x16x32_bf16 v[56:59], v[132:135], v[160:163], v[56:59]
	v_mfma_f32_16x16x32_bf16 v[56:59], v[136:139], v[164:167], v[56:59]
	v_mfma_f32_16x16x32_bf16 v[48:51], v[104:107], v[168:171], v[48:51]
	v_mfma_f32_16x16x32_bf16 v[48:51], v[108:111], v[172:175], v[48:51]
	v_mfma_f32_16x16x32_bf16 v[40:43], v[132:135], v[168:171], v[40:43]
	v_mfma_f32_16x16x32_bf16 v[40:43], v[136:139], v[172:175], v[40:43]
	v_mfma_f32_16x16x32_bf16 v[32:35], v[104:107], v[186:189], v[32:35]
	v_mfma_f32_16x16x32_bf16 v[32:35], v[108:111], v[190:193], v[32:35]
	v_mfma_f32_16x16x32_bf16 v[24:27], v[132:135], v[186:189], v[24:27]
	v_mfma_f32_16x16x32_bf16 v[24:27], v[136:139], v[190:193], v[24:27]
	v_mfma_f32_16x16x32_bf16 v[16:19], v[104:107], v[200:203], v[16:19]
	v_mfma_f32_16x16x32_bf16 v[16:19], v[108:111], v[204:207], v[16:19]
	v_mfma_f32_16x16x32_bf16 v[8:11], v[132:135], v[200:203], v[8:11]
	v_mfma_f32_16x16x32_bf16 v[8:11], v[136:139], v[204:207], v[8:11]
	v_mfma_f32_16x16x32_bf16 v[52:55], v[144:147], v[160:163], v[52:55]
	v_mfma_f32_16x16x32_bf16 v[52:55], v[148:151], v[164:167], v[52:55]
	v_mfma_f32_16x16x32_bf16 v[44:47], v[152:155], v[160:163], v[44:47]
	v_mfma_f32_16x16x32_bf16 v[44:47], v[156:159], v[164:167], v[44:47]
	v_mfma_f32_16x16x32_bf16 v[36:39], v[144:147], v[168:171], v[36:39]
	v_mfma_f32_16x16x32_bf16 v[36:39], v[148:151], v[172:175], v[36:39]
	v_mfma_f32_16x16x32_bf16 v[28:31], v[152:155], v[168:171], v[28:31]
	v_mfma_f32_16x16x32_bf16 v[28:31], v[156:159], v[172:175], v[28:31]
	v_mfma_f32_16x16x32_bf16 v[20:23], v[144:147], v[186:189], v[20:23]
	v_mfma_f32_16x16x32_bf16 v[20:23], v[148:151], v[190:193], v[20:23]
	v_mfma_f32_16x16x32_bf16 v[12:15], v[152:155], v[186:189], v[12:15]
	v_mfma_f32_16x16x32_bf16 v[12:15], v[156:159], v[190:193], v[12:15]
	v_mfma_f32_16x16x32_bf16 v[4:7], v[144:147], v[200:203], v[4:7]
	v_mfma_f32_16x16x32_bf16 v[4:7], v[148:151], v[204:207], v[4:7]
	v_mfma_f32_16x16x32_bf16 v[0:3], v[152:155], v[200:203], v[0:3]
	v_mfma_f32_16x16x32_bf16 v[0:3], v[156:159], v[204:207], v[0:3]
	s_setprio 0
	s_barrier
	s_add_i32 vcc_lo, 0, 0x18000
	s_add_i32 vcc_hi, 0, 0x1c000
	v_add_u32_e32 v136, vcc_lo, v184
	v_add_u32_e32 v156, vcc_hi, v184
	ds_read_b128 v[104:107], v136
	ds_read_b128 v[108:111], v136 offset:1024
	ds_read_b128 v[132:135], v136 offset:2048
	ds_read_b128 v[136:139], v136 offset:3072
	ds_read_b128 v[144:147], v156
	ds_read_b128 v[148:151], v156 offset:1024
	ds_read_b128 v[152:155], v156 offset:2048
	ds_read_b128 v[156:159], v156 offset:3072
	s_add_u32 s8, s56, 0x80000
	s_addc_u32 s9, s57, 0
	s_mov_b32 m0, s93
	ds_read_b128 v[160:163], v185 offset:32768
	ds_read_b128 v[164:167], v185 offset:33792
	ds_read_b128 v[168:171], v185 offset:34816
	ds_read_b128 v[172:175], v185 offset:35840
	ds_read_b128 v[186:189], v185 offset:36864
	ds_read_b128 v[190:193], v185 offset:37888
	ds_read_b128 v[200:203], v185 offset:38912
	ds_read_b128 v[204:207], v185 offset:39936
	s_nop 0
	global_load_lds_dwordx4 v179, s[8:9]
	s_mov_b32 m0, s48
	s_nop 0
	global_load_lds_dwordx4 v182, s[8:9]
	s_waitcnt vmcnt(8)
	s_waitcnt lgkmcnt(0)
	s_setprio 1
	s_barrier
	v_mfma_f32_16x16x32_bf16 v[140:143], v[104:107], v[160:163], v[140:143]
	v_mfma_f32_16x16x32_bf16 v[140:143], v[108:111], v[164:167], v[140:143]
	v_mfma_f32_16x16x32_bf16 v[128:131], v[132:135], v[160:163], v[128:131]
	v_mfma_f32_16x16x32_bf16 v[128:131], v[136:139], v[164:167], v[128:131]
	v_mfma_f32_16x16x32_bf16 v[124:127], v[104:107], v[168:171], v[124:127]
	v_mfma_f32_16x16x32_bf16 v[124:127], v[108:111], v[172:175], v[124:127]
	v_mfma_f32_16x16x32_bf16 v[112:115], v[132:135], v[168:171], v[112:115]
	v_mfma_f32_16x16x32_bf16 v[112:115], v[136:139], v[172:175], v[112:115]
	v_mfma_f32_16x16x32_bf16 v[96:99], v[104:107], v[186:189], v[96:99]
	v_mfma_f32_16x16x32_bf16 v[96:99], v[108:111], v[190:193], v[96:99]
	v_mfma_f32_16x16x32_bf16 v[88:91], v[132:135], v[186:189], v[88:91]
	v_mfma_f32_16x16x32_bf16 v[88:91], v[136:139], v[190:193], v[88:91]
	v_mfma_f32_16x16x32_bf16 v[84:87], v[104:107], v[200:203], v[84:87]
	v_mfma_f32_16x16x32_bf16 v[84:87], v[108:111], v[204:207], v[84:87]
	v_mfma_f32_16x16x32_bf16 v[72:75], v[132:135], v[200:203], v[72:75]
	v_mfma_f32_16x16x32_bf16 v[72:75], v[136:139], v[204:207], v[72:75]
	v_mfma_f32_16x16x32_bf16 v[120:123], v[144:147], v[160:163], v[120:123]
	v_mfma_f32_16x16x32_bf16 v[120:123], v[148:151], v[164:167], v[120:123]
	v_mfma_f32_16x16x32_bf16 v[116:119], v[152:155], v[160:163], v[116:119]
	v_mfma_f32_16x16x32_bf16 v[116:119], v[156:159], v[164:167], v[116:119]
	v_mfma_f32_16x16x32_bf16 v[100:103], v[144:147], v[168:171], v[100:103]
	v_mfma_f32_16x16x32_bf16 v[100:103], v[148:151], v[172:175], v[100:103]
	v_mfma_f32_16x16x32_bf16 v[92:95], v[152:155], v[168:171], v[92:95]
	v_mfma_f32_16x16x32_bf16 v[92:95], v[156:159], v[172:175], v[92:95]
	v_mfma_f32_16x16x32_bf16 v[80:83], v[144:147], v[186:189], v[80:83]
	v_mfma_f32_16x16x32_bf16 v[80:83], v[148:151], v[190:193], v[80:83]
	v_mfma_f32_16x16x32_bf16 v[76:79], v[152:155], v[186:189], v[76:79]
	v_mfma_f32_16x16x32_bf16 v[76:79], v[156:159], v[190:193], v[76:79]
	v_mfma_f32_16x16x32_bf16 v[68:71], v[144:147], v[200:203], v[68:71]
	v_mfma_f32_16x16x32_bf16 v[68:71], v[148:151], v[204:207], v[68:71]
	v_mfma_f32_16x16x32_bf16 v[64:67], v[152:155], v[200:203], v[64:67]
	v_mfma_f32_16x16x32_bf16 v[64:67], v[156:159], v[204:207], v[64:67]
	s_setprio 0
	s_barrier
	s_add_u32 s8, s86, 0x80
	s_addc_u32 s9, s87, 0
	s_add_i32 s56, vcc_lo, s97
	s_mov_b32 m0, s56
	ds_read_b128 v[160:163], v185 offset:49152
	ds_read_b128 v[164:167], v185 offset:50176
	ds_read_b128 v[168:171], v185 offset:51200
	ds_read_b128 v[172:175], v185 offset:52224
	ds_read_b128 v[186:189], v185 offset:53248
	ds_read_b128 v[190:193], v185 offset:54272
	ds_read_b128 v[200:203], v185 offset:55296
	ds_read_b128 v[204:207], v185 offset:56320
	s_nop 0
	global_load_lds_dwordx4 v181, s[8:9]
	s_add_i32 m0, s56, 0x2000
	s_nop 0
	global_load_lds_dwordx4 v183, s[8:9]
	s_add_u32 s8, s86, 0x80080
	s_addc_u32 s9, s87, 0
	s_add_i32 s56, vcc_hi, s97
	s_mov_b32 m0, s56
	s_nop 0
	global_load_lds_dwordx4 v181, s[8:9]
	s_add_i32 m0, s56, 0x2000
	s_nop 0
	global_load_lds_dwordx4 v183, s[8:9]
	s_mov_b32 m0, s46
	s_nop 0
	global_load_lds_dwordx4 v179, s[12:13]
	s_mov_b32 m0, s70
	s_nop 0
	global_load_lds_dwordx4 v182, s[12:13]
	s_waitcnt vmcnt(8)
	s_waitcnt lgkmcnt(0)
	s_setprio 1
	s_barrier
	v_mfma_f32_16x16x32_bf16 v[60:63], v[104:107], v[160:163], v[60:63]
	v_mfma_f32_16x16x32_bf16 v[60:63], v[108:111], v[164:167], v[60:63]
	v_mfma_f32_16x16x32_bf16 v[56:59], v[132:135], v[160:163], v[56:59]
	v_mfma_f32_16x16x32_bf16 v[56:59], v[136:139], v[164:167], v[56:59]
	v_mfma_f32_16x16x32_bf16 v[48:51], v[104:107], v[168:171], v[48:51]
	v_mfma_f32_16x16x32_bf16 v[48:51], v[108:111], v[172:175], v[48:51]
	v_mfma_f32_16x16x32_bf16 v[40:43], v[132:135], v[168:171], v[40:43]
	v_mfma_f32_16x16x32_bf16 v[40:43], v[136:139], v[172:175], v[40:43]
	v_mfma_f32_16x16x32_bf16 v[32:35], v[104:107], v[186:189], v[32:35]
	v_mfma_f32_16x16x32_bf16 v[32:35], v[108:111], v[190:193], v[32:35]
	v_mfma_f32_16x16x32_bf16 v[24:27], v[132:135], v[186:189], v[24:27]
	v_mfma_f32_16x16x32_bf16 v[24:27], v[136:139], v[190:193], v[24:27]
	v_mfma_f32_16x16x32_bf16 v[16:19], v[104:107], v[200:203], v[16:19]
	v_mfma_f32_16x16x32_bf16 v[16:19], v[108:111], v[204:207], v[16:19]
	v_mfma_f32_16x16x32_bf16 v[8:11], v[132:135], v[200:203], v[8:11]
	v_mfma_f32_16x16x32_bf16 v[8:11], v[136:139], v[204:207], v[8:11]
	v_mfma_f32_16x16x32_bf16 v[52:55], v[144:147], v[160:163], v[52:55]
	v_mfma_f32_16x16x32_bf16 v[52:55], v[148:151], v[164:167], v[52:55]
	v_mfma_f32_16x16x32_bf16 v[44:47], v[152:155], v[160:163], v[44:47]
	v_mfma_f32_16x16x32_bf16 v[44:47], v[156:159], v[164:167], v[44:47]
	v_mfma_f32_16x16x32_bf16 v[36:39], v[144:147], v[168:171], v[36:39]
	v_mfma_f32_16x16x32_bf16 v[36:39], v[148:151], v[172:175], v[36:39]
	v_mfma_f32_16x16x32_bf16 v[28:31], v[152:155], v[168:171], v[28:31]
	v_mfma_f32_16x16x32_bf16 v[28:31], v[156:159], v[172:175], v[28:31]
	v_mfma_f32_16x16x32_bf16 v[20:23], v[144:147], v[186:189], v[20:23]
	v_mfma_f32_16x16x32_bf16 v[20:23], v[148:151], v[190:193], v[20:23]
	v_mfma_f32_16x16x32_bf16 v[12:15], v[152:155], v[186:189], v[12:15]
	v_mfma_f32_16x16x32_bf16 v[12:15], v[156:159], v[190:193], v[12:15]
	v_mfma_f32_16x16x32_bf16 v[4:7], v[144:147], v[200:203], v[4:7]
	v_mfma_f32_16x16x32_bf16 v[4:7], v[148:151], v[204:207], v[4:7]
	v_mfma_f32_16x16x32_bf16 v[0:3], v[152:155], v[200:203], v[0:3]
	v_mfma_f32_16x16x32_bf16 v[0:3], v[156:159], v[204:207], v[0:3]
	s_setprio 0
	s_barrier
	s_add_i32 s85, s85, 2
	s_add_u32 s39, s39, 0x100
	s_addc_u32 s69, s69, 0
	s_add_u32 s72, s72, 0x100
	s_addc_u32 s74, s74, 0
	s_add_u32 s16, s16, 0x100
	s_addc_u32 s17, s17, 0
	s_cmp_gt_u32 s85, 29
	s_cbranch_scc0 .LBB0_527
	s_and_b64 vcc, exec, s[60:61]
	s_cbranch_vccz .LBB0_530
	s_barrier

.LBB0_604:
	s_cmp_eq_u32 s21, 4
	s_cselect_b32 s38, s22, s4
	s_cselect_b32 s39, s23, s5
	s_cselect_b32 s36, s24, s15
	s_cselect_b32 s37, s25, s17
	s_add_u32 s34, s38, 0x80
	s_addc_u32 s35, s39, 0
	s_add_i32 s65, 0, 0x10000
	s_add_i32 s69, 0, 0x14000
	v_add_u32_e32 v132, s65, v154
	v_add_u32_e32 v148, s69, v154
	ds_read_b128 v[112:115], v132
	ds_read_b128 v[120:123], v132 offset:1024
	ds_read_b128 v[128:131], v132 offset:2048
	ds_read_b128 v[132:135], v132 offset:3072
	ds_read_b128 v[144:147], v148
	ds_read_b128 v[156:159], v148 offset:1024
	ds_read_b128 v[160:163], v148 offset:2048
	ds_read_b128 v[164:167], v148 offset:3072
	s_add_u32 s70, s4, 0x7ff80
	s_addc_u32 s71, s5, 0
	s_add_i32 m0, s27, 0xc000
	ds_read_b128 v[168:171], v155
	ds_read_b128 v[172:175], v155 offset:1024
	ds_read_b128 v[176:179], v155 offset:2048
	ds_read_b128 v[180:183], v155 offset:3072
	ds_read_b128 v[184:187], v155 offset:4096
	ds_read_b128 v[188:191], v155 offset:5120
	ds_read_b128 v[192:195], v155 offset:6144
	ds_read_b128 v[200:203], v155 offset:7168
	s_nop 0
	global_load_lds_dwordx4 v151, s[70:71]
	s_add_i32 m0, s27, 0xe000
	s_nop 0
	global_load_lds_dwordx4 v150, s[70:71]
	s_waitcnt vmcnt(8)
	s_waitcnt lgkmcnt(0)
	s_setprio 1
	s_barrier
	v_mfma_f32_16x16x32_bf16 v[140:143], v[112:115], v[168:171], v[140:143]
	v_mfma_f32_16x16x32_bf16 v[140:143], v[120:123], v[172:175], v[140:143]
	v_mfma_f32_16x16x32_bf16 v[136:139], v[128:131], v[168:171], v[136:139]
	v_mfma_f32_16x16x32_bf16 v[136:139], v[132:135], v[172:175], v[136:139]
	v_mfma_f32_16x16x32_bf16 v[108:111], v[112:115], v[176:179], v[108:111]
	v_mfma_f32_16x16x32_bf16 v[108:111], v[120:123], v[180:183], v[108:111]
	v_mfma_f32_16x16x32_bf16 v[104:107], v[128:131], v[176:179], v[104:107]
	v_mfma_f32_16x16x32_bf16 v[104:107], v[132:135], v[180:183], v[104:107]
	v_mfma_f32_16x16x32_bf16 v[92:95], v[112:115], v[184:187], v[92:95]
	v_mfma_f32_16x16x32_bf16 v[92:95], v[120:123], v[188:191], v[92:95]
	v_mfma_f32_16x16x32_bf16 v[88:91], v[128:131], v[184:187], v[88:91]
	v_mfma_f32_16x16x32_bf16 v[88:91], v[132:135], v[188:191], v[88:91]
	v_mfma_f32_16x16x32_bf16 v[76:79], v[112:115], v[192:195], v[76:79]
	v_mfma_f32_16x16x32_bf16 v[76:79], v[120:123], v[200:203], v[76:79]
	v_mfma_f32_16x16x32_bf16 v[72:75], v[128:131], v[192:195], v[72:75]
	v_mfma_f32_16x16x32_bf16 v[72:75], v[132:135], v[200:203], v[72:75]
	v_mfma_f32_16x16x32_bf16 v[124:127], v[144:147], v[168:171], v[124:127]
	v_mfma_f32_16x16x32_bf16 v[124:127], v[156:159], v[172:175], v[124:127]
	v_mfma_f32_16x16x32_bf16 v[116:119], v[160:163], v[168:171], v[116:119]
	v_mfma_f32_16x16x32_bf16 v[116:119], v[164:167], v[172:175], v[116:119]
	v_mfma_f32_16x16x32_bf16 v[100:103], v[144:147], v[176:179], v[100:103]
	v_mfma_f32_16x16x32_bf16 v[100:103], v[156:159], v[180:183], v[100:103]
	v_mfma_f32_16x16x32_bf16 v[96:99], v[160:163], v[176:179], v[96:99]
	v_mfma_f32_16x16x32_bf16 v[96:99], v[164:167], v[180:183], v[96:99]
	v_mfma_f32_16x16x32_bf16 v[84:87], v[144:147], v[184:187], v[84:87]
	v_mfma_f32_16x16x32_bf16 v[84:87], v[156:159], v[188:191], v[84:87]
	v_mfma_f32_16x16x32_bf16 v[80:83], v[160:163], v[184:187], v[80:83]
	v_mfma_f32_16x16x32_bf16 v[80:83], v[164:167], v[188:191], v[80:83]
	v_mfma_f32_16x16x32_bf16 v[68:71], v[144:147], v[192:195], v[68:71]
	v_mfma_f32_16x16x32_bf16 v[68:71], v[156:159], v[200:203], v[68:71]
	v_mfma_f32_16x16x32_bf16 v[64:67], v[160:163], v[192:195], v[64:67]
	v_mfma_f32_16x16x32_bf16 v[64:67], v[164:167], v[200:203], v[64:67]
	s_setprio 0
	s_barrier
	s_add_i32 s65, s65, s97
	s_mov_b64 s[70:71], s[36:37]
	s_mov_b32 m0, s65
	ds_read_b128 v[168:171], v155 offset:16384
	ds_read_b128 v[172:175], v155 offset:17408
	ds_read_b128 v[176:179], v155 offset:18432
	ds_read_b128 v[180:183], v155 offset:19456
	ds_read_b128 v[184:187], v155 offset:20480
	ds_read_b128 v[188:191], v155 offset:21504
	ds_read_b128 v[192:195], v155 offset:22528
	ds_read_b128 v[200:203], v155 offset:23552
	s_nop 0
	global_load_lds_dwordx4 v152, s[70:71]
	s_add_i32 m0, s65, 0x2000
	s_nop 0
	global_load_lds_dwordx4 v153, s[70:71]
	s_add_u32 s70, s36, 0x80000
	s_addc_u32 s71, s37, 0
	s_add_i32 s65, s69, s97
	s_mov_b32 m0, s65
	s_nop 0
	global_load_lds_dwordx4 v152, s[70:71]
	s_add_i32 m0, s65, 0x2000
	s_nop 0
	global_load_lds_dwordx4 v153, s[70:71]
	s_mov_b64 s[70:71], s[38:39]
	s_mov_b32 m0, s27
	s_nop 0
	global_load_lds_dwordx4 v151, s[70:71]
	s_mov_b32 m0, s29
	s_nop 0
	global_load_lds_dwordx4 v150, s[70:71]
	s_waitcnt vmcnt(8)
	s_waitcnt lgkmcnt(0)
	s_setprio 1
	s_barrier
	v_mfma_f32_16x16x32_bf16 v[60:63], v[112:115], v[168:171], v[60:63]
	v_mfma_f32_16x16x32_bf16 v[60:63], v[120:123], v[172:175], v[60:63]
	v_mfma_f32_16x16x32_bf16 v[56:59], v[128:131], v[168:171], v[56:59]
	v_mfma_f32_16x16x32_bf16 v[56:59], v[132:135], v[172:175], v[56:59]
	v_mfma_f32_16x16x32_bf16 v[52:55], v[112:115], v[176:179], v[52:55]
	v_mfma_f32_16x16x32_bf16 v[52:55], v[120:123], v[180:183], v[52:55]
	v_mfma_f32_16x16x32_bf16 v[44:47], v[128:131], v[176:179], v[44:47]
	v_mfma_f32_16x16x32_bf16 v[44:47], v[132:135], v[180:183], v[44:47]
	v_mfma_f32_16x16x32_bf16 v[36:39], v[112:115], v[184:187], v[36:39]
	v_mfma_f32_16x16x32_bf16 v[36:39], v[120:123], v[188:191], v[36:39]
	v_mfma_f32_16x16x32_bf16 v[28:31], v[128:131], v[184:187], v[28:31]
	v_mfma_f32_16x16x32_bf16 v[28:31], v[132:135], v[188:191], v[28:31]
	v_mfma_f32_16x16x32_bf16 v[20:23], v[112:115], v[192:195], v[20:23]
	v_mfma_f32_16x16x32_bf16 v[20:23], v[120:123], v[200:203], v[20:23]
	v_mfma_f32_16x16x32_bf16 v[8:11], v[128:131], v[192:195], v[8:11]
	v_mfma_f32_16x16x32_bf16 v[8:11], v[132:135], v[200:203], v[8:11]
	v_mfma_f32_16x16x32_bf16 v[48:51], v[144:147], v[168:171], v[48:51]
	v_mfma_f32_16x16x32_bf16 v[48:51], v[156:159], v[172:175], v[48:51]
	v_mfma_f32_16x16x32_bf16 v[40:43], v[160:163], v[168:171], v[40:43]
	v_mfma_f32_16x16x32_bf16 v[40:43], v[164:167], v[172:175], v[40:43]
	v_mfma_f32_16x16x32_bf16 v[32:35], v[144:147], v[176:179], v[32:35]
	v_mfma_f32_16x16x32_bf16 v[32:35], v[156:159], v[180:183], v[32:35]
	v_mfma_f32_16x16x32_bf16 v[24:27], v[160:163], v[176:179], v[24:27]
	v_mfma_f32_16x16x32_bf16 v[24:27], v[164:167], v[180:183], v[24:27]
	v_mfma_f32_16x16x32_bf16 v[16:19], v[144:147], v[184:187], v[16:19]
	v_mfma_f32_16x16x32_bf16 v[16:19], v[156:159], v[188:191], v[16:19]
	v_mfma_f32_16x16x32_bf16 v[12:15], v[160:163], v[184:187], v[12:15]
	v_mfma_f32_16x16x32_bf16 v[12:15], v[164:167], v[188:191], v[12:15]
	v_mfma_f32_16x16x32_bf16 v[4:7], v[144:147], v[192:195], v[4:7]
	v_mfma_f32_16x16x32_bf16 v[4:7], v[156:159], v[200:203], v[4:7]
	v_mfma_f32_16x16x32_bf16 v[0:3], v[160:163], v[192:195], v[0:3]
	v_mfma_f32_16x16x32_bf16 v[0:3], v[164:167], v[200:203], v[0:3]
	s_setprio 0
	s_barrier
	s_add_i32 s65, 0, 0x18000
	s_add_i32 s69, 0, 0x1c000
	v_add_u32_e32 v132, s65, v154
	v_add_u32_e32 v148, s69, v154
	ds_read_b128 v[112:115], v132
	ds_read_b128 v[120:123], v132 offset:1024
	ds_read_b128 v[128:131], v132 offset:2048
	ds_read_b128 v[132:135], v132 offset:3072
	ds_read_b128 v[144:147], v148
	ds_read_b128 v[156:159], v148 offset:1024
	ds_read_b128 v[160:163], v148 offset:2048
	ds_read_b128 v[164:167], v148 offset:3072
	s_add_u32 s38, s38, 0x80000
	s_addc_u32 s39, s39, 0
	s_mov_b32 m0, s31
	ds_read_b128 v[168:171], v155 offset:32768
	ds_read_b128 v[172:175], v155 offset:33792
	ds_read_b128 v[176:179], v155 offset:34816
	ds_read_b128 v[180:183], v155 offset:35840
	ds_read_b128 v[184:187], v155 offset:36864
	ds_read_b128 v[188:191], v155 offset:37888
	ds_read_b128 v[192:195], v155 offset:38912
	ds_read_b128 v[200:203], v155 offset:39936
	s_nop 0
	global_load_lds_dwordx4 v151, s[38:39]
	s_mov_b32 m0, s48
	s_nop 0
	global_load_lds_dwordx4 v150, s[38:39]
	s_waitcnt vmcnt(8)
	s_waitcnt lgkmcnt(0)
	s_setprio 1
	s_barrier
	v_mfma_f32_16x16x32_bf16 v[140:143], v[112:115], v[168:171], v[140:143]
	v_mfma_f32_16x16x32_bf16 v[140:143], v[120:123], v[172:175], v[140:143]
	v_mfma_f32_16x16x32_bf16 v[136:139], v[128:131], v[168:171], v[136:139]
	v_mfma_f32_16x16x32_bf16 v[136:139], v[132:135], v[172:175], v[136:139]
	v_mfma_f32_16x16x32_bf16 v[108:111], v[112:115], v[176:179], v[108:111]
	v_mfma_f32_16x16x32_bf16 v[108:111], v[120:123], v[180:183], v[108:111]
	v_mfma_f32_16x16x32_bf16 v[104:107], v[128:131], v[176:179], v[104:107]
	v_mfma_f32_16x16x32_bf16 v[104:107], v[132:135], v[180:183], v[104:107]
	v_mfma_f32_16x16x32_bf16 v[92:95], v[112:115], v[184:187], v[92:95]
	v_mfma_f32_16x16x32_bf16 v[92:95], v[120:123], v[188:191], v[92:95]
	v_mfma_f32_16x16x32_bf16 v[88:91], v[128:131], v[184:187], v[88:91]
	v_mfma_f32_16x16x32_bf16 v[88:91], v[132:135], v[188:191], v[88:91]
	v_mfma_f32_16x16x32_bf16 v[76:79], v[112:115], v[192:195], v[76:79]
	v_mfma_f32_16x16x32_bf16 v[76:79], v[120:123], v[200:203], v[76:79]
	v_mfma_f32_16x16x32_bf16 v[72:75], v[128:131], v[192:195], v[72:75]
	v_mfma_f32_16x16x32_bf16 v[72:75], v[132:135], v[200:203], v[72:75]
	v_mfma_f32_16x16x32_bf16 v[124:127], v[144:147], v[168:171], v[124:127]
	v_mfma_f32_16x16x32_bf16 v[124:127], v[156:159], v[172:175], v[124:127]
	v_mfma_f32_16x16x32_bf16 v[116:119], v[160:163], v[168:171], v[116:119]
	v_mfma_f32_16x16x32_bf16 v[116:119], v[164:167], v[172:175], v[116:119]
	v_mfma_f32_16x16x32_bf16 v[100:103], v[144:147], v[176:179], v[100:103]
	v_mfma_f32_16x16x32_bf16 v[100:103], v[156:159], v[180:183], v[100:103]
	v_mfma_f32_16x16x32_bf16 v[96:99], v[160:163], v[176:179], v[96:99]
	v_mfma_f32_16x16x32_bf16 v[96:99], v[164:167], v[180:183], v[96:99]
	v_mfma_f32_16x16x32_bf16 v[84:87], v[144:147], v[184:187], v[84:87]
	v_mfma_f32_16x16x32_bf16 v[84:87], v[156:159], v[188:191], v[84:87]
	v_mfma_f32_16x16x32_bf16 v[80:83], v[160:163], v[184:187], v[80:83]
	v_mfma_f32_16x16x32_bf16 v[80:83], v[164:167], v[188:191], v[80:83]
	v_mfma_f32_16x16x32_bf16 v[68:71], v[144:147], v[192:195], v[68:71]
	v_mfma_f32_16x16x32_bf16 v[68:71], v[156:159], v[200:203], v[68:71]
	v_mfma_f32_16x16x32_bf16 v[64:67], v[160:163], v[192:195], v[64:67]
	v_mfma_f32_16x16x32_bf16 v[64:67], v[164:167], v[200:203], v[64:67]
	s_setprio 0
	s_barrier
	s_add_u32 s38, s36, 0x80
	s_addc_u32 s39, s37, 0
	s_add_i32 s65, s65, s97
	s_mov_b32 m0, s65
	ds_read_b128 v[168:171], v155 offset:49152
	ds_read_b128 v[172:175], v155 offset:50176
	ds_read_b128 v[176:179], v155 offset:51200
	ds_read_b128 v[180:183], v155 offset:52224
	ds_read_b128 v[184:187], v155 offset:53248
	ds_read_b128 v[188:191], v155 offset:54272
	ds_read_b128 v[192:195], v155 offset:55296
	ds_read_b128 v[200:203], v155 offset:56320
	s_nop 0
	global_load_lds_dwordx4 v152, s[38:39]
	s_add_i32 m0, s65, 0x2000
	s_add_u32 s36, s36, 0x80080
	s_addc_u32 s37, s37, 0
	global_load_lds_dwordx4 v153, s[38:39]
	s_add_i32 s38, s69, s97
	s_mov_b32 m0, s38
	s_nop 0
	global_load_lds_dwordx4 v152, s[36:37]
	s_add_i32 m0, s38, 0x2000
	s_nop 0
	global_load_lds_dwordx4 v153, s[36:37]
	s_mov_b32 m0, s49
	s_nop 0
	global_load_lds_dwordx4 v151, s[34:35]
	s_mov_b32 m0, s56
	s_nop 0
	global_load_lds_dwordx4 v150, s[34:35]
	s_waitcnt vmcnt(8)
	s_waitcnt lgkmcnt(0)
	s_setprio 1
	s_barrier
	v_mfma_f32_16x16x32_bf16 v[60:63], v[112:115], v[168:171], v[60:63]
	v_mfma_f32_16x16x32_bf16 v[60:63], v[120:123], v[172:175], v[60:63]
	v_mfma_f32_16x16x32_bf16 v[56:59], v[128:131], v[168:171], v[56:59]
	v_mfma_f32_16x16x32_bf16 v[56:59], v[132:135], v[172:175], v[56:59]
	v_mfma_f32_16x16x32_bf16 v[52:55], v[112:115], v[176:179], v[52:55]
	v_mfma_f32_16x16x32_bf16 v[52:55], v[120:123], v[180:183], v[52:55]
	v_mfma_f32_16x16x32_bf16 v[44:47], v[128:131], v[176:179], v[44:47]
	v_mfma_f32_16x16x32_bf16 v[44:47], v[132:135], v[180:183], v[44:47]
	v_mfma_f32_16x16x32_bf16 v[36:39], v[112:115], v[184:187], v[36:39]
	v_mfma_f32_16x16x32_bf16 v[36:39], v[120:123], v[188:191], v[36:39]
	v_mfma_f32_16x16x32_bf16 v[28:31], v[128:131], v[184:187], v[28:31]
	v_mfma_f32_16x16x32_bf16 v[28:31], v[132:135], v[188:191], v[28:31]
	v_mfma_f32_16x16x32_bf16 v[20:23], v[112:115], v[192:195], v[20:23]
	v_mfma_f32_16x16x32_bf16 v[20:23], v[120:123], v[200:203], v[20:23]
	v_mfma_f32_16x16x32_bf16 v[8:11], v[128:131], v[192:195], v[8:11]
	v_mfma_f32_16x16x32_bf16 v[8:11], v[132:135], v[200:203], v[8:11]
	v_mfma_f32_16x16x32_bf16 v[48:51], v[144:147], v[168:171], v[48:51]
	v_mfma_f32_16x16x32_bf16 v[48:51], v[156:159], v[172:175], v[48:51]
	v_mfma_f32_16x16x32_bf16 v[40:43], v[160:163], v[168:171], v[40:43]
	v_mfma_f32_16x16x32_bf16 v[40:43], v[164:167], v[172:175], v[40:43]
	v_mfma_f32_16x16x32_bf16 v[32:35], v[144:147], v[176:179], v[32:35]
	v_mfma_f32_16x16x32_bf16 v[32:35], v[156:159], v[180:183], v[32:35]
	v_mfma_f32_16x16x32_bf16 v[24:27], v[160:163], v[176:179], v[24:27]
	v_mfma_f32_16x16x32_bf16 v[24:27], v[164:167], v[180:183], v[24:27]
	v_mfma_f32_16x16x32_bf16 v[16:19], v[144:147], v[184:187], v[16:19]
	v_mfma_f32_16x16x32_bf16 v[16:19], v[156:159], v[188:191], v[16:19]
	v_mfma_f32_16x16x32_bf16 v[12:15], v[160:163], v[184:187], v[12:15]
	v_mfma_f32_16x16x32_bf16 v[12:15], v[164:167], v[188:191], v[12:15]
	v_mfma_f32_16x16x32_bf16 v[4:7], v[144:147], v[192:195], v[4:7]
	v_mfma_f32_16x16x32_bf16 v[4:7], v[156:159], v[200:203], v[4:7]
	v_mfma_f32_16x16x32_bf16 v[0:3], v[160:163], v[192:195], v[0:3]
	v_mfma_f32_16x16x32_bf16 v[0:3], v[164:167], v[200:203], v[0:3]
	s_setprio 0
	s_barrier
	s_add_i32 s21, s21, 2
	s_add_u32 s4, s4, 0x100
	s_addc_u32 s5, s5, 0
	s_add_u32 s15, s15, 0x100
	s_addc_u32 s17, s17, 0
	s_cmp_gt_u32 s21, 5
	s_cbranch_scc0 .LBB0_604
	s_and_b64 vcc, exec, s[60:61]
	s_cbranch_vccz .LBB0_607
	s_barrier

.LBB0_676:
	s_add_u32 s30, s28, 0x100
	s_addc_u32 s31, s29, 0
	s_cmp_eq_u32 s69, 28
	s_cselect_b32 s38, s5, s30
	s_cselect_b32 s39, s4, s31
	s_cselect_b32 s36, s17, s21
	s_cselect_b32 s37, s13, s27
	s_add_u32 s34, s38, 0x80
	s_addc_u32 s35, s39, 0
	s_add_i32 s74, 0, 0x10000
	s_add_i32 s84, 0, 0x14000
	v_add_u32_e32 v140, s74, v150
	v_add_u32_e32 v144, s84, v150
	ds_read_b128 v[128:131], v140
	ds_read_b128 v[132:135], v140 offset:1024
	ds_read_b128 v[136:139], v140 offset:2048
	ds_read_b128 v[140:143], v140 offset:3072
	ds_read_b128 v[152:155], v144
	ds_read_b128 v[156:159], v144 offset:1024
	ds_read_b128 v[160:163], v144 offset:2048
	ds_read_b128 v[164:167], v144 offset:3072
	s_add_u32 s28, s28, 0x80080
	s_addc_u32 s29, s29, 0
	s_add_i32 m0, s48, 0xc000
	ds_read_b128 v[168:171], v151
	ds_read_b128 v[172:175], v151 offset:1024
	ds_read_b128 v[176:179], v151 offset:2048
	ds_read_b128 v[180:183], v151 offset:3072
	ds_read_b128 v[184:187], v151 offset:4096
	ds_read_b128 v[188:191], v151 offset:5120
	ds_read_b128 v[192:195], v151 offset:6144
	ds_read_b128 v[200:203], v151 offset:7168
	s_nop 0
	global_load_lds_dwordx4 v146, s[28:29]
	s_add_i32 m0, s48, 0xe000
	s_nop 0
	global_load_lds_dwordx4 v148, s[28:29]
	s_waitcnt vmcnt(8)
	s_waitcnt lgkmcnt(0)
	s_setprio 1
	s_barrier
	v_mfma_f32_16x16x32_bf16 v[124:127], v[128:131], v[168:171], v[124:127]
	v_mfma_f32_16x16x32_bf16 v[124:127], v[132:135], v[172:175], v[124:127]
	v_mfma_f32_16x16x32_bf16 v[120:123], v[136:139], v[168:171], v[120:123]
	v_mfma_f32_16x16x32_bf16 v[120:123], v[140:143], v[172:175], v[120:123]
	v_mfma_f32_16x16x32_bf16 v[108:111], v[128:131], v[176:179], v[108:111]
	v_mfma_f32_16x16x32_bf16 v[108:111], v[132:135], v[180:183], v[108:111]
	v_mfma_f32_16x16x32_bf16 v[104:107], v[136:139], v[176:179], v[104:107]
	v_mfma_f32_16x16x32_bf16 v[104:107], v[140:143], v[180:183], v[104:107]
	v_mfma_f32_16x16x32_bf16 v[96:99], v[128:131], v[184:187], v[96:99]
	v_mfma_f32_16x16x32_bf16 v[96:99], v[132:135], v[188:191], v[96:99]
	v_mfma_f32_16x16x32_bf16 v[88:91], v[136:139], v[184:187], v[88:91]
	v_mfma_f32_16x16x32_bf16 v[88:91], v[140:143], v[188:191], v[88:91]
	v_mfma_f32_16x16x32_bf16 v[80:83], v[128:131], v[192:195], v[80:83]
	v_mfma_f32_16x16x32_bf16 v[80:83], v[132:135], v[200:203], v[80:83]
	v_mfma_f32_16x16x32_bf16 v[72:75], v[136:139], v[192:195], v[72:75]
	v_mfma_f32_16x16x32_bf16 v[72:75], v[140:143], v[200:203], v[72:75]
	v_mfma_f32_16x16x32_bf16 v[116:119], v[152:155], v[168:171], v[116:119]
	v_mfma_f32_16x16x32_bf16 v[116:119], v[156:159], v[172:175], v[116:119]
	v_mfma_f32_16x16x32_bf16 v[112:115], v[160:163], v[168:171], v[112:115]
	v_mfma_f32_16x16x32_bf16 v[112:115], v[164:167], v[172:175], v[112:115]
	v_mfma_f32_16x16x32_bf16 v[100:103], v[152:155], v[176:179], v[100:103]
	v_mfma_f32_16x16x32_bf16 v[100:103], v[156:159], v[180:183], v[100:103]
	v_mfma_f32_16x16x32_bf16 v[92:95], v[160:163], v[176:179], v[92:95]
	v_mfma_f32_16x16x32_bf16 v[92:95], v[164:167], v[180:183], v[92:95]
	v_mfma_f32_16x16x32_bf16 v[84:87], v[152:155], v[184:187], v[84:87]
	v_mfma_f32_16x16x32_bf16 v[84:87], v[156:159], v[188:191], v[84:87]
	v_mfma_f32_16x16x32_bf16 v[76:79], v[160:163], v[184:187], v[76:79]
	v_mfma_f32_16x16x32_bf16 v[76:79], v[164:167], v[188:191], v[76:79]
	v_mfma_f32_16x16x32_bf16 v[68:71], v[152:155], v[192:195], v[68:71]
	v_mfma_f32_16x16x32_bf16 v[68:71], v[156:159], v[200:203], v[68:71]
	v_mfma_f32_16x16x32_bf16 v[64:67], v[160:163], v[192:195], v[64:67]
	v_mfma_f32_16x16x32_bf16 v[64:67], v[164:167], v[200:203], v[64:67]
	s_setprio 0
	s_barrier
	s_add_i32 s74, s74, s97
	s_mov_b64 s[28:29], s[36:37]
	s_mov_b32 m0, s74
	ds_read_b128 v[168:171], v151 offset:16384
	ds_read_b128 v[172:175], v151 offset:17408
	ds_read_b128 v[176:179], v151 offset:18432
	ds_read_b128 v[180:183], v151 offset:19456
	ds_read_b128 v[184:187], v151 offset:20480
	ds_read_b128 v[188:191], v151 offset:21504
	ds_read_b128 v[192:195], v151 offset:22528
	ds_read_b128 v[200:203], v151 offset:23552
	s_nop 0
	global_load_lds_dwordx4 v147, s[28:29]
	s_add_i32 m0, s74, 0x2000
	s_nop 0
	global_load_lds_dwordx4 v149, s[28:29]
	s_add_u32 s28, s36, 0x80000
	s_addc_u32 s29, s37, 0
	s_add_i32 s74, s84, s97
	s_mov_b32 m0, s74
	s_nop 0
	global_load_lds_dwordx4 v147, s[28:29]
	s_add_i32 m0, s74, 0x2000
	s_nop 0
	global_load_lds_dwordx4 v149, s[28:29]
	s_mov_b64 s[28:29], s[38:39]
	s_mov_b32 m0, s48
	s_nop 0
	global_load_lds_dwordx4 v146, s[28:29]
	s_mov_b32 m0, s49
	s_nop 0
	global_load_lds_dwordx4 v148, s[28:29]
	s_waitcnt vmcnt(8)
	s_waitcnt lgkmcnt(0)
	s_setprio 1
	s_barrier
	v_mfma_f32_16x16x32_bf16 v[60:63], v[128:131], v[168:171], v[60:63]
	v_mfma_f32_16x16x32_bf16 v[60:63], v[132:135], v[172:175], v[60:63]
	v_mfma_f32_16x16x32_bf16 v[56:59], v[136:139], v[168:171], v[56:59]
	v_mfma_f32_16x16x32_bf16 v[56:59], v[140:143], v[172:175], v[56:59]
	v_mfma_f32_16x16x32_bf16 v[48:51], v[128:131], v[176:179], v[48:51]
	v_mfma_f32_16x16x32_bf16 v[48:51], v[132:135], v[180:183], v[48:51]
	v_mfma_f32_16x16x32_bf16 v[40:43], v[136:139], v[176:179], v[40:43]
	v_mfma_f32_16x16x32_bf16 v[40:43], v[140:143], v[180:183], v[40:43]
	v_mfma_f32_16x16x32_bf16 v[32:35], v[128:131], v[184:187], v[32:35]
	v_mfma_f32_16x16x32_bf16 v[32:35], v[132:135], v[188:191], v[32:35]
	v_mfma_f32_16x16x32_bf16 v[24:27], v[136:139], v[184:187], v[24:27]
	v_mfma_f32_16x16x32_bf16 v[24:27], v[140:143], v[188:191], v[24:27]
	v_mfma_f32_16x16x32_bf16 v[16:19], v[128:131], v[192:195], v[16:19]
	v_mfma_f32_16x16x32_bf16 v[16:19], v[132:135], v[200:203], v[16:19]
	v_mfma_f32_16x16x32_bf16 v[8:11], v[136:139], v[192:195], v[8:11]
	v_mfma_f32_16x16x32_bf16 v[8:11], v[140:143], v[200:203], v[8:11]
	v_mfma_f32_16x16x32_bf16 v[52:55], v[152:155], v[168:171], v[52:55]
	v_mfma_f32_16x16x32_bf16 v[52:55], v[156:159], v[172:175], v[52:55]
	v_mfma_f32_16x16x32_bf16 v[44:47], v[160:163], v[168:171], v[44:47]
	v_mfma_f32_16x16x32_bf16 v[44:47], v[164:167], v[172:175], v[44:47]
	v_mfma_f32_16x16x32_bf16 v[36:39], v[152:155], v[176:179], v[36:39]
	v_mfma_f32_16x16x32_bf16 v[36:39], v[156:159], v[180:183], v[36:39]
	v_mfma_f32_16x16x32_bf16 v[28:31], v[160:163], v[176:179], v[28:31]
	v_mfma_f32_16x16x32_bf16 v[28:31], v[164:167], v[180:183], v[28:31]
	v_mfma_f32_16x16x32_bf16 v[20:23], v[152:155], v[184:187], v[20:23]
	v_mfma_f32_16x16x32_bf16 v[20:23], v[156:159], v[188:191], v[20:23]
	v_mfma_f32_16x16x32_bf16 v[12:15], v[160:163], v[184:187], v[12:15]
	v_mfma_f32_16x16x32_bf16 v[12:15], v[164:167], v[188:191], v[12:15]
	v_mfma_f32_16x16x32_bf16 v[4:7], v[152:155], v[192:195], v[4:7]
	v_mfma_f32_16x16x32_bf16 v[4:7], v[156:159], v[200:203], v[4:7]
	v_mfma_f32_16x16x32_bf16 v[0:3], v[160:163], v[192:195], v[0:3]
	v_mfma_f32_16x16x32_bf16 v[0:3], v[164:167], v[200:203], v[0:3]
	s_setprio 0
	s_barrier
	s_add_i32 s74, 0, 0x18000
	s_add_i32 s84, 0, 0x1c000
	v_add_u32_e32 v140, s74, v150
	v_add_u32_e32 v144, s84, v150
	ds_read_b128 v[128:131], v140
	ds_read_b128 v[132:135], v140 offset:1024
	ds_read_b128 v[136:139], v140 offset:2048
	ds_read_b128 v[140:143], v140 offset:3072
	ds_read_b128 v[152:155], v144
	ds_read_b128 v[156:159], v144 offset:1024
	ds_read_b128 v[160:163], v144 offset:2048
	ds_read_b128 v[164:167], v144 offset:3072
	s_add_u32 s28, s38, 0x80000
	s_addc_u32 s29, s39, 0
	s_mov_b32 m0, s56
	ds_read_b128 v[168:171], v151 offset:32768
	ds_read_b128 v[172:175], v151 offset:33792
	ds_read_b128 v[176:179], v151 offset:34816
	ds_read_b128 v[180:183], v151 offset:35840
	ds_read_b128 v[184:187], v151 offset:36864
	ds_read_b128 v[188:191], v151 offset:37888
	ds_read_b128 v[192:195], v151 offset:38912
	ds_read_b128 v[200:203], v151 offset:39936
	s_nop 0
	global_load_lds_dwordx4 v146, s[28:29]
	s_mov_b32 m0, s57
	s_nop 0
	global_load_lds_dwordx4 v148, s[28:29]
	s_waitcnt vmcnt(8)
	s_waitcnt lgkmcnt(0)
	s_setprio 1
	s_barrier
	v_mfma_f32_16x16x32_bf16 v[124:127], v[128:131], v[168:171], v[124:127]
	v_mfma_f32_16x16x32_bf16 v[124:127], v[132:135], v[172:175], v[124:127]
	v_mfma_f32_16x16x32_bf16 v[120:123], v[136:139], v[168:171], v[120:123]
	v_mfma_f32_16x16x32_bf16 v[120:123], v[140:143], v[172:175], v[120:123]
	v_mfma_f32_16x16x32_bf16 v[108:111], v[128:131], v[176:179], v[108:111]
	v_mfma_f32_16x16x32_bf16 v[108:111], v[132:135], v[180:183], v[108:111]
	v_mfma_f32_16x16x32_bf16 v[104:107], v[136:139], v[176:179], v[104:107]
	v_mfma_f32_16x16x32_bf16 v[104:107], v[140:143], v[180:183], v[104:107]
	v_mfma_f32_16x16x32_bf16 v[96:99], v[128:131], v[184:187], v[96:99]
	v_mfma_f32_16x16x32_bf16 v[96:99], v[132:135], v[188:191], v[96:99]
	v_mfma_f32_16x16x32_bf16 v[88:91], v[136:139], v[184:187], v[88:91]
	v_mfma_f32_16x16x32_bf16 v[88:91], v[140:143], v[188:191], v[88:91]
	v_mfma_f32_16x16x32_bf16 v[80:83], v[128:131], v[192:195], v[80:83]
	v_mfma_f32_16x16x32_bf16 v[80:83], v[132:135], v[200:203], v[80:83]
	v_mfma_f32_16x16x32_bf16 v[72:75], v[136:139], v[192:195], v[72:75]
	v_mfma_f32_16x16x32_bf16 v[72:75], v[140:143], v[200:203], v[72:75]
	v_mfma_f32_16x16x32_bf16 v[116:119], v[152:155], v[168:171], v[116:119]
	v_mfma_f32_16x16x32_bf16 v[116:119], v[156:159], v[172:175], v[116:119]
	v_mfma_f32_16x16x32_bf16 v[112:115], v[160:163], v[168:171], v[112:115]
	v_mfma_f32_16x16x32_bf16 v[112:115], v[164:167], v[172:175], v[112:115]
	v_mfma_f32_16x16x32_bf16 v[100:103], v[152:155], v[176:179], v[100:103]
	v_mfma_f32_16x16x32_bf16 v[100:103], v[156:159], v[180:183], v[100:103]
	v_mfma_f32_16x16x32_bf16 v[92:95], v[160:163], v[176:179], v[92:95]
	v_mfma_f32_16x16x32_bf16 v[92:95], v[164:167], v[180:183], v[92:95]
	v_mfma_f32_16x16x32_bf16 v[84:87], v[152:155], v[184:187], v[84:87]
	v_mfma_f32_16x16x32_bf16 v[84:87], v[156:159], v[188:191], v[84:87]
	v_mfma_f32_16x16x32_bf16 v[76:79], v[160:163], v[184:187], v[76:79]
	v_mfma_f32_16x16x32_bf16 v[76:79], v[164:167], v[188:191], v[76:79]
	v_mfma_f32_16x16x32_bf16 v[68:71], v[152:155], v[192:195], v[68:71]
	v_mfma_f32_16x16x32_bf16 v[68:71], v[156:159], v[200:203], v[68:71]
	v_mfma_f32_16x16x32_bf16 v[64:67], v[160:163], v[192:195], v[64:67]
	v_mfma_f32_16x16x32_bf16 v[64:67], v[164:167], v[200:203], v[64:67]
	s_setprio 0
	s_barrier
	s_add_u32 s28, s36, 0x80
	s_addc_u32 s29, s37, 0
	s_add_i32 s38, s74, s97
	s_mov_b32 m0, s38
	ds_read_b128 v[168:171], v151 offset:49152
	ds_read_b128 v[172:175], v151 offset:50176
	ds_read_b128 v[176:179], v151 offset:51200
	ds_read_b128 v[180:183], v151 offset:52224
	ds_read_b128 v[184:187], v151 offset:53248
	ds_read_b128 v[188:191], v151 offset:54272
	ds_read_b128 v[192:195], v151 offset:55296
	ds_read_b128 v[200:203], v151 offset:56320
	s_nop 0
	global_load_lds_dwordx4 v147, s[28:29]
	s_add_i32 m0, s38, 0x2000
	s_nop 0
	global_load_lds_dwordx4 v149, s[28:29]
	s_add_u32 s28, s36, 0x80080
	s_addc_u32 s29, s37, 0
	s_add_i32 s36, s84, s97
	s_mov_b32 m0, s36
	s_nop 0
	global_load_lds_dwordx4 v147, s[28:29]
	s_add_i32 m0, s36, 0x2000
	s_nop 0
	global_load_lds_dwordx4 v149, s[28:29]
	s_mov_b32 m0, s82
	s_nop 0
	global_load_lds_dwordx4 v146, s[34:35]
	s_mov_b32 m0, s83
	s_nop 0
	global_load_lds_dwordx4 v148, s[34:35]
	s_waitcnt vmcnt(8)
	s_waitcnt lgkmcnt(0)
	s_setprio 1
	s_barrier
	v_mfma_f32_16x16x32_bf16 v[60:63], v[128:131], v[168:171], v[60:63]
	v_mfma_f32_16x16x32_bf16 v[60:63], v[132:135], v[172:175], v[60:63]
	v_mfma_f32_16x16x32_bf16 v[56:59], v[136:139], v[168:171], v[56:59]
	v_mfma_f32_16x16x32_bf16 v[56:59], v[140:143], v[172:175], v[56:59]
	v_mfma_f32_16x16x32_bf16 v[48:51], v[128:131], v[176:179], v[48:51]
	v_mfma_f32_16x16x32_bf16 v[48:51], v[132:135], v[180:183], v[48:51]
	v_mfma_f32_16x16x32_bf16 v[40:43], v[136:139], v[176:179], v[40:43]
	v_mfma_f32_16x16x32_bf16 v[40:43], v[140:143], v[180:183], v[40:43]
	v_mfma_f32_16x16x32_bf16 v[32:35], v[128:131], v[184:187], v[32:35]
	v_mfma_f32_16x16x32_bf16 v[32:35], v[132:135], v[188:191], v[32:35]
	v_mfma_f32_16x16x32_bf16 v[24:27], v[136:139], v[184:187], v[24:27]
	v_mfma_f32_16x16x32_bf16 v[24:27], v[140:143], v[188:191], v[24:27]
	v_mfma_f32_16x16x32_bf16 v[16:19], v[128:131], v[192:195], v[16:19]
	v_mfma_f32_16x16x32_bf16 v[16:19], v[132:135], v[200:203], v[16:19]
	v_mfma_f32_16x16x32_bf16 v[8:11], v[136:139], v[192:195], v[8:11]
	v_mfma_f32_16x16x32_bf16 v[8:11], v[140:143], v[200:203], v[8:11]
	v_mfma_f32_16x16x32_bf16 v[52:55], v[152:155], v[168:171], v[52:55]
	v_mfma_f32_16x16x32_bf16 v[52:55], v[156:159], v[172:175], v[52:55]
	v_mfma_f32_16x16x32_bf16 v[44:47], v[160:163], v[168:171], v[44:47]
	v_mfma_f32_16x16x32_bf16 v[44:47], v[164:167], v[172:175], v[44:47]
	v_mfma_f32_16x16x32_bf16 v[36:39], v[152:155], v[176:179], v[36:39]
	v_mfma_f32_16x16x32_bf16 v[36:39], v[156:159], v[180:183], v[36:39]
	v_mfma_f32_16x16x32_bf16 v[28:31], v[160:163], v[176:179], v[28:31]
	v_mfma_f32_16x16x32_bf16 v[28:31], v[164:167], v[180:183], v[28:31]
	v_mfma_f32_16x16x32_bf16 v[20:23], v[152:155], v[184:187], v[20:23]
	v_mfma_f32_16x16x32_bf16 v[20:23], v[156:159], v[188:191], v[20:23]
	v_mfma_f32_16x16x32_bf16 v[12:15], v[160:163], v[184:187], v[12:15]
	v_mfma_f32_16x16x32_bf16 v[12:15], v[164:167], v[188:191], v[12:15]
	v_mfma_f32_16x16x32_bf16 v[4:7], v[152:155], v[192:195], v[4:7]
	v_mfma_f32_16x16x32_bf16 v[4:7], v[156:159], v[200:203], v[4:7]
	v_mfma_f32_16x16x32_bf16 v[0:3], v[160:163], v[192:195], v[0:3]
	v_mfma_f32_16x16x32_bf16 v[0:3], v[164:167], v[200:203], v[0:3]
	s_setprio 0
	s_barrier
	s_add_i32 s69, s69, 2
	s_add_u32 s21, s21, 0x100
	s_addc_u32 s27, s27, 0
	s_cmp_gt_u32 s69, 29
	s_mov_b64 s[28:29], s[30:31]
	s_cbranch_scc0 .LBB0_676
	s_and_b64 vcc, exec, s[60:61]
	s_cbranch_vccz .LBB0_679
	s_barrier

.LBB0_788:
	s_add_u32 s30, s28, 0x100
	s_addc_u32 s31, s29, 0
	s_cmp_eq_u32 s17, 4
	s_cselect_b32 s38, s20, s30
	s_cselect_b32 s39, s21, s31
	s_cselect_b32 s36, s22, s5
	s_cselect_b32 s37, s23, s15
	s_add_u32 s34, s38, 0x80
	s_addc_u32 s35, s39, 0
	s_add_i32 s83, 0, 0x10000
	s_add_i32 s84, 0, 0x14000
	v_add_u32_e32 v146, s83, v136
	v_add_u32_e32 v162, s84, v136
	ds_read_b128 v[128:131], v146
	ds_read_b128 v[138:141], v146 offset:1024
	ds_read_b128 v[142:145], v146 offset:2048
	ds_read_b128 v[146:149], v146 offset:3072
	ds_read_b128 v[150:153], v162
	ds_read_b128 v[154:157], v162 offset:1024
	ds_read_b128 v[158:161], v162 offset:2048
	ds_read_b128 v[162:165], v162 offset:3072
	s_add_u32 s28, s28, 0x20080
	s_addc_u32 s29, s29, 0
	s_add_i32 m0, s27, 0xc000
	ds_read_b128 v[166:169], v137
	ds_read_b128 v[170:173], v137 offset:1024
	ds_read_b128 v[174:177], v137 offset:2048
	ds_read_b128 v[178:181], v137 offset:3072
	ds_read_b128 v[182:185], v137 offset:4096
	ds_read_b128 v[186:189], v137 offset:5120
	ds_read_b128 v[190:193], v137 offset:6144
	ds_read_b128 v[200:203], v137 offset:7168
	s_nop 0
	global_load_lds_dwordx4 v132, s[28:29]
	s_add_i32 m0, s27, 0xe000
	s_nop 0
	global_load_lds_dwordx4 v134, s[28:29]
	s_waitcnt vmcnt(8)
	s_waitcnt lgkmcnt(0)
	s_setprio 1
	s_barrier
	v_mfma_f32_16x16x32_bf16 v[124:127], v[128:131], v[166:169], v[124:127]
	v_mfma_f32_16x16x32_bf16 v[124:127], v[138:141], v[170:173], v[124:127]
	v_mfma_f32_16x16x32_bf16 v[120:123], v[142:145], v[166:169], v[120:123]
	v_mfma_f32_16x16x32_bf16 v[120:123], v[146:149], v[170:173], v[120:123]
	v_mfma_f32_16x16x32_bf16 v[108:111], v[128:131], v[174:177], v[108:111]
	v_mfma_f32_16x16x32_bf16 v[108:111], v[138:141], v[178:181], v[108:111]
	v_mfma_f32_16x16x32_bf16 v[104:107], v[142:145], v[174:177], v[104:107]
	v_mfma_f32_16x16x32_bf16 v[104:107], v[146:149], v[178:181], v[104:107]
	v_mfma_f32_16x16x32_bf16 v[92:95], v[128:131], v[182:185], v[92:95]
	v_mfma_f32_16x16x32_bf16 v[92:95], v[138:141], v[186:189], v[92:95]
	v_mfma_f32_16x16x32_bf16 v[88:91], v[142:145], v[182:185], v[88:91]
	v_mfma_f32_16x16x32_bf16 v[88:91], v[146:149], v[186:189], v[88:91]
	v_mfma_f32_16x16x32_bf16 v[76:79], v[128:131], v[190:193], v[76:79]
	v_mfma_f32_16x16x32_bf16 v[76:79], v[138:141], v[200:203], v[76:79]
	v_mfma_f32_16x16x32_bf16 v[72:75], v[142:145], v[190:193], v[72:75]
	v_mfma_f32_16x16x32_bf16 v[72:75], v[146:149], v[200:203], v[72:75]
	v_mfma_f32_16x16x32_bf16 v[116:119], v[150:153], v[166:169], v[116:119]
	v_mfma_f32_16x16x32_bf16 v[116:119], v[154:157], v[170:173], v[116:119]
	v_mfma_f32_16x16x32_bf16 v[112:115], v[158:161], v[166:169], v[112:115]
	v_mfma_f32_16x16x32_bf16 v[112:115], v[162:165], v[170:173], v[112:115]
	v_mfma_f32_16x16x32_bf16 v[100:103], v[150:153], v[174:177], v[100:103]
	v_mfma_f32_16x16x32_bf16 v[100:103], v[154:157], v[178:181], v[100:103]
	v_mfma_f32_16x16x32_bf16 v[96:99], v[158:161], v[174:177], v[96:99]
	v_mfma_f32_16x16x32_bf16 v[96:99], v[162:165], v[178:181], v[96:99]
	v_mfma_f32_16x16x32_bf16 v[84:87], v[150:153], v[182:185], v[84:87]
	v_mfma_f32_16x16x32_bf16 v[84:87], v[154:157], v[186:189], v[84:87]
	v_mfma_f32_16x16x32_bf16 v[80:83], v[158:161], v[182:185], v[80:83]
	v_mfma_f32_16x16x32_bf16 v[80:83], v[162:165], v[186:189], v[80:83]
	v_mfma_f32_16x16x32_bf16 v[68:71], v[150:153], v[190:193], v[68:71]
	v_mfma_f32_16x16x32_bf16 v[68:71], v[154:157], v[200:203], v[68:71]
	v_mfma_f32_16x16x32_bf16 v[64:67], v[158:161], v[190:193], v[64:67]
	v_mfma_f32_16x16x32_bf16 v[64:67], v[162:165], v[200:203], v[64:67]
	s_setprio 0
	s_barrier
	s_add_i32 s83, s83, s97
	s_mov_b64 s[28:29], s[36:37]
	s_mov_b32 m0, s83
	ds_read_b128 v[166:169], v137 offset:16384
	ds_read_b128 v[170:173], v137 offset:17408
	ds_read_b128 v[174:177], v137 offset:18432
	ds_read_b128 v[178:181], v137 offset:19456
	ds_read_b128 v[182:185], v137 offset:20480
	ds_read_b128 v[186:189], v137 offset:21504
	ds_read_b128 v[190:193], v137 offset:22528
	ds_read_b128 v[200:203], v137 offset:23552
	s_nop 0
	global_load_lds_dwordx4 v133, s[28:29]
	s_add_i32 m0, s83, 0x2000
	s_nop 0
	global_load_lds_dwordx4 v135, s[28:29]
	s_add_u32 s28, s36, 0x20000
	s_addc_u32 s29, s37, 0
	s_add_i32 s83, s84, s97
	s_mov_b32 m0, s83
	s_nop 0
	global_load_lds_dwordx4 v133, s[28:29]
	s_add_i32 m0, s83, 0x2000
	s_nop 0
	global_load_lds_dwordx4 v135, s[28:29]
	s_mov_b64 s[28:29], s[38:39]
	s_mov_b32 m0, s27
	s_nop 0
	global_load_lds_dwordx4 v132, s[28:29]
	s_mov_b32 m0, s69
	s_nop 0
	global_load_lds_dwordx4 v134, s[28:29]
	s_waitcnt vmcnt(8)
	s_waitcnt lgkmcnt(0)
	s_setprio 1
	s_barrier
	v_mfma_f32_16x16x32_bf16 v[60:63], v[128:131], v[166:169], v[60:63]
	v_mfma_f32_16x16x32_bf16 v[60:63], v[138:141], v[170:173], v[60:63]
	v_mfma_f32_16x16x32_bf16 v[56:59], v[142:145], v[166:169], v[56:59]
	v_mfma_f32_16x16x32_bf16 v[56:59], v[146:149], v[170:173], v[56:59]
	v_mfma_f32_16x16x32_bf16 v[44:47], v[128:131], v[174:177], v[44:47]
	v_mfma_f32_16x16x32_bf16 v[44:47], v[138:141], v[178:181], v[44:47]
	v_mfma_f32_16x16x32_bf16 v[40:43], v[142:145], v[174:177], v[40:43]
	v_mfma_f32_16x16x32_bf16 v[40:43], v[146:149], v[178:181], v[40:43]
	v_mfma_f32_16x16x32_bf16 v[28:31], v[128:131], v[182:185], v[28:31]
	v_mfma_f32_16x16x32_bf16 v[28:31], v[138:141], v[186:189], v[28:31]
	v_mfma_f32_16x16x32_bf16 v[24:27], v[142:145], v[182:185], v[24:27]
	v_mfma_f32_16x16x32_bf16 v[24:27], v[146:149], v[186:189], v[24:27]
	v_mfma_f32_16x16x32_bf16 v[12:15], v[128:131], v[190:193], v[12:15]
	v_mfma_f32_16x16x32_bf16 v[12:15], v[138:141], v[200:203], v[12:15]
	v_mfma_f32_16x16x32_bf16 v[8:11], v[142:145], v[190:193], v[8:11]
	v_mfma_f32_16x16x32_bf16 v[8:11], v[146:149], v[200:203], v[8:11]
	v_mfma_f32_16x16x32_bf16 v[52:55], v[150:153], v[166:169], v[52:55]
	v_mfma_f32_16x16x32_bf16 v[52:55], v[154:157], v[170:173], v[52:55]
	v_mfma_f32_16x16x32_bf16 v[48:51], v[158:161], v[166:169], v[48:51]
	v_mfma_f32_16x16x32_bf16 v[48:51], v[162:165], v[170:173], v[48:51]
	v_mfma_f32_16x16x32_bf16 v[36:39], v[150:153], v[174:177], v[36:39]
	v_mfma_f32_16x16x32_bf16 v[36:39], v[154:157], v[178:181], v[36:39]
	v_mfma_f32_16x16x32_bf16 v[32:35], v[158:161], v[174:177], v[32:35]
	v_mfma_f32_16x16x32_bf16 v[32:35], v[162:165], v[178:181], v[32:35]
	v_mfma_f32_16x16x32_bf16 v[20:23], v[150:153], v[182:185], v[20:23]
	v_mfma_f32_16x16x32_bf16 v[20:23], v[154:157], v[186:189], v[20:23]
	v_mfma_f32_16x16x32_bf16 v[16:19], v[158:161], v[182:185], v[16:19]
	v_mfma_f32_16x16x32_bf16 v[16:19], v[162:165], v[186:189], v[16:19]
	v_mfma_f32_16x16x32_bf16 v[4:7], v[150:153], v[190:193], v[4:7]
	v_mfma_f32_16x16x32_bf16 v[4:7], v[154:157], v[200:203], v[4:7]
	v_mfma_f32_16x16x32_bf16 v[0:3], v[158:161], v[190:193], v[0:3]
	v_mfma_f32_16x16x32_bf16 v[0:3], v[162:165], v[200:203], v[0:3]
	s_setprio 0
	s_barrier
	s_add_i32 s83, 0, 0x18000
	s_add_i32 s84, 0, 0x1c000
	v_add_u32_e32 v146, s83, v136
	v_add_u32_e32 v162, s84, v136
	ds_read_b128 v[128:131], v146
	ds_read_b128 v[138:141], v146 offset:1024
	ds_read_b128 v[142:145], v146 offset:2048
	ds_read_b128 v[146:149], v146 offset:3072
	ds_read_b128 v[150:153], v162
	ds_read_b128 v[154:157], v162 offset:1024
	ds_read_b128 v[158:161], v162 offset:2048
	ds_read_b128 v[162:165], v162 offset:3072
	s_add_u32 s28, s38, 0x20000
	s_addc_u32 s29, s39, 0
	s_mov_b32 m0, s71
	ds_read_b128 v[166:169], v137 offset:32768
	ds_read_b128 v[170:173], v137 offset:33792
	ds_read_b128 v[174:177], v137 offset:34816
	ds_read_b128 v[178:181], v137 offset:35840
	ds_read_b128 v[182:185], v137 offset:36864
	ds_read_b128 v[186:189], v137 offset:37888
	ds_read_b128 v[190:193], v137 offset:38912
	ds_read_b128 v[200:203], v137 offset:39936
	s_nop 0
	global_load_lds_dwordx4 v132, s[28:29]
	s_mov_b32 m0, s72
	s_nop 0
	global_load_lds_dwordx4 v134, s[28:29]
	s_waitcnt vmcnt(8)
	s_waitcnt lgkmcnt(0)
	s_setprio 1
	s_barrier
	v_mfma_f32_16x16x32_bf16 v[124:127], v[128:131], v[166:169], v[124:127]
	v_mfma_f32_16x16x32_bf16 v[124:127], v[138:141], v[170:173], v[124:127]
	v_mfma_f32_16x16x32_bf16 v[120:123], v[142:145], v[166:169], v[120:123]
	v_mfma_f32_16x16x32_bf16 v[120:123], v[146:149], v[170:173], v[120:123]
	v_mfma_f32_16x16x32_bf16 v[108:111], v[128:131], v[174:177], v[108:111]
	v_mfma_f32_16x16x32_bf16 v[108:111], v[138:141], v[178:181], v[108:111]
	v_mfma_f32_16x16x32_bf16 v[104:107], v[142:145], v[174:177], v[104:107]
	v_mfma_f32_16x16x32_bf16 v[104:107], v[146:149], v[178:181], v[104:107]
	v_mfma_f32_16x16x32_bf16 v[92:95], v[128:131], v[182:185], v[92:95]
	v_mfma_f32_16x16x32_bf16 v[92:95], v[138:141], v[186:189], v[92:95]
	v_mfma_f32_16x16x32_bf16 v[88:91], v[142:145], v[182:185], v[88:91]
	v_mfma_f32_16x16x32_bf16 v[88:91], v[146:149], v[186:189], v[88:91]
	v_mfma_f32_16x16x32_bf16 v[76:79], v[128:131], v[190:193], v[76:79]
	v_mfma_f32_16x16x32_bf16 v[76:79], v[138:141], v[200:203], v[76:79]
	v_mfma_f32_16x16x32_bf16 v[72:75], v[142:145], v[190:193], v[72:75]
	v_mfma_f32_16x16x32_bf16 v[72:75], v[146:149], v[200:203], v[72:75]
	v_mfma_f32_16x16x32_bf16 v[116:119], v[150:153], v[166:169], v[116:119]
	v_mfma_f32_16x16x32_bf16 v[116:119], v[154:157], v[170:173], v[116:119]
	v_mfma_f32_16x16x32_bf16 v[112:115], v[158:161], v[166:169], v[112:115]
	v_mfma_f32_16x16x32_bf16 v[112:115], v[162:165], v[170:173], v[112:115]
	v_mfma_f32_16x16x32_bf16 v[100:103], v[150:153], v[174:177], v[100:103]
	v_mfma_f32_16x16x32_bf16 v[100:103], v[154:157], v[178:181], v[100:103]
	v_mfma_f32_16x16x32_bf16 v[96:99], v[158:161], v[174:177], v[96:99]
	v_mfma_f32_16x16x32_bf16 v[96:99], v[162:165], v[178:181], v[96:99]
	v_mfma_f32_16x16x32_bf16 v[84:87], v[150:153], v[182:185], v[84:87]
	v_mfma_f32_16x16x32_bf16 v[84:87], v[154:157], v[186:189], v[84:87]
	v_mfma_f32_16x16x32_bf16 v[80:83], v[158:161], v[182:185], v[80:83]
	v_mfma_f32_16x16x32_bf16 v[80:83], v[162:165], v[186:189], v[80:83]
	v_mfma_f32_16x16x32_bf16 v[68:71], v[150:153], v[190:193], v[68:71]
	v_mfma_f32_16x16x32_bf16 v[68:71], v[154:157], v[200:203], v[68:71]
	v_mfma_f32_16x16x32_bf16 v[64:67], v[158:161], v[190:193], v[64:67]
	v_mfma_f32_16x16x32_bf16 v[64:67], v[162:165], v[200:203], v[64:67]
	s_setprio 0
	s_barrier
	s_add_u32 s28, s36, 0x80
	s_addc_u32 s29, s37, 0
	s_add_i32 s38, s83, s97
	s_mov_b32 m0, s38
	ds_read_b128 v[166:169], v137 offset:49152
	ds_read_b128 v[170:173], v137 offset:50176
	ds_read_b128 v[174:177], v137 offset:51200
	ds_read_b128 v[178:181], v137 offset:52224
	ds_read_b128 v[182:185], v137 offset:53248
	ds_read_b128 v[186:189], v137 offset:54272
	ds_read_b128 v[190:193], v137 offset:55296
	ds_read_b128 v[200:203], v137 offset:56320
	s_nop 0
	global_load_lds_dwordx4 v133, s[28:29]
	s_add_i32 m0, s38, 0x2000
	s_nop 0
	global_load_lds_dwordx4 v135, s[28:29]
	s_add_u32 s28, s36, 0x20080
	s_addc_u32 s29, s37, 0
	s_add_i32 s36, s84, s97
	s_mov_b32 m0, s36
	s_nop 0
	global_load_lds_dwordx4 v133, s[28:29]
	s_add_i32 m0, s36, 0x2000
	s_nop 0
	global_load_lds_dwordx4 v135, s[28:29]
	s_mov_b32 m0, s80
	s_nop 0
	global_load_lds_dwordx4 v132, s[34:35]
	s_mov_b32 m0, s81
	s_nop 0
	global_load_lds_dwordx4 v134, s[34:35]
	s_waitcnt vmcnt(8)
	s_waitcnt lgkmcnt(0)
	s_setprio 1
	s_barrier
	v_mfma_f32_16x16x32_bf16 v[60:63], v[128:131], v[166:169], v[60:63]
	v_mfma_f32_16x16x32_bf16 v[60:63], v[138:141], v[170:173], v[60:63]
	v_mfma_f32_16x16x32_bf16 v[56:59], v[142:145], v[166:169], v[56:59]
	v_mfma_f32_16x16x32_bf16 v[56:59], v[146:149], v[170:173], v[56:59]
	v_mfma_f32_16x16x32_bf16 v[44:47], v[128:131], v[174:177], v[44:47]
	v_mfma_f32_16x16x32_bf16 v[44:47], v[138:141], v[178:181], v[44:47]
	v_mfma_f32_16x16x32_bf16 v[40:43], v[142:145], v[174:177], v[40:43]
	v_mfma_f32_16x16x32_bf16 v[40:43], v[146:149], v[178:181], v[40:43]
	v_mfma_f32_16x16x32_bf16 v[28:31], v[128:131], v[182:185], v[28:31]
	v_mfma_f32_16x16x32_bf16 v[28:31], v[138:141], v[186:189], v[28:31]
	v_mfma_f32_16x16x32_bf16 v[24:27], v[142:145], v[182:185], v[24:27]
	v_mfma_f32_16x16x32_bf16 v[24:27], v[146:149], v[186:189], v[24:27]
	v_mfma_f32_16x16x32_bf16 v[12:15], v[128:131], v[190:193], v[12:15]
	v_mfma_f32_16x16x32_bf16 v[12:15], v[138:141], v[200:203], v[12:15]
	v_mfma_f32_16x16x32_bf16 v[8:11], v[142:145], v[190:193], v[8:11]
	v_mfma_f32_16x16x32_bf16 v[8:11], v[146:149], v[200:203], v[8:11]
	v_mfma_f32_16x16x32_bf16 v[52:55], v[150:153], v[166:169], v[52:55]
	v_mfma_f32_16x16x32_bf16 v[52:55], v[154:157], v[170:173], v[52:55]
	v_mfma_f32_16x16x32_bf16 v[48:51], v[158:161], v[166:169], v[48:51]
	v_mfma_f32_16x16x32_bf16 v[48:51], v[162:165], v[170:173], v[48:51]
	v_mfma_f32_16x16x32_bf16 v[36:39], v[150:153], v[174:177], v[36:39]
	v_mfma_f32_16x16x32_bf16 v[36:39], v[154:157], v[178:181], v[36:39]
	v_mfma_f32_16x16x32_bf16 v[32:35], v[158:161], v[174:177], v[32:35]
	v_mfma_f32_16x16x32_bf16 v[32:35], v[162:165], v[178:181], v[32:35]
	v_mfma_f32_16x16x32_bf16 v[20:23], v[150:153], v[182:185], v[20:23]
	v_mfma_f32_16x16x32_bf16 v[20:23], v[154:157], v[186:189], v[20:23]
	v_mfma_f32_16x16x32_bf16 v[16:19], v[158:161], v[182:185], v[16:19]
	v_mfma_f32_16x16x32_bf16 v[16:19], v[162:165], v[186:189], v[16:19]
	v_mfma_f32_16x16x32_bf16 v[4:7], v[150:153], v[190:193], v[4:7]
	v_mfma_f32_16x16x32_bf16 v[4:7], v[154:157], v[200:203], v[4:7]
	v_mfma_f32_16x16x32_bf16 v[0:3], v[158:161], v[190:193], v[0:3]
	v_mfma_f32_16x16x32_bf16 v[0:3], v[162:165], v[200:203], v[0:3]
	s_setprio 0
	s_barrier
	s_add_i32 s17, s17, 2
	s_add_u32 s5, s5, 0x100
	s_addc_u32 s15, s15, 0
	s_cmp_gt_u32 s17, 5
	s_mov_b64 s[28:29], s[30:31]
	s_cbranch_scc0 .LBB0_788
	s_and_b64 vcc, exec, s[60:61]
	s_cbranch_vccz .LBB0_791
	s_barrier

.LBB0_1050:
	s_cmp_eq_u32 s83, 28
	s_cselect_b32 s56, s5, s39
	s_cselect_b32 s57, s4, s69
	s_cselect_b32 s84, s37, s72
	s_cselect_b32 s85, s11, s74
	s_add_u32 s12, s56, 0x80
	s_addc_u32 s13, s57, 0
	s_add_i32 vcc_lo, 0, 0x10000
	s_add_i32 vcc_hi, 0, 0x14000
	v_add_u32_e32 v136, vcc_lo, v184
	v_add_u32_e32 v156, vcc_hi, v184
	ds_read_b128 v[104:107], v136
	ds_read_b128 v[108:111], v136 offset:1024
	ds_read_b128 v[132:135], v136 offset:2048
	ds_read_b128 v[136:139], v136 offset:3072
	ds_read_b128 v[144:147], v156
	ds_read_b128 v[148:151], v156 offset:1024
	ds_read_b128 v[152:155], v156 offset:2048
	ds_read_b128 v[156:159], v156 offset:3072
	s_mov_b64 s[86:87], s[8:9]
	s_add_i32 m0, s92, 0xc000
	ds_read_b128 v[160:163], v185
	ds_read_b128 v[164:167], v185 offset:1024
	ds_read_b128 v[168:171], v185 offset:2048
	ds_read_b128 v[172:175], v185 offset:3072
	ds_read_b128 v[186:189], v185 offset:4096
	ds_read_b128 v[190:193], v185 offset:5120
	ds_read_b128 v[200:203], v185 offset:6144
	ds_read_b128 v[204:207], v185 offset:7168
	s_nop 0
	global_load_lds_dwordx4 v179, s[86:87]
	s_add_i32 m0, s92, 0xe000
	s_nop 0
	global_load_lds_dwordx4 v182, s[86:87]
	s_waitcnt vmcnt(8)
	s_waitcnt lgkmcnt(0)
	s_setprio 1
	s_barrier
	v_mfma_f32_16x16x32_bf16 v[140:143], v[104:107], v[160:163], v[140:143]
	v_mfma_f32_16x16x32_bf16 v[140:143], v[108:111], v[164:167], v[140:143]
	v_mfma_f32_16x16x32_bf16 v[128:131], v[132:135], v[160:163], v[128:131]
	v_mfma_f32_16x16x32_bf16 v[128:131], v[136:139], v[164:167], v[128:131]
	v_mfma_f32_16x16x32_bf16 v[124:127], v[104:107], v[168:171], v[124:127]
	v_mfma_f32_16x16x32_bf16 v[124:127], v[108:111], v[172:175], v[124:127]
	v_mfma_f32_16x16x32_bf16 v[112:115], v[132:135], v[168:171], v[112:115]
	v_mfma_f32_16x16x32_bf16 v[112:115], v[136:139], v[172:175], v[112:115]
	v_mfma_f32_16x16x32_bf16 v[96:99], v[104:107], v[186:189], v[96:99]
	v_mfma_f32_16x16x32_bf16 v[96:99], v[108:111], v[190:193], v[96:99]
	v_mfma_f32_16x16x32_bf16 v[88:91], v[132:135], v[186:189], v[88:91]
	v_mfma_f32_16x16x32_bf16 v[88:91], v[136:139], v[190:193], v[88:91]
	v_mfma_f32_16x16x32_bf16 v[84:87], v[104:107], v[200:203], v[84:87]
	v_mfma_f32_16x16x32_bf16 v[84:87], v[108:111], v[204:207], v[84:87]
	v_mfma_f32_16x16x32_bf16 v[72:75], v[132:135], v[200:203], v[72:75]
	v_mfma_f32_16x16x32_bf16 v[72:75], v[136:139], v[204:207], v[72:75]
	v_mfma_f32_16x16x32_bf16 v[120:123], v[144:147], v[160:163], v[120:123]
	v_mfma_f32_16x16x32_bf16 v[120:123], v[148:151], v[164:167], v[120:123]
	v_mfma_f32_16x16x32_bf16 v[116:119], v[152:155], v[160:163], v[116:119]
	v_mfma_f32_16x16x32_bf16 v[116:119], v[156:159], v[164:167], v[116:119]
	v_mfma_f32_16x16x32_bf16 v[100:103], v[144:147], v[168:171], v[100:103]
	v_mfma_f32_16x16x32_bf16 v[100:103], v[148:151], v[172:175], v[100:103]
	v_mfma_f32_16x16x32_bf16 v[92:95], v[152:155], v[168:171], v[92:95]
	v_mfma_f32_16x16x32_bf16 v[92:95], v[156:159], v[172:175], v[92:95]
	v_mfma_f32_16x16x32_bf16 v[80:83], v[144:147], v[186:189], v[80:83]
	v_mfma_f32_16x16x32_bf16 v[80:83], v[148:151], v[190:193], v[80:83]
	v_mfma_f32_16x16x32_bf16 v[76:79], v[152:155], v[186:189], v[76:79]
	v_mfma_f32_16x16x32_bf16 v[76:79], v[156:159], v[190:193], v[76:79]
	v_mfma_f32_16x16x32_bf16 v[68:71], v[144:147], v[200:203], v[68:71]
	v_mfma_f32_16x16x32_bf16 v[68:71], v[148:151], v[204:207], v[68:71]
	v_mfma_f32_16x16x32_bf16 v[64:67], v[152:155], v[200:203], v[64:67]
	v_mfma_f32_16x16x32_bf16 v[64:67], v[156:159], v[204:207], v[64:67]
	s_setprio 0
	s_barrier
	s_add_i32 vcc_lo, vcc_lo, s97
	s_mov_b64 s[86:87], s[84:85]
	s_mov_b32 m0, vcc_lo
	ds_read_b128 v[160:163], v185 offset:16384
	ds_read_b128 v[164:167], v185 offset:17408
	ds_read_b128 v[168:171], v185 offset:18432
	ds_read_b128 v[172:175], v185 offset:19456
	ds_read_b128 v[186:189], v185 offset:20480
	ds_read_b128 v[190:193], v185 offset:21504
	ds_read_b128 v[200:203], v185 offset:22528
	ds_read_b128 v[204:207], v185 offset:23552
	s_nop 0
	global_load_lds_dwordx4 v181, s[86:87]
	s_add_i32 m0, vcc_lo, 0x2000
	s_nop 0
	global_load_lds_dwordx4 v183, s[86:87]
	s_add_u32 s86, s84, 0x80000
	s_addc_u32 s87, s85, 0
	s_add_i32 vcc_lo, vcc_hi, s97
	s_mov_b32 m0, vcc_lo
	s_nop 0
	global_load_lds_dwordx4 v181, s[86:87]
	s_add_i32 m0, vcc_lo, 0x2000
	s_nop 0
	global_load_lds_dwordx4 v183, s[86:87]
	s_mov_b64 s[86:87], s[56:57]
	s_mov_b32 m0, s92
	s_nop 0
	global_load_lds_dwordx4 v179, s[86:87]
	s_mov_b32 m0, s93
	s_nop 0
	global_load_lds_dwordx4 v182, s[86:87]
	s_waitcnt vmcnt(8)
	s_waitcnt lgkmcnt(0)
	s_setprio 1
	s_barrier
	v_mfma_f32_16x16x32_bf16 v[60:63], v[104:107], v[160:163], v[60:63]
	v_mfma_f32_16x16x32_bf16 v[60:63], v[108:111], v[164:167], v[60:63]
	v_mfma_f32_16x16x32_bf16 v[56:59], v[132:135], v[160:163], v[56:59]
	v_mfma_f32_16x16x32_bf16 v[56:59], v[136:139], v[164:167], v[56:59]
	v_mfma_f32_16x16x32_bf16 v[48:51], v[104:107], v[168:171], v[48:51]
	v_mfma_f32_16x16x32_bf16 v[48:51], v[108:111], v[172:175], v[48:51]
	v_mfma_f32_16x16x32_bf16 v[40:43], v[132:135], v[168:171], v[40:43]
	v_mfma_f32_16x16x32_bf16 v[40:43], v[136:139], v[172:175], v[40:43]
	v_mfma_f32_16x16x32_bf16 v[32:35], v[104:107], v[186:189], v[32:35]
	v_mfma_f32_16x16x32_bf16 v[32:35], v[108:111], v[190:193], v[32:35]
	v_mfma_f32_16x16x32_bf16 v[24:27], v[132:135], v[186:189], v[24:27]
	v_mfma_f32_16x16x32_bf16 v[24:27], v[136:139], v[190:193], v[24:27]
	v_mfma_f32_16x16x32_bf16 v[16:19], v[104:107], v[200:203], v[16:19]
	v_mfma_f32_16x16x32_bf16 v[16:19], v[108:111], v[204:207], v[16:19]
	v_mfma_f32_16x16x32_bf16 v[8:11], v[132:135], v[200:203], v[8:11]
	v_mfma_f32_16x16x32_bf16 v[8:11], v[136:139], v[204:207], v[8:11]
	v_mfma_f32_16x16x32_bf16 v[52:55], v[144:147], v[160:163], v[52:55]
	v_mfma_f32_16x16x32_bf16 v[52:55], v[148:151], v[164:167], v[52:55]
	v_mfma_f32_16x16x32_bf16 v[44:47], v[152:155], v[160:163], v[44:47]
	v_mfma_f32_16x16x32_bf16 v[44:47], v[156:159], v[164:167], v[44:47]
	v_mfma_f32_16x16x32_bf16 v[36:39], v[144:147], v[168:171], v[36:39]
	v_mfma_f32_16x16x32_bf16 v[36:39], v[148:151], v[172:175], v[36:39]
	v_mfma_f32_16x16x32_bf16 v[28:31], v[152:155], v[168:171], v[28:31]
	v_mfma_f32_16x16x32_bf16 v[28:31], v[156:159], v[172:175], v[28:31]
	v_mfma_f32_16x16x32_bf16 v[20:23], v[144:147], v[186:189], v[20:23]
	v_mfma_f32_16x16x32_bf16 v[20:23], v[148:151], v[190:193], v[20:23]
	v_mfma_f32_16x16x32_bf16 v[12:15], v[152:155], v[186:189], v[12:15]
	v_mfma_f32_16x16x32_bf16 v[12:15], v[156:159], v[190:193], v[12:15]
	v_mfma_f32_16x16x32_bf16 v[4:7], v[144:147], v[200:203], v[4:7]
	v_mfma_f32_16x16x32_bf16 v[4:7], v[148:151], v[204:207], v[4:7]
	v_mfma_f32_16x16x32_bf16 v[0:3], v[152:155], v[200:203], v[0:3]
	v_mfma_f32_16x16x32_bf16 v[0:3], v[156:159], v[204:207], v[0:3]
	s_setprio 0
	s_barrier
	s_add_i32 s86, 0, 0x18000
	s_add_i32 s87, 0, 0x1c000
	v_add_u32_e32 v136, s86, v184
	v_add_u32_e32 v156, s87, v184
	ds_read_b128 v[104:107], v136
	ds_read_b128 v[108:111], v136 offset:1024
	ds_read_b128 v[132:135], v136 offset:2048
	ds_read_b128 v[136:139], v136 offset:3072
	ds_read_b128 v[144:147], v156
	ds_read_b128 v[148:151], v156 offset:1024
	ds_read_b128 v[152:155], v156 offset:2048
	ds_read_b128 v[156:159], v156 offset:3072
	s_add_u32 s56, s56, 0x80000
	s_addc_u32 s57, s57, 0
	s_mov_b32 m0, s80
	ds_read_b128 v[160:163], v185 offset:32768
	ds_read_b128 v[164:167], v185 offset:33792
	ds_read_b128 v[168:171], v185 offset:34816
	ds_read_b128 v[172:175], v185 offset:35840
	ds_read_b128 v[186:189], v185 offset:36864
	ds_read_b128 v[190:193], v185 offset:37888
	ds_read_b128 v[200:203], v185 offset:38912
	ds_read_b128 v[204:207], v185 offset:39936
	s_nop 0
	global_load_lds_dwordx4 v179, s[56:57]
	s_mov_b32 m0, s48
	s_nop 0
	global_load_lds_dwordx4 v182, s[56:57]
	s_waitcnt vmcnt(8)
	s_waitcnt lgkmcnt(0)
	s_setprio 1
	s_barrier
	v_mfma_f32_16x16x32_bf16 v[140:143], v[104:107], v[160:163], v[140:143]
	v_mfma_f32_16x16x32_bf16 v[140:143], v[108:111], v[164:167], v[140:143]
	v_mfma_f32_16x16x32_bf16 v[128:131], v[132:135], v[160:163], v[128:131]
	v_mfma_f32_16x16x32_bf16 v[128:131], v[136:139], v[164:167], v[128:131]
	v_mfma_f32_16x16x32_bf16 v[124:127], v[104:107], v[168:171], v[124:127]
	v_mfma_f32_16x16x32_bf16 v[124:127], v[108:111], v[172:175], v[124:127]
	v_mfma_f32_16x16x32_bf16 v[112:115], v[132:135], v[168:171], v[112:115]
	v_mfma_f32_16x16x32_bf16 v[112:115], v[136:139], v[172:175], v[112:115]
	v_mfma_f32_16x16x32_bf16 v[96:99], v[104:107], v[186:189], v[96:99]
	v_mfma_f32_16x16x32_bf16 v[96:99], v[108:111], v[190:193], v[96:99]
	v_mfma_f32_16x16x32_bf16 v[88:91], v[132:135], v[186:189], v[88:91]
	v_mfma_f32_16x16x32_bf16 v[88:91], v[136:139], v[190:193], v[88:91]
	v_mfma_f32_16x16x32_bf16 v[84:87], v[104:107], v[200:203], v[84:87]
	v_mfma_f32_16x16x32_bf16 v[84:87], v[108:111], v[204:207], v[84:87]
	v_mfma_f32_16x16x32_bf16 v[72:75], v[132:135], v[200:203], v[72:75]
	v_mfma_f32_16x16x32_bf16 v[72:75], v[136:139], v[204:207], v[72:75]
	v_mfma_f32_16x16x32_bf16 v[120:123], v[144:147], v[160:163], v[120:123]
	v_mfma_f32_16x16x32_bf16 v[120:123], v[148:151], v[164:167], v[120:123]
	v_mfma_f32_16x16x32_bf16 v[116:119], v[152:155], v[160:163], v[116:119]
	v_mfma_f32_16x16x32_bf16 v[116:119], v[156:159], v[164:167], v[116:119]
	v_mfma_f32_16x16x32_bf16 v[100:103], v[144:147], v[168:171], v[100:103]
	v_mfma_f32_16x16x32_bf16 v[100:103], v[148:151], v[172:175], v[100:103]
	v_mfma_f32_16x16x32_bf16 v[92:95], v[152:155], v[168:171], v[92:95]
	v_mfma_f32_16x16x32_bf16 v[92:95], v[156:159], v[172:175], v[92:95]
	v_mfma_f32_16x16x32_bf16 v[80:83], v[144:147], v[186:189], v[80:83]
	v_mfma_f32_16x16x32_bf16 v[80:83], v[148:151], v[190:193], v[80:83]
	v_mfma_f32_16x16x32_bf16 v[76:79], v[152:155], v[186:189], v[76:79]
	v_mfma_f32_16x16x32_bf16 v[76:79], v[156:159], v[190:193], v[76:79]
	v_mfma_f32_16x16x32_bf16 v[68:71], v[144:147], v[200:203], v[68:71]
	v_mfma_f32_16x16x32_bf16 v[68:71], v[148:151], v[204:207], v[68:71]
	v_mfma_f32_16x16x32_bf16 v[64:67], v[152:155], v[200:203], v[64:67]
	v_mfma_f32_16x16x32_bf16 v[64:67], v[156:159], v[204:207], v[64:67]
	s_setprio 0
	s_barrier
	s_add_u32 s56, s84, 0x80
	s_addc_u32 s57, s85, 0
	s_add_i32 s86, s86, s97
	s_mov_b32 m0, s86
	ds_read_b128 v[160:163], v185 offset:49152
	ds_read_b128 v[164:167], v185 offset:50176
	ds_read_b128 v[168:171], v185 offset:51200
	ds_read_b128 v[172:175], v185 offset:52224
	ds_read_b128 v[186:189], v185 offset:53248
	ds_read_b128 v[190:193], v185 offset:54272
	ds_read_b128 v[200:203], v185 offset:55296
	ds_read_b128 v[204:207], v185 offset:56320
	s_nop 0
	global_load_lds_dwordx4 v181, s[56:57]
	s_add_i32 m0, s86, 0x2000
	s_nop 0
	global_load_lds_dwordx4 v183, s[56:57]
	s_add_u32 s56, s84, 0x80080
	s_addc_u32 s57, s85, 0
	s_add_i32 s84, s87, s97
	s_mov_b32 m0, s84
	s_nop 0
	global_load_lds_dwordx4 v181, s[56:57]
	s_add_i32 m0, s84, 0x2000
	s_nop 0
	global_load_lds_dwordx4 v183, s[56:57]
	s_mov_b32 m0, s81
	s_nop 0
	global_load_lds_dwordx4 v179, s[12:13]
	s_mov_b32 m0, s70
	s_nop 0
	global_load_lds_dwordx4 v182, s[12:13]
	s_waitcnt vmcnt(8)
	s_waitcnt lgkmcnt(0)
	s_setprio 1
	s_barrier
	v_mfma_f32_16x16x32_bf16 v[60:63], v[104:107], v[160:163], v[60:63]
	v_mfma_f32_16x16x32_bf16 v[60:63], v[108:111], v[164:167], v[60:63]
	v_mfma_f32_16x16x32_bf16 v[56:59], v[132:135], v[160:163], v[56:59]
	v_mfma_f32_16x16x32_bf16 v[56:59], v[136:139], v[164:167], v[56:59]
	v_mfma_f32_16x16x32_bf16 v[48:51], v[104:107], v[168:171], v[48:51]
	v_mfma_f32_16x16x32_bf16 v[48:51], v[108:111], v[172:175], v[48:51]
	v_mfma_f32_16x16x32_bf16 v[40:43], v[132:135], v[168:171], v[40:43]
	v_mfma_f32_16x16x32_bf16 v[40:43], v[136:139], v[172:175], v[40:43]
	v_mfma_f32_16x16x32_bf16 v[32:35], v[104:107], v[186:189], v[32:35]
	v_mfma_f32_16x16x32_bf16 v[32:35], v[108:111], v[190:193], v[32:35]
	v_mfma_f32_16x16x32_bf16 v[24:27], v[132:135], v[186:189], v[24:27]
	v_mfma_f32_16x16x32_bf16 v[24:27], v[136:139], v[190:193], v[24:27]
	v_mfma_f32_16x16x32_bf16 v[16:19], v[104:107], v[200:203], v[16:19]
	v_mfma_f32_16x16x32_bf16 v[16:19], v[108:111], v[204:207], v[16:19]
	v_mfma_f32_16x16x32_bf16 v[8:11], v[132:135], v[200:203], v[8:11]
	v_mfma_f32_16x16x32_bf16 v[8:11], v[136:139], v[204:207], v[8:11]
	v_mfma_f32_16x16x32_bf16 v[52:55], v[144:147], v[160:163], v[52:55]
	v_mfma_f32_16x16x32_bf16 v[52:55], v[148:151], v[164:167], v[52:55]
	v_mfma_f32_16x16x32_bf16 v[44:47], v[152:155], v[160:163], v[44:47]
	v_mfma_f32_16x16x32_bf16 v[44:47], v[156:159], v[164:167], v[44:47]
	v_mfma_f32_16x16x32_bf16 v[36:39], v[144:147], v[168:171], v[36:39]
	v_mfma_f32_16x16x32_bf16 v[36:39], v[148:151], v[172:175], v[36:39]
	v_mfma_f32_16x16x32_bf16 v[28:31], v[152:155], v[168:171], v[28:31]
	v_mfma_f32_16x16x32_bf16 v[28:31], v[156:159], v[172:175], v[28:31]
	v_mfma_f32_16x16x32_bf16 v[20:23], v[144:147], v[186:189], v[20:23]
	v_mfma_f32_16x16x32_bf16 v[20:23], v[148:151], v[190:193], v[20:23]
	v_mfma_f32_16x16x32_bf16 v[12:15], v[152:155], v[186:189], v[12:15]
	v_mfma_f32_16x16x32_bf16 v[12:15], v[156:159], v[190:193], v[12:15]
	v_mfma_f32_16x16x32_bf16 v[4:7], v[144:147], v[200:203], v[4:7]
	v_mfma_f32_16x16x32_bf16 v[4:7], v[148:151], v[204:207], v[4:7]
	v_mfma_f32_16x16x32_bf16 v[0:3], v[152:155], v[200:203], v[0:3]
	v_mfma_f32_16x16x32_bf16 v[0:3], v[156:159], v[204:207], v[0:3]
	s_setprio 0
	s_barrier
	s_add_i32 s83, s83, 2
	s_add_u32 s39, s39, 0x100
	s_addc_u32 s69, s69, 0
	s_add_u32 s72, s72, 0x100
	s_addc_u32 s74, s74, 0
	s_add_u32 s8, s8, 0x100
	s_addc_u32 s9, s9, 0
	s_cmp_gt_u32 s83, 29
	s_cbranch_scc0 .LBB0_1050
	s_and_b64 vcc, exec, s[60:61]
	s_cbranch_vccz .LBB0_1053
	s_barrier

.LBB0_1127:
	s_cmp_eq_u32 s21, 4
	s_cselect_b32 s38, s22, s4
	s_cselect_b32 s39, s23, s5
	s_cselect_b32 s36, s24, s15
	s_cselect_b32 s37, s25, s17
	s_add_u32 s34, s38, 0x80
	s_addc_u32 s35, s39, 0
	s_add_i32 s65, 0, 0x10000
	s_add_i32 s69, 0, 0x14000
	v_add_u32_e32 v132, s65, v154
	v_add_u32_e32 v148, s69, v154
	ds_read_b128 v[112:115], v132
	ds_read_b128 v[120:123], v132 offset:1024
	ds_read_b128 v[128:131], v132 offset:2048
	ds_read_b128 v[132:135], v132 offset:3072
	ds_read_b128 v[144:147], v148
	ds_read_b128 v[156:159], v148 offset:1024
	ds_read_b128 v[160:163], v148 offset:2048
	ds_read_b128 v[164:167], v148 offset:3072
	s_add_u32 s56, s4, 0x7ff80
	s_addc_u32 s57, s5, 0
	s_add_i32 m0, s27, 0xc000
	ds_read_b128 v[168:171], v155
	ds_read_b128 v[172:175], v155 offset:1024
	ds_read_b128 v[176:179], v155 offset:2048
	ds_read_b128 v[180:183], v155 offset:3072
	ds_read_b128 v[184:187], v155 offset:4096
	ds_read_b128 v[188:191], v155 offset:5120
	ds_read_b128 v[192:195], v155 offset:6144
	ds_read_b128 v[200:203], v155 offset:7168
	s_nop 0
	global_load_lds_dwordx4 v151, s[56:57]
	s_add_i32 m0, s27, 0xe000
	s_nop 0
	global_load_lds_dwordx4 v150, s[56:57]
	s_waitcnt vmcnt(8)
	s_waitcnt lgkmcnt(0)
	s_setprio 1
	s_barrier
	v_mfma_f32_16x16x32_bf16 v[140:143], v[112:115], v[168:171], v[140:143]
	v_mfma_f32_16x16x32_bf16 v[140:143], v[120:123], v[172:175], v[140:143]
	v_mfma_f32_16x16x32_bf16 v[136:139], v[128:131], v[168:171], v[136:139]
	v_mfma_f32_16x16x32_bf16 v[136:139], v[132:135], v[172:175], v[136:139]
	v_mfma_f32_16x16x32_bf16 v[108:111], v[112:115], v[176:179], v[108:111]
	v_mfma_f32_16x16x32_bf16 v[108:111], v[120:123], v[180:183], v[108:111]
	v_mfma_f32_16x16x32_bf16 v[104:107], v[128:131], v[176:179], v[104:107]
	v_mfma_f32_16x16x32_bf16 v[104:107], v[132:135], v[180:183], v[104:107]
	v_mfma_f32_16x16x32_bf16 v[92:95], v[112:115], v[184:187], v[92:95]
	v_mfma_f32_16x16x32_bf16 v[92:95], v[120:123], v[188:191], v[92:95]
	v_mfma_f32_16x16x32_bf16 v[88:91], v[128:131], v[184:187], v[88:91]
	v_mfma_f32_16x16x32_bf16 v[88:91], v[132:135], v[188:191], v[88:91]
	v_mfma_f32_16x16x32_bf16 v[76:79], v[112:115], v[192:195], v[76:79]
	v_mfma_f32_16x16x32_bf16 v[76:79], v[120:123], v[200:203], v[76:79]
	v_mfma_f32_16x16x32_bf16 v[72:75], v[128:131], v[192:195], v[72:75]
	v_mfma_f32_16x16x32_bf16 v[72:75], v[132:135], v[200:203], v[72:75]
	v_mfma_f32_16x16x32_bf16 v[124:127], v[144:147], v[168:171], v[124:127]
	v_mfma_f32_16x16x32_bf16 v[124:127], v[156:159], v[172:175], v[124:127]
	v_mfma_f32_16x16x32_bf16 v[116:119], v[160:163], v[168:171], v[116:119]
	v_mfma_f32_16x16x32_bf16 v[116:119], v[164:167], v[172:175], v[116:119]
	v_mfma_f32_16x16x32_bf16 v[100:103], v[144:147], v[176:179], v[100:103]
	v_mfma_f32_16x16x32_bf16 v[100:103], v[156:159], v[180:183], v[100:103]
	v_mfma_f32_16x16x32_bf16 v[96:99], v[160:163], v[176:179], v[96:99]
	v_mfma_f32_16x16x32_bf16 v[96:99], v[164:167], v[180:183], v[96:99]
	v_mfma_f32_16x16x32_bf16 v[84:87], v[144:147], v[184:187], v[84:87]
	v_mfma_f32_16x16x32_bf16 v[84:87], v[156:159], v[188:191], v[84:87]
	v_mfma_f32_16x16x32_bf16 v[80:83], v[160:163], v[184:187], v[80:83]
	v_mfma_f32_16x16x32_bf16 v[80:83], v[164:167], v[188:191], v[80:83]
	v_mfma_f32_16x16x32_bf16 v[68:71], v[144:147], v[192:195], v[68:71]
	v_mfma_f32_16x16x32_bf16 v[68:71], v[156:159], v[200:203], v[68:71]
	v_mfma_f32_16x16x32_bf16 v[64:67], v[160:163], v[192:195], v[64:67]
	v_mfma_f32_16x16x32_bf16 v[64:67], v[164:167], v[200:203], v[64:67]
	s_setprio 0
	s_barrier
	s_add_i32 s65, s65, s97
	s_mov_b64 s[56:57], s[36:37]
	s_mov_b32 m0, s65
	ds_read_b128 v[168:171], v155 offset:16384
	ds_read_b128 v[172:175], v155 offset:17408
	ds_read_b128 v[176:179], v155 offset:18432
	ds_read_b128 v[180:183], v155 offset:19456
	ds_read_b128 v[184:187], v155 offset:20480
	ds_read_b128 v[188:191], v155 offset:21504
	ds_read_b128 v[192:195], v155 offset:22528
	ds_read_b128 v[200:203], v155 offset:23552
	s_nop 0
	global_load_lds_dwordx4 v152, s[56:57]
	s_add_i32 m0, s65, 0x2000
	s_nop 0
	global_load_lds_dwordx4 v153, s[56:57]
	s_add_u32 s56, s36, 0x80000
	s_addc_u32 s57, s37, 0
	s_add_i32 s65, s69, s97
	s_mov_b32 m0, s65
	s_nop 0
	global_load_lds_dwordx4 v152, s[56:57]
	s_add_i32 m0, s65, 0x2000
	s_nop 0
	global_load_lds_dwordx4 v153, s[56:57]
	s_mov_b64 s[56:57], s[38:39]
	s_mov_b32 m0, s27
	s_nop 0
	global_load_lds_dwordx4 v151, s[56:57]
	s_mov_b32 m0, s29
	s_nop 0
	global_load_lds_dwordx4 v150, s[56:57]
	s_waitcnt vmcnt(8)
	s_waitcnt lgkmcnt(0)
	s_setprio 1
	s_barrier
	v_mfma_f32_16x16x32_bf16 v[60:63], v[112:115], v[168:171], v[60:63]
	v_mfma_f32_16x16x32_bf16 v[60:63], v[120:123], v[172:175], v[60:63]
	v_mfma_f32_16x16x32_bf16 v[56:59], v[128:131], v[168:171], v[56:59]
	v_mfma_f32_16x16x32_bf16 v[56:59], v[132:135], v[172:175], v[56:59]
	v_mfma_f32_16x16x32_bf16 v[52:55], v[112:115], v[176:179], v[52:55]
	v_mfma_f32_16x16x32_bf16 v[52:55], v[120:123], v[180:183], v[52:55]
	v_mfma_f32_16x16x32_bf16 v[44:47], v[128:131], v[176:179], v[44:47]
	v_mfma_f32_16x16x32_bf16 v[44:47], v[132:135], v[180:183], v[44:47]
	v_mfma_f32_16x16x32_bf16 v[36:39], v[112:115], v[184:187], v[36:39]
	v_mfma_f32_16x16x32_bf16 v[36:39], v[120:123], v[188:191], v[36:39]
	v_mfma_f32_16x16x32_bf16 v[28:31], v[128:131], v[184:187], v[28:31]
	v_mfma_f32_16x16x32_bf16 v[28:31], v[132:135], v[188:191], v[28:31]
	v_mfma_f32_16x16x32_bf16 v[20:23], v[112:115], v[192:195], v[20:23]
	v_mfma_f32_16x16x32_bf16 v[20:23], v[120:123], v[200:203], v[20:23]
	v_mfma_f32_16x16x32_bf16 v[8:11], v[128:131], v[192:195], v[8:11]
	v_mfma_f32_16x16x32_bf16 v[8:11], v[132:135], v[200:203], v[8:11]
	v_mfma_f32_16x16x32_bf16 v[48:51], v[144:147], v[168:171], v[48:51]
	v_mfma_f32_16x16x32_bf16 v[48:51], v[156:159], v[172:175], v[48:51]
	v_mfma_f32_16x16x32_bf16 v[40:43], v[160:163], v[168:171], v[40:43]
	v_mfma_f32_16x16x32_bf16 v[40:43], v[164:167], v[172:175], v[40:43]
	v_mfma_f32_16x16x32_bf16 v[32:35], v[144:147], v[176:179], v[32:35]
	v_mfma_f32_16x16x32_bf16 v[32:35], v[156:159], v[180:183], v[32:35]
	v_mfma_f32_16x16x32_bf16 v[24:27], v[160:163], v[176:179], v[24:27]
	v_mfma_f32_16x16x32_bf16 v[24:27], v[164:167], v[180:183], v[24:27]
	v_mfma_f32_16x16x32_bf16 v[16:19], v[144:147], v[184:187], v[16:19]
	v_mfma_f32_16x16x32_bf16 v[16:19], v[156:159], v[188:191], v[16:19]
	v_mfma_f32_16x16x32_bf16 v[12:15], v[160:163], v[184:187], v[12:15]
	v_mfma_f32_16x16x32_bf16 v[12:15], v[164:167], v[188:191], v[12:15]
	v_mfma_f32_16x16x32_bf16 v[4:7], v[144:147], v[192:195], v[4:7]
	v_mfma_f32_16x16x32_bf16 v[4:7], v[156:159], v[200:203], v[4:7]
	v_mfma_f32_16x16x32_bf16 v[0:3], v[160:163], v[192:195], v[0:3]
	v_mfma_f32_16x16x32_bf16 v[0:3], v[164:167], v[200:203], v[0:3]
	s_setprio 0
	s_barrier
	s_add_i32 s56, 0, 0x18000
	s_add_i32 s57, 0, 0x1c000
	v_add_u32_e32 v132, s56, v154
	v_add_u32_e32 v148, s57, v154
	ds_read_b128 v[112:115], v132
	ds_read_b128 v[120:123], v132 offset:1024
	ds_read_b128 v[128:131], v132 offset:2048
	ds_read_b128 v[132:135], v132 offset:3072
	ds_read_b128 v[144:147], v148
	ds_read_b128 v[156:159], v148 offset:1024
	ds_read_b128 v[160:163], v148 offset:2048
	ds_read_b128 v[164:167], v148 offset:3072
	s_add_u32 s38, s38, 0x80000
	s_addc_u32 s39, s39, 0
	s_mov_b32 m0, s31
	ds_read_b128 v[168:171], v155 offset:32768
	ds_read_b128 v[172:175], v155 offset:33792
	ds_read_b128 v[176:179], v155 offset:34816
	ds_read_b128 v[180:183], v155 offset:35840
	ds_read_b128 v[184:187], v155 offset:36864
	ds_read_b128 v[188:191], v155 offset:37888
	ds_read_b128 v[192:195], v155 offset:38912
	ds_read_b128 v[200:203], v155 offset:39936
	s_nop 0
	global_load_lds_dwordx4 v151, s[38:39]
	s_mov_b32 m0, s46
	s_nop 0
	global_load_lds_dwordx4 v150, s[38:39]
	s_waitcnt vmcnt(8)
	s_waitcnt lgkmcnt(0)
	s_setprio 1
	s_barrier
	v_mfma_f32_16x16x32_bf16 v[140:143], v[112:115], v[168:171], v[140:143]
	v_mfma_f32_16x16x32_bf16 v[140:143], v[120:123], v[172:175], v[140:143]
	v_mfma_f32_16x16x32_bf16 v[136:139], v[128:131], v[168:171], v[136:139]
	v_mfma_f32_16x16x32_bf16 v[136:139], v[132:135], v[172:175], v[136:139]
	v_mfma_f32_16x16x32_bf16 v[108:111], v[112:115], v[176:179], v[108:111]
	v_mfma_f32_16x16x32_bf16 v[108:111], v[120:123], v[180:183], v[108:111]
	v_mfma_f32_16x16x32_bf16 v[104:107], v[128:131], v[176:179], v[104:107]
	v_mfma_f32_16x16x32_bf16 v[104:107], v[132:135], v[180:183], v[104:107]
	v_mfma_f32_16x16x32_bf16 v[92:95], v[112:115], v[184:187], v[92:95]
	v_mfma_f32_16x16x32_bf16 v[92:95], v[120:123], v[188:191], v[92:95]
	v_mfma_f32_16x16x32_bf16 v[88:91], v[128:131], v[184:187], v[88:91]
	v_mfma_f32_16x16x32_bf16 v[88:91], v[132:135], v[188:191], v[88:91]
	v_mfma_f32_16x16x32_bf16 v[76:79], v[112:115], v[192:195], v[76:79]
	v_mfma_f32_16x16x32_bf16 v[76:79], v[120:123], v[200:203], v[76:79]
	v_mfma_f32_16x16x32_bf16 v[72:75], v[128:131], v[192:195], v[72:75]
	v_mfma_f32_16x16x32_bf16 v[72:75], v[132:135], v[200:203], v[72:75]
	v_mfma_f32_16x16x32_bf16 v[124:127], v[144:147], v[168:171], v[124:127]
	v_mfma_f32_16x16x32_bf16 v[124:127], v[156:159], v[172:175], v[124:127]
	v_mfma_f32_16x16x32_bf16 v[116:119], v[160:163], v[168:171], v[116:119]
	v_mfma_f32_16x16x32_bf16 v[116:119], v[164:167], v[172:175], v[116:119]
	v_mfma_f32_16x16x32_bf16 v[100:103], v[144:147], v[176:179], v[100:103]
	v_mfma_f32_16x16x32_bf16 v[100:103], v[156:159], v[180:183], v[100:103]
	v_mfma_f32_16x16x32_bf16 v[96:99], v[160:163], v[176:179], v[96:99]
	v_mfma_f32_16x16x32_bf16 v[96:99], v[164:167], v[180:183], v[96:99]
	v_mfma_f32_16x16x32_bf16 v[84:87], v[144:147], v[184:187], v[84:87]
	v_mfma_f32_16x16x32_bf16 v[84:87], v[156:159], v[188:191], v[84:87]
	v_mfma_f32_16x16x32_bf16 v[80:83], v[160:163], v[184:187], v[80:83]
	v_mfma_f32_16x16x32_bf16 v[80:83], v[164:167], v[188:191], v[80:83]
	v_mfma_f32_16x16x32_bf16 v[68:71], v[144:147], v[192:195], v[68:71]
	v_mfma_f32_16x16x32_bf16 v[68:71], v[156:159], v[200:203], v[68:71]
	v_mfma_f32_16x16x32_bf16 v[64:67], v[160:163], v[192:195], v[64:67]
	v_mfma_f32_16x16x32_bf16 v[64:67], v[164:167], v[200:203], v[64:67]
	s_setprio 0
	s_barrier
	s_add_u32 s38, s36, 0x80
	s_addc_u32 s39, s37, 0
	s_add_i32 s56, s56, s97
	s_mov_b32 m0, s56
	ds_read_b128 v[168:171], v155 offset:49152
	ds_read_b128 v[172:175], v155 offset:50176
	ds_read_b128 v[176:179], v155 offset:51200
	ds_read_b128 v[180:183], v155 offset:52224
	ds_read_b128 v[184:187], v155 offset:53248
	ds_read_b128 v[188:191], v155 offset:54272
	ds_read_b128 v[192:195], v155 offset:55296
	ds_read_b128 v[200:203], v155 offset:56320
	s_nop 0
	global_load_lds_dwordx4 v152, s[38:39]
	s_add_i32 m0, s56, 0x2000
	s_add_u32 s36, s36, 0x80080
	s_addc_u32 s37, s37, 0
	global_load_lds_dwordx4 v153, s[38:39]
	s_add_i32 s38, s57, s97
	s_mov_b32 m0, s38
	s_nop 0
	global_load_lds_dwordx4 v152, s[36:37]
	s_add_i32 m0, s38, 0x2000
	s_nop 0
	global_load_lds_dwordx4 v153, s[36:37]
	s_mov_b32 m0, s47
	s_nop 0
	global_load_lds_dwordx4 v151, s[34:35]
	s_mov_b32 m0, s48
	s_nop 0
	global_load_lds_dwordx4 v150, s[34:35]
	s_waitcnt vmcnt(8)
	s_waitcnt lgkmcnt(0)
	s_setprio 1
	s_barrier
	v_mfma_f32_16x16x32_bf16 v[60:63], v[112:115], v[168:171], v[60:63]
	v_mfma_f32_16x16x32_bf16 v[60:63], v[120:123], v[172:175], v[60:63]
	v_mfma_f32_16x16x32_bf16 v[56:59], v[128:131], v[168:171], v[56:59]
	v_mfma_f32_16x16x32_bf16 v[56:59], v[132:135], v[172:175], v[56:59]
	v_mfma_f32_16x16x32_bf16 v[52:55], v[112:115], v[176:179], v[52:55]
	v_mfma_f32_16x16x32_bf16 v[52:55], v[120:123], v[180:183], v[52:55]
	v_mfma_f32_16x16x32_bf16 v[44:47], v[128:131], v[176:179], v[44:47]
	v_mfma_f32_16x16x32_bf16 v[44:47], v[132:135], v[180:183], v[44:47]
	v_mfma_f32_16x16x32_bf16 v[36:39], v[112:115], v[184:187], v[36:39]
	v_mfma_f32_16x16x32_bf16 v[36:39], v[120:123], v[188:191], v[36:39]
	v_mfma_f32_16x16x32_bf16 v[28:31], v[128:131], v[184:187], v[28:31]
	v_mfma_f32_16x16x32_bf16 v[28:31], v[132:135], v[188:191], v[28:31]
	v_mfma_f32_16x16x32_bf16 v[20:23], v[112:115], v[192:195], v[20:23]
	v_mfma_f32_16x16x32_bf16 v[20:23], v[120:123], v[200:203], v[20:23]
	v_mfma_f32_16x16x32_bf16 v[8:11], v[128:131], v[192:195], v[8:11]
	v_mfma_f32_16x16x32_bf16 v[8:11], v[132:135], v[200:203], v[8:11]
	v_mfma_f32_16x16x32_bf16 v[48:51], v[144:147], v[168:171], v[48:51]
	v_mfma_f32_16x16x32_bf16 v[48:51], v[156:159], v[172:175], v[48:51]
	v_mfma_f32_16x16x32_bf16 v[40:43], v[160:163], v[168:171], v[40:43]
	v_mfma_f32_16x16x32_bf16 v[40:43], v[164:167], v[172:175], v[40:43]
	v_mfma_f32_16x16x32_bf16 v[32:35], v[144:147], v[176:179], v[32:35]
	v_mfma_f32_16x16x32_bf16 v[32:35], v[156:159], v[180:183], v[32:35]
	v_mfma_f32_16x16x32_bf16 v[24:27], v[160:163], v[176:179], v[24:27]
	v_mfma_f32_16x16x32_bf16 v[24:27], v[164:167], v[180:183], v[24:27]
	v_mfma_f32_16x16x32_bf16 v[16:19], v[144:147], v[184:187], v[16:19]
	v_mfma_f32_16x16x32_bf16 v[16:19], v[156:159], v[188:191], v[16:19]
	v_mfma_f32_16x16x32_bf16 v[12:15], v[160:163], v[184:187], v[12:15]
	v_mfma_f32_16x16x32_bf16 v[12:15], v[164:167], v[188:191], v[12:15]
	v_mfma_f32_16x16x32_bf16 v[4:7], v[144:147], v[192:195], v[4:7]
	v_mfma_f32_16x16x32_bf16 v[4:7], v[156:159], v[200:203], v[4:7]
	v_mfma_f32_16x16x32_bf16 v[0:3], v[160:163], v[192:195], v[0:3]
	v_mfma_f32_16x16x32_bf16 v[0:3], v[164:167], v[200:203], v[0:3]
	s_setprio 0
	s_barrier
	s_add_i32 s21, s21, 2
	s_add_u32 s4, s4, 0x100
	s_addc_u32 s5, s5, 0
	s_add_u32 s15, s15, 0x100
	s_addc_u32 s17, s17, 0
	s_cmp_gt_u32 s21, 5
	s_cbranch_scc0 .LBB0_1127
	s_and_b64 vcc, exec, s[60:61]
	s_cbranch_vccz .LBB0_1130
	s_barrier

.LBB0_1253:
	s_add_u32 s34, s10, 0x100
	s_addc_u32 s35, s11, 0
	s_cmp_eq_u32 vcc_hi, 28
	s_cselect_b32 s40, s5, s34
	s_cselect_b32 s41, s4, s35
	s_cselect_b32 s38, s25, s27
	s_cselect_b32 s39, s9, vcc_lo
	s_add_u32 s36, s40, 0x80
	s_addc_u32 s37, s41, 0
	s_add_i32 s75, 0, 0x10000
	s_add_i32 s46, 0, 0x14000
	v_add_u32_e32 v140, s75, v196
	v_add_u32_e32 v156, s46, v196
	ds_read_b128 v[128:131], v140
	ds_read_b128 v[132:135], v140 offset:1024
	ds_read_b128 v[136:139], v140 offset:2048
	ds_read_b128 v[140:143], v140 offset:3072
	ds_read_b128 v[144:147], v156
	ds_read_b128 v[148:151], v156 offset:1024
	ds_read_b128 v[152:155], v156 offset:2048
	ds_read_b128 v[156:159], v156 offset:3072
	s_add_u32 s10, s10, 0x80080
	s_addc_u32 s11, s11, 0
	s_add_i32 m0, s15, 0xc000
	ds_read_b128 v[160:163], v200
	ds_read_b128 v[164:167], v200 offset:1024
	ds_read_b128 v[168:171], v200 offset:2048
	ds_read_b128 v[172:175], v200 offset:3072
	ds_read_b128 v[176:179], v200 offset:4096
	ds_read_b128 v[180:183], v200 offset:5120
	ds_read_b128 v[184:187], v200 offset:6144
	ds_read_b128 v[188:191], v200 offset:7168
	s_nop 0
	global_load_lds_dwordx4 v192, s[10:11]
	s_add_i32 m0, s15, 0xe000
	s_nop 0
	global_load_lds_dwordx4 v194, s[10:11]
	s_waitcnt vmcnt(8)
	s_waitcnt lgkmcnt(0)
	s_setprio 1
	s_barrier
	v_mfma_f32_16x16x32_bf16 v[124:127], v[128:131], v[160:163], v[124:127]
	v_mfma_f32_16x16x32_bf16 v[124:127], v[132:135], v[164:167], v[124:127]
	v_mfma_f32_16x16x32_bf16 v[60:63], v[136:139], v[160:163], v[60:63]
	v_mfma_f32_16x16x32_bf16 v[60:63], v[140:143], v[164:167], v[60:63]
	v_mfma_f32_16x16x32_bf16 v[120:123], v[128:131], v[168:171], v[120:123]
	v_mfma_f32_16x16x32_bf16 v[120:123], v[132:135], v[172:175], v[120:123]
	v_mfma_f32_16x16x32_bf16 v[56:59], v[136:139], v[168:171], v[56:59]
	v_mfma_f32_16x16x32_bf16 v[56:59], v[140:143], v[172:175], v[56:59]
	v_mfma_f32_16x16x32_bf16 v[116:119], v[128:131], v[176:179], v[116:119]
	v_mfma_f32_16x16x32_bf16 v[116:119], v[132:135], v[180:183], v[116:119]
	v_mfma_f32_16x16x32_bf16 v[52:55], v[136:139], v[176:179], v[52:55]
	v_mfma_f32_16x16x32_bf16 v[52:55], v[140:143], v[180:183], v[52:55]
	v_mfma_f32_16x16x32_bf16 v[112:115], v[128:131], v[184:187], v[112:115]
	v_mfma_f32_16x16x32_bf16 v[112:115], v[132:135], v[188:191], v[112:115]
	v_mfma_f32_16x16x32_bf16 v[48:51], v[136:139], v[184:187], v[48:51]
	v_mfma_f32_16x16x32_bf16 v[48:51], v[140:143], v[188:191], v[48:51]
	v_mfma_f32_16x16x32_bf16 v[108:111], v[144:147], v[160:163], v[108:111]
	v_mfma_f32_16x16x32_bf16 v[108:111], v[148:151], v[164:167], v[108:111]
	v_mfma_f32_16x16x32_bf16 v[44:47], v[152:155], v[160:163], v[44:47]
	v_mfma_f32_16x16x32_bf16 v[44:47], v[156:159], v[164:167], v[44:47]
	v_mfma_f32_16x16x32_bf16 v[104:107], v[144:147], v[168:171], v[104:107]
	v_mfma_f32_16x16x32_bf16 v[104:107], v[148:151], v[172:175], v[104:107]
	v_mfma_f32_16x16x32_bf16 v[40:43], v[152:155], v[168:171], v[40:43]
	v_mfma_f32_16x16x32_bf16 v[40:43], v[156:159], v[172:175], v[40:43]
	v_mfma_f32_16x16x32_bf16 v[100:103], v[144:147], v[176:179], v[100:103]
	v_mfma_f32_16x16x32_bf16 v[100:103], v[148:151], v[180:183], v[100:103]
	v_mfma_f32_16x16x32_bf16 v[36:39], v[152:155], v[176:179], v[36:39]
	v_mfma_f32_16x16x32_bf16 v[36:39], v[156:159], v[180:183], v[36:39]
	v_mfma_f32_16x16x32_bf16 v[96:99], v[144:147], v[184:187], v[96:99]
	v_mfma_f32_16x16x32_bf16 v[96:99], v[148:151], v[188:191], v[96:99]
	v_mfma_f32_16x16x32_bf16 v[32:35], v[152:155], v[184:187], v[32:35]
	v_mfma_f32_16x16x32_bf16 v[32:35], v[156:159], v[188:191], v[32:35]
	s_setprio 0
	s_barrier
	s_add_i32 s47, s75, s97
	s_mov_b64 s[10:11], s[38:39]
	s_mov_b32 m0, s47
	ds_read_b128 v[160:163], v200 offset:16384
	ds_read_b128 v[164:167], v200 offset:17408
	ds_read_b128 v[168:171], v200 offset:18432
	ds_read_b128 v[172:175], v200 offset:19456
	ds_read_b128 v[176:179], v200 offset:20480
	ds_read_b128 v[180:183], v200 offset:21504
	ds_read_b128 v[184:187], v200 offset:22528
	ds_read_b128 v[188:191], v200 offset:23552
	s_nop 0
	global_load_lds_dwordx4 v193, s[10:11]
	s_add_i32 m0, s47, 0x2000
	s_nop 0
	global_load_lds_dwordx4 v195, s[10:11]
	s_add_u32 s10, s38, 0x80000
	s_addc_u32 s11, s39, 0
	s_add_i32 s46, s46, s97
	s_mov_b32 m0, s46
	s_nop 0
	global_load_lds_dwordx4 v193, s[10:11]
	s_add_i32 m0, s46, 0x2000
	s_nop 0
	global_load_lds_dwordx4 v195, s[10:11]
	s_mov_b64 s[10:11], s[40:41]
	s_mov_b32 m0, s15
	s_nop 0
	global_load_lds_dwordx4 v192, s[10:11]
	s_mov_b32 m0, s69
	s_nop 0
	global_load_lds_dwordx4 v194, s[10:11]
	s_waitcnt vmcnt(8)
	s_waitcnt lgkmcnt(0)
	s_setprio 1
	s_barrier
	v_mfma_f32_16x16x32_bf16 v[92:95], v[128:131], v[160:163], v[92:95]
	v_mfma_f32_16x16x32_bf16 v[92:95], v[132:135], v[164:167], v[92:95]
	v_mfma_f32_16x16x32_bf16 v[28:31], v[136:139], v[160:163], v[28:31]
	v_mfma_f32_16x16x32_bf16 v[28:31], v[140:143], v[164:167], v[28:31]
	v_mfma_f32_16x16x32_bf16 v[88:91], v[128:131], v[168:171], v[88:91]
	v_mfma_f32_16x16x32_bf16 v[88:91], v[132:135], v[172:175], v[88:91]
	v_mfma_f32_16x16x32_bf16 v[16:19], v[136:139], v[168:171], v[16:19]
	v_mfma_f32_16x16x32_bf16 v[16:19], v[140:143], v[172:175], v[16:19]
	v_mfma_f32_16x16x32_bf16 v[84:87], v[128:131], v[176:179], v[84:87]
	v_mfma_f32_16x16x32_bf16 v[84:87], v[132:135], v[180:183], v[84:87]
	v_mfma_f32_16x16x32_bf16 v[20:23], v[136:139], v[176:179], v[20:23]
	v_mfma_f32_16x16x32_bf16 v[20:23], v[140:143], v[180:183], v[20:23]
	v_mfma_f32_16x16x32_bf16 v[80:83], v[128:131], v[184:187], v[80:83]
	v_mfma_f32_16x16x32_bf16 v[80:83], v[132:135], v[188:191], v[80:83]
	v_mfma_f32_16x16x32_bf16 v[8:11], v[136:139], v[184:187], v[8:11]
	v_mfma_f32_16x16x32_bf16 v[8:11], v[140:143], v[188:191], v[8:11]
	v_mfma_f32_16x16x32_bf16 v[76:79], v[144:147], v[160:163], v[76:79]
	v_mfma_f32_16x16x32_bf16 v[76:79], v[148:151], v[164:167], v[76:79]
	v_mfma_f32_16x16x32_bf16 v[24:27], v[152:155], v[160:163], v[24:27]
	v_mfma_f32_16x16x32_bf16 v[24:27], v[156:159], v[164:167], v[24:27]
	v_mfma_f32_16x16x32_bf16 v[72:75], v[144:147], v[168:171], v[72:75]
	v_mfma_f32_16x16x32_bf16 v[72:75], v[148:151], v[172:175], v[72:75]
	v_mfma_f32_16x16x32_bf16 v[12:15], v[152:155], v[168:171], v[12:15]
	v_mfma_f32_16x16x32_bf16 v[12:15], v[156:159], v[172:175], v[12:15]
	v_mfma_f32_16x16x32_bf16 v[68:71], v[144:147], v[176:179], v[68:71]
	v_mfma_f32_16x16x32_bf16 v[68:71], v[148:151], v[180:183], v[68:71]
	v_mfma_f32_16x16x32_bf16 v[4:7], v[152:155], v[176:179], v[4:7]
	v_mfma_f32_16x16x32_bf16 v[4:7], v[156:159], v[180:183], v[4:7]
	v_mfma_f32_16x16x32_bf16 v[64:67], v[144:147], v[184:187], v[64:67]
	v_mfma_f32_16x16x32_bf16 v[64:67], v[148:151], v[188:191], v[64:67]
	v_mfma_f32_16x16x32_bf16 v[0:3], v[152:155], v[184:187], v[0:3]
	v_mfma_f32_16x16x32_bf16 v[0:3], v[156:159], v[188:191], v[0:3]
	s_setprio 0
	s_barrier
	s_add_i32 s46, 0, 0x18000
	s_add_i32 s47, 0, 0x1c000
	v_add_u32_e32 v140, s46, v196
	v_add_u32_e32 v156, s47, v196
	ds_read_b128 v[128:131], v140
	ds_read_b128 v[132:135], v140 offset:1024
	ds_read_b128 v[136:139], v140 offset:2048
	ds_read_b128 v[140:143], v140 offset:3072
	ds_read_b128 v[144:147], v156
	ds_read_b128 v[148:151], v156 offset:1024
	ds_read_b128 v[152:155], v156 offset:2048
	ds_read_b128 v[156:159], v156 offset:3072
	s_add_u32 s10, s40, 0x80000
	s_addc_u32 s11, s41, 0
	s_mov_b32 m0, s78
	ds_read_b128 v[160:163], v200 offset:32768
	ds_read_b128 v[164:167], v200 offset:33792
	ds_read_b128 v[168:171], v200 offset:34816
	ds_read_b128 v[172:175], v200 offset:35840
	ds_read_b128 v[176:179], v200 offset:36864
	ds_read_b128 v[180:183], v200 offset:37888
	ds_read_b128 v[184:187], v200 offset:38912
	ds_read_b128 v[188:191], v200 offset:39936
	s_nop 0
	global_load_lds_dwordx4 v192, s[10:11]
	s_mov_b32 m0, s80
	s_nop 0
	global_load_lds_dwordx4 v194, s[10:11]
	s_waitcnt vmcnt(8)
	s_waitcnt lgkmcnt(0)
	s_setprio 1
	s_barrier
	v_mfma_f32_16x16x32_bf16 v[124:127], v[128:131], v[160:163], v[124:127]
	v_mfma_f32_16x16x32_bf16 v[124:127], v[132:135], v[164:167], v[124:127]
	v_mfma_f32_16x16x32_bf16 v[60:63], v[136:139], v[160:163], v[60:63]
	v_mfma_f32_16x16x32_bf16 v[60:63], v[140:143], v[164:167], v[60:63]
	v_mfma_f32_16x16x32_bf16 v[120:123], v[128:131], v[168:171], v[120:123]
	v_mfma_f32_16x16x32_bf16 v[120:123], v[132:135], v[172:175], v[120:123]
	v_mfma_f32_16x16x32_bf16 v[56:59], v[136:139], v[168:171], v[56:59]
	v_mfma_f32_16x16x32_bf16 v[56:59], v[140:143], v[172:175], v[56:59]
	v_mfma_f32_16x16x32_bf16 v[116:119], v[128:131], v[176:179], v[116:119]
	v_mfma_f32_16x16x32_bf16 v[116:119], v[132:135], v[180:183], v[116:119]
	v_mfma_f32_16x16x32_bf16 v[52:55], v[136:139], v[176:179], v[52:55]
	v_mfma_f32_16x16x32_bf16 v[52:55], v[140:143], v[180:183], v[52:55]
	v_mfma_f32_16x16x32_bf16 v[112:115], v[128:131], v[184:187], v[112:115]
	v_mfma_f32_16x16x32_bf16 v[112:115], v[132:135], v[188:191], v[112:115]
	v_mfma_f32_16x16x32_bf16 v[48:51], v[136:139], v[184:187], v[48:51]
	v_mfma_f32_16x16x32_bf16 v[48:51], v[140:143], v[188:191], v[48:51]
	v_mfma_f32_16x16x32_bf16 v[108:111], v[144:147], v[160:163], v[108:111]
	v_mfma_f32_16x16x32_bf16 v[108:111], v[148:151], v[164:167], v[108:111]
	v_mfma_f32_16x16x32_bf16 v[44:47], v[152:155], v[160:163], v[44:47]
	v_mfma_f32_16x16x32_bf16 v[44:47], v[156:159], v[164:167], v[44:47]
	v_mfma_f32_16x16x32_bf16 v[104:107], v[144:147], v[168:171], v[104:107]
	v_mfma_f32_16x16x32_bf16 v[104:107], v[148:151], v[172:175], v[104:107]
	v_mfma_f32_16x16x32_bf16 v[40:43], v[152:155], v[168:171], v[40:43]
	v_mfma_f32_16x16x32_bf16 v[40:43], v[156:159], v[172:175], v[40:43]
	v_mfma_f32_16x16x32_bf16 v[100:103], v[144:147], v[176:179], v[100:103]
	v_mfma_f32_16x16x32_bf16 v[100:103], v[148:151], v[180:183], v[100:103]
	v_mfma_f32_16x16x32_bf16 v[36:39], v[152:155], v[176:179], v[36:39]
	v_mfma_f32_16x16x32_bf16 v[36:39], v[156:159], v[180:183], v[36:39]
	v_mfma_f32_16x16x32_bf16 v[96:99], v[144:147], v[184:187], v[96:99]
	v_mfma_f32_16x16x32_bf16 v[96:99], v[148:151], v[188:191], v[96:99]
	v_mfma_f32_16x16x32_bf16 v[32:35], v[152:155], v[184:187], v[32:35]
	v_mfma_f32_16x16x32_bf16 v[32:35], v[156:159], v[188:191], v[32:35]
	s_setprio 0
	s_barrier
	s_add_u32 s10, s38, 0x80
	s_addc_u32 s11, s39, 0
	s_add_i32 s40, s46, s97
	s_mov_b32 m0, s40
	ds_read_b128 v[160:163], v200 offset:49152
	ds_read_b128 v[164:167], v200 offset:50176
	ds_read_b128 v[168:171], v200 offset:51200
	ds_read_b128 v[172:175], v200 offset:52224
	ds_read_b128 v[176:179], v200 offset:53248
	ds_read_b128 v[180:183], v200 offset:54272
	ds_read_b128 v[184:187], v200 offset:55296
	ds_read_b128 v[188:191], v200 offset:56320
	s_nop 0
	global_load_lds_dwordx4 v193, s[10:11]
	s_add_i32 m0, s40, 0x2000
	s_nop 0
	global_load_lds_dwordx4 v195, s[10:11]
	s_add_u32 s10, s38, 0x80080
	s_addc_u32 s11, s39, 0
	s_add_i32 s38, s47, s97
	s_mov_b32 m0, s38
	s_nop 0
	global_load_lds_dwordx4 v193, s[10:11]
	s_add_i32 m0, s38, 0x2000
	s_nop 0
	global_load_lds_dwordx4 v195, s[10:11]
	s_mov_b32 m0, s85
	s_nop 0
	global_load_lds_dwordx4 v192, s[36:37]
	s_mov_b32 m0, s86
	s_nop 0
	global_load_lds_dwordx4 v194, s[36:37]
	s_waitcnt vmcnt(8)
	s_waitcnt lgkmcnt(0)
	s_setprio 1
	s_barrier
	v_mfma_f32_16x16x32_bf16 v[92:95], v[128:131], v[160:163], v[92:95]
	v_mfma_f32_16x16x32_bf16 v[92:95], v[132:135], v[164:167], v[92:95]
	v_mfma_f32_16x16x32_bf16 v[28:31], v[136:139], v[160:163], v[28:31]
	v_mfma_f32_16x16x32_bf16 v[28:31], v[140:143], v[164:167], v[28:31]
	v_mfma_f32_16x16x32_bf16 v[88:91], v[128:131], v[168:171], v[88:91]
	v_mfma_f32_16x16x32_bf16 v[88:91], v[132:135], v[172:175], v[88:91]
	v_mfma_f32_16x16x32_bf16 v[16:19], v[136:139], v[168:171], v[16:19]
	v_mfma_f32_16x16x32_bf16 v[16:19], v[140:143], v[172:175], v[16:19]
	v_mfma_f32_16x16x32_bf16 v[84:87], v[128:131], v[176:179], v[84:87]
	v_mfma_f32_16x16x32_bf16 v[84:87], v[132:135], v[180:183], v[84:87]
	v_mfma_f32_16x16x32_bf16 v[20:23], v[136:139], v[176:179], v[20:23]
	v_mfma_f32_16x16x32_bf16 v[20:23], v[140:143], v[180:183], v[20:23]
	v_mfma_f32_16x16x32_bf16 v[80:83], v[128:131], v[184:187], v[80:83]
	v_mfma_f32_16x16x32_bf16 v[80:83], v[132:135], v[188:191], v[80:83]
	v_mfma_f32_16x16x32_bf16 v[8:11], v[136:139], v[184:187], v[8:11]
	v_mfma_f32_16x16x32_bf16 v[8:11], v[140:143], v[188:191], v[8:11]
	v_mfma_f32_16x16x32_bf16 v[76:79], v[144:147], v[160:163], v[76:79]
	v_mfma_f32_16x16x32_bf16 v[76:79], v[148:151], v[164:167], v[76:79]
	v_mfma_f32_16x16x32_bf16 v[24:27], v[152:155], v[160:163], v[24:27]
	v_mfma_f32_16x16x32_bf16 v[24:27], v[156:159], v[164:167], v[24:27]
	v_mfma_f32_16x16x32_bf16 v[72:75], v[144:147], v[168:171], v[72:75]
	v_mfma_f32_16x16x32_bf16 v[72:75], v[148:151], v[172:175], v[72:75]
	v_mfma_f32_16x16x32_bf16 v[12:15], v[152:155], v[168:171], v[12:15]
	v_mfma_f32_16x16x32_bf16 v[12:15], v[156:159], v[172:175], v[12:15]
	v_mfma_f32_16x16x32_bf16 v[68:71], v[144:147], v[176:179], v[68:71]
	v_mfma_f32_16x16x32_bf16 v[68:71], v[148:151], v[180:183], v[68:71]
	v_mfma_f32_16x16x32_bf16 v[4:7], v[152:155], v[176:179], v[4:7]
	v_mfma_f32_16x16x32_bf16 v[4:7], v[156:159], v[180:183], v[4:7]
	v_mfma_f32_16x16x32_bf16 v[64:67], v[144:147], v[184:187], v[64:67]
	v_mfma_f32_16x16x32_bf16 v[64:67], v[148:151], v[188:191], v[64:67]
	v_mfma_f32_16x16x32_bf16 v[0:3], v[152:155], v[184:187], v[0:3]
	v_mfma_f32_16x16x32_bf16 v[0:3], v[156:159], v[188:191], v[0:3]
	s_setprio 0
	s_barrier
	s_add_i32 vcc_hi, vcc_hi, 2
	s_add_u32 s27, s27, 0x100
	s_addc_u32 vcc_lo, vcc_lo, 0
	s_cmp_gt_u32 vcc_hi, 29
	s_mov_b64 s[10:11], s[34:35]
	s_cbranch_scc0 .LBB0_1253
	s_and_b64 vcc, exec, s[60:61]
	s_cbranch_vccz .LBB0_1256
	s_barrier

.LBB0_1290:
	s_cmp_eq_u32 s21, 12
	s_cselect_b32 s40, s24, s4
	s_cselect_b32 s41, s25, s5
	s_cselect_b32 s38, s30, s15
	s_cselect_b32 s39, s31, s17
	s_add_u32 s36, s40, 0x80
	s_addc_u32 s37, s41, 0
	s_add_i32 s23, 0, 0x10000
	v_add_u32_e32 v128, s23, v134
	s_add_i32 s46, 0, 0x14000
	ds_read_b128 v[136:139], v128
	ds_read_b128 v[140:143], v128 offset:1024
	ds_read_b128 v[144:147], v128 offset:2048
	ds_read_b128 v[148:151], v128 offset:3072
	v_add_u32_e32 v128, s46, v134
	ds_read_b128 v[152:155], v128
	ds_read_b128 v[156:159], v128 offset:1024
	ds_read_b128 v[160:163], v128 offset:2048
	ds_read_b128 v[164:167], v128 offset:3072
	s_mov_b64 s[74:75], s[34:35]
	s_add_i32 m0, s27, 0xc000
	ds_read_b128 v[168:171], v135
	ds_read_b128 v[172:175], v135 offset:1024
	ds_read_b128 v[176:179], v135 offset:2048
	ds_read_b128 v[180:183], v135 offset:3072
	ds_read_b128 v[184:187], v135 offset:4096
	ds_read_b128 v[188:191], v135 offset:5120
	ds_read_b128 v[192:195], v135 offset:6144
	ds_read_b128 v[200:203], v135 offset:7168
	s_nop 0
	global_load_lds_dwordx4 v133, s[74:75]
	s_add_i32 m0, s27, 0xe000
	s_nop 0
	global_load_lds_dwordx4 v131, s[74:75]
	s_waitcnt vmcnt(8)
	s_waitcnt lgkmcnt(0)
	s_setprio 1
	s_barrier
	v_mfma_f32_16x16x32_bf16 v[124:127], v[136:139], v[168:171], v[124:127]
	v_mfma_f32_16x16x32_bf16 v[124:127], v[140:143], v[172:175], v[124:127]
	v_mfma_f32_16x16x32_bf16 v[120:123], v[144:147], v[168:171], v[120:123]
	v_mfma_f32_16x16x32_bf16 v[120:123], v[148:151], v[172:175], v[120:123]
	v_mfma_f32_16x16x32_bf16 v[116:119], v[136:139], v[176:179], v[116:119]
	v_mfma_f32_16x16x32_bf16 v[116:119], v[140:143], v[180:183], v[116:119]
	v_mfma_f32_16x16x32_bf16 v[108:111], v[144:147], v[176:179], v[108:111]
	v_mfma_f32_16x16x32_bf16 v[108:111], v[148:151], v[180:183], v[108:111]
	v_mfma_f32_16x16x32_bf16 v[100:103], v[136:139], v[184:187], v[100:103]
	v_mfma_f32_16x16x32_bf16 v[100:103], v[140:143], v[188:191], v[100:103]
	v_mfma_f32_16x16x32_bf16 v[92:95], v[144:147], v[184:187], v[92:95]
	v_mfma_f32_16x16x32_bf16 v[92:95], v[148:151], v[188:191], v[92:95]
	v_mfma_f32_16x16x32_bf16 v[84:87], v[136:139], v[192:195], v[84:87]
	v_mfma_f32_16x16x32_bf16 v[84:87], v[140:143], v[200:203], v[84:87]
	v_mfma_f32_16x16x32_bf16 v[76:79], v[144:147], v[192:195], v[76:79]
	v_mfma_f32_16x16x32_bf16 v[76:79], v[148:151], v[200:203], v[76:79]
	v_mfma_f32_16x16x32_bf16 v[112:115], v[152:155], v[168:171], v[112:115]
	v_mfma_f32_16x16x32_bf16 v[112:115], v[156:159], v[172:175], v[112:115]
	v_mfma_f32_16x16x32_bf16 v[104:107], v[160:163], v[168:171], v[104:107]
	v_mfma_f32_16x16x32_bf16 v[104:107], v[164:167], v[172:175], v[104:107]
	v_mfma_f32_16x16x32_bf16 v[96:99], v[152:155], v[176:179], v[96:99]
	v_mfma_f32_16x16x32_bf16 v[96:99], v[156:159], v[180:183], v[96:99]
	v_mfma_f32_16x16x32_bf16 v[88:91], v[160:163], v[176:179], v[88:91]
	v_mfma_f32_16x16x32_bf16 v[88:91], v[164:167], v[180:183], v[88:91]
	v_mfma_f32_16x16x32_bf16 v[80:83], v[152:155], v[184:187], v[80:83]
	v_mfma_f32_16x16x32_bf16 v[80:83], v[156:159], v[188:191], v[80:83]
	v_mfma_f32_16x16x32_bf16 v[72:75], v[160:163], v[184:187], v[72:75]
	v_mfma_f32_16x16x32_bf16 v[72:75], v[164:167], v[188:191], v[72:75]
	v_mfma_f32_16x16x32_bf16 v[68:71], v[152:155], v[192:195], v[68:71]
	v_mfma_f32_16x16x32_bf16 v[68:71], v[156:159], v[200:203], v[68:71]
	v_mfma_f32_16x16x32_bf16 v[64:67], v[160:163], v[192:195], v[64:67]
	v_mfma_f32_16x16x32_bf16 v[64:67], v[164:167], v[200:203], v[64:67]
	s_setprio 0
	s_barrier
	s_add_i32 s23, s23, s97
	s_mov_b64 s[74:75], s[38:39]
	s_mov_b32 m0, s23
	ds_read_b128 v[168:171], v135 offset:16384
	ds_read_b128 v[172:175], v135 offset:17408
	ds_read_b128 v[176:179], v135 offset:18432
	ds_read_b128 v[180:183], v135 offset:19456
	ds_read_b128 v[184:187], v135 offset:20480
	ds_read_b128 v[188:191], v135 offset:21504
	ds_read_b128 v[192:195], v135 offset:22528
	ds_read_b128 v[200:203], v135 offset:23552
	s_nop 0
	global_load_lds_dwordx4 v132, s[74:75]
	s_add_i32 m0, s23, 0x2000
	s_nop 0
	global_load_lds_dwordx4 v130, s[74:75]
	s_add_u32 s74, s38, 0x80000
	s_addc_u32 s75, s39, 0
	s_add_i32 s23, s46, s97
	s_mov_b32 m0, s23
	s_nop 0
	global_load_lds_dwordx4 v132, s[74:75]
	s_add_i32 m0, s23, 0x2000
	s_nop 0
	global_load_lds_dwordx4 v130, s[74:75]
	s_mov_b64 s[74:75], s[40:41]
	s_mov_b32 m0, s27
	s_nop 0
	global_load_lds_dwordx4 v133, s[74:75]
	s_mov_b32 m0, s29
	s_nop 0
	global_load_lds_dwordx4 v131, s[74:75]
	s_waitcnt vmcnt(8)
	s_waitcnt lgkmcnt(0)
	s_setprio 1
	s_barrier
	v_mfma_f32_16x16x32_bf16 v[60:63], v[136:139], v[168:171], v[60:63]
	v_mfma_f32_16x16x32_bf16 v[60:63], v[140:143], v[172:175], v[60:63]
	v_mfma_f32_16x16x32_bf16 v[56:59], v[144:147], v[168:171], v[56:59]
	v_mfma_f32_16x16x32_bf16 v[56:59], v[148:151], v[172:175], v[56:59]
	v_mfma_f32_16x16x32_bf16 v[52:55], v[136:139], v[176:179], v[52:55]
	v_mfma_f32_16x16x32_bf16 v[52:55], v[140:143], v[180:183], v[52:55]
	v_mfma_f32_16x16x32_bf16 v[44:47], v[144:147], v[176:179], v[44:47]
	v_mfma_f32_16x16x32_bf16 v[44:47], v[148:151], v[180:183], v[44:47]
	v_mfma_f32_16x16x32_bf16 v[36:39], v[136:139], v[184:187], v[36:39]
	v_mfma_f32_16x16x32_bf16 v[36:39], v[140:143], v[188:191], v[36:39]
	v_mfma_f32_16x16x32_bf16 v[28:31], v[144:147], v[184:187], v[28:31]
	v_mfma_f32_16x16x32_bf16 v[28:31], v[148:151], v[188:191], v[28:31]
	v_mfma_f32_16x16x32_bf16 v[20:23], v[136:139], v[192:195], v[20:23]
	v_mfma_f32_16x16x32_bf16 v[20:23], v[140:143], v[200:203], v[20:23]
	v_mfma_f32_16x16x32_bf16 v[12:15], v[144:147], v[192:195], v[12:15]
	v_mfma_f32_16x16x32_bf16 v[12:15], v[148:151], v[200:203], v[12:15]
	v_mfma_f32_16x16x32_bf16 v[48:51], v[152:155], v[168:171], v[48:51]
	v_mfma_f32_16x16x32_bf16 v[48:51], v[156:159], v[172:175], v[48:51]
	v_mfma_f32_16x16x32_bf16 v[40:43], v[160:163], v[168:171], v[40:43]
	v_mfma_f32_16x16x32_bf16 v[40:43], v[164:167], v[172:175], v[40:43]
	v_mfma_f32_16x16x32_bf16 v[32:35], v[152:155], v[176:179], v[32:35]
	v_mfma_f32_16x16x32_bf16 v[32:35], v[156:159], v[180:183], v[32:35]
	v_mfma_f32_16x16x32_bf16 v[24:27], v[160:163], v[176:179], v[24:27]
	v_mfma_f32_16x16x32_bf16 v[24:27], v[164:167], v[180:183], v[24:27]
	v_mfma_f32_16x16x32_bf16 v[16:19], v[152:155], v[184:187], v[16:19]
	v_mfma_f32_16x16x32_bf16 v[16:19], v[156:159], v[188:191], v[16:19]
	v_mfma_f32_16x16x32_bf16 v[8:11], v[160:163], v[184:187], v[8:11]
	v_mfma_f32_16x16x32_bf16 v[8:11], v[164:167], v[188:191], v[8:11]
	v_mfma_f32_16x16x32_bf16 v[4:7], v[152:155], v[192:195], v[4:7]
	v_mfma_f32_16x16x32_bf16 v[4:7], v[156:159], v[200:203], v[4:7]
	v_mfma_f32_16x16x32_bf16 v[0:3], v[160:163], v[192:195], v[0:3]
	v_mfma_f32_16x16x32_bf16 v[0:3], v[164:167], v[200:203], v[0:3]
	s_setprio 0
	s_barrier
	s_add_i32 s23, 0, 0x18000
	v_add_u32_e32 v128, s23, v134
	s_add_i32 s46, 0, 0x1c000
	ds_read_b128 v[136:139], v128
	ds_read_b128 v[140:143], v128 offset:1024
	ds_read_b128 v[144:147], v128 offset:2048
	ds_read_b128 v[148:151], v128 offset:3072
	v_add_u32_e32 v128, s46, v134
	ds_read_b128 v[152:155], v128
	ds_read_b128 v[156:159], v128 offset:1024
	ds_read_b128 v[160:163], v128 offset:2048
	ds_read_b128 v[164:167], v128 offset:3072
	s_add_u32 s40, s40, 0x80000
	s_addc_u32 s41, s41, 0
	s_mov_b32 m0, s56
	ds_read_b128 v[168:171], v135 offset:32768
	ds_read_b128 v[172:175], v135 offset:33792
	ds_read_b128 v[176:179], v135 offset:34816
	ds_read_b128 v[180:183], v135 offset:35840
	ds_read_b128 v[184:187], v135 offset:36864
	ds_read_b128 v[188:191], v135 offset:37888
	ds_read_b128 v[192:195], v135 offset:38912
	ds_read_b128 v[200:203], v135 offset:39936
	s_nop 0
	global_load_lds_dwordx4 v133, s[40:41]
	s_mov_b32 m0, s57
	s_nop 0
	global_load_lds_dwordx4 v131, s[40:41]
	s_waitcnt vmcnt(8)
	s_waitcnt lgkmcnt(0)
	s_setprio 1
	s_barrier
	v_mfma_f32_16x16x32_bf16 v[124:127], v[136:139], v[168:171], v[124:127]
	v_mfma_f32_16x16x32_bf16 v[124:127], v[140:143], v[172:175], v[124:127]
	v_mfma_f32_16x16x32_bf16 v[120:123], v[144:147], v[168:171], v[120:123]
	v_mfma_f32_16x16x32_bf16 v[120:123], v[148:151], v[172:175], v[120:123]
	v_mfma_f32_16x16x32_bf16 v[116:119], v[136:139], v[176:179], v[116:119]
	v_mfma_f32_16x16x32_bf16 v[116:119], v[140:143], v[180:183], v[116:119]
	v_mfma_f32_16x16x32_bf16 v[108:111], v[144:147], v[176:179], v[108:111]
	v_mfma_f32_16x16x32_bf16 v[108:111], v[148:151], v[180:183], v[108:111]
	v_mfma_f32_16x16x32_bf16 v[100:103], v[136:139], v[184:187], v[100:103]
	v_mfma_f32_16x16x32_bf16 v[100:103], v[140:143], v[188:191], v[100:103]
	v_mfma_f32_16x16x32_bf16 v[92:95], v[144:147], v[184:187], v[92:95]
	v_mfma_f32_16x16x32_bf16 v[92:95], v[148:151], v[188:191], v[92:95]
	v_mfma_f32_16x16x32_bf16 v[84:87], v[136:139], v[192:195], v[84:87]
	v_mfma_f32_16x16x32_bf16 v[84:87], v[140:143], v[200:203], v[84:87]
	v_mfma_f32_16x16x32_bf16 v[76:79], v[144:147], v[192:195], v[76:79]
	v_mfma_f32_16x16x32_bf16 v[76:79], v[148:151], v[200:203], v[76:79]
	v_mfma_f32_16x16x32_bf16 v[112:115], v[152:155], v[168:171], v[112:115]
	v_mfma_f32_16x16x32_bf16 v[112:115], v[156:159], v[172:175], v[112:115]
	v_mfma_f32_16x16x32_bf16 v[104:107], v[160:163], v[168:171], v[104:107]
	v_mfma_f32_16x16x32_bf16 v[104:107], v[164:167], v[172:175], v[104:107]
	v_mfma_f32_16x16x32_bf16 v[96:99], v[152:155], v[176:179], v[96:99]
	v_mfma_f32_16x16x32_bf16 v[96:99], v[156:159], v[180:183], v[96:99]
	v_mfma_f32_16x16x32_bf16 v[88:91], v[160:163], v[176:179], v[88:91]
	v_mfma_f32_16x16x32_bf16 v[88:91], v[164:167], v[180:183], v[88:91]
	v_mfma_f32_16x16x32_bf16 v[80:83], v[152:155], v[184:187], v[80:83]
	v_mfma_f32_16x16x32_bf16 v[80:83], v[156:159], v[188:191], v[80:83]
	v_mfma_f32_16x16x32_bf16 v[72:75], v[160:163], v[184:187], v[72:75]
	v_mfma_f32_16x16x32_bf16 v[72:75], v[164:167], v[188:191], v[72:75]
	v_mfma_f32_16x16x32_bf16 v[68:71], v[152:155], v[192:195], v[68:71]
	v_mfma_f32_16x16x32_bf16 v[68:71], v[156:159], v[200:203], v[68:71]
	v_mfma_f32_16x16x32_bf16 v[64:67], v[160:163], v[192:195], v[64:67]
	v_mfma_f32_16x16x32_bf16 v[64:67], v[164:167], v[200:203], v[64:67]
	s_setprio 0
	s_barrier
	s_add_u32 s40, s38, 0x80
	s_addc_u32 s41, s39, 0
	s_add_i32 s23, s23, s97
	s_mov_b32 m0, s23
	ds_read_b128 v[168:171], v135 offset:49152
	ds_read_b128 v[172:175], v135 offset:50176
	ds_read_b128 v[176:179], v135 offset:51200
	ds_read_b128 v[180:183], v135 offset:52224
	ds_read_b128 v[184:187], v135 offset:53248
	ds_read_b128 v[188:191], v135 offset:54272
	ds_read_b128 v[192:195], v135 offset:55296
	ds_read_b128 v[200:203], v135 offset:56320
	s_nop 0
	global_load_lds_dwordx4 v132, s[40:41]
	s_add_i32 m0, s23, 0x2000
	s_add_u32 s38, s38, 0x80080
	s_addc_u32 s39, s39, 0
	s_add_i32 s23, s46, s97
	s_nop 0
	global_load_lds_dwordx4 v130, s[40:41]
	s_mov_b32 m0, s23
	s_nop 0
	global_load_lds_dwordx4 v132, s[38:39]
	s_add_i32 m0, s23, 0x2000
	s_nop 0
	global_load_lds_dwordx4 v130, s[38:39]
	s_mov_b32 m0, s70
	s_nop 0
	global_load_lds_dwordx4 v133, s[36:37]
	s_mov_b32 m0, s71
	s_nop 0
	global_load_lds_dwordx4 v131, s[36:37]
	s_waitcnt vmcnt(8)
	s_waitcnt lgkmcnt(0)
	s_setprio 1
	s_barrier
	v_mfma_f32_16x16x32_bf16 v[60:63], v[136:139], v[168:171], v[60:63]
	v_mfma_f32_16x16x32_bf16 v[60:63], v[140:143], v[172:175], v[60:63]
	v_mfma_f32_16x16x32_bf16 v[56:59], v[144:147], v[168:171], v[56:59]
	v_mfma_f32_16x16x32_bf16 v[56:59], v[148:151], v[172:175], v[56:59]
	v_mfma_f32_16x16x32_bf16 v[52:55], v[136:139], v[176:179], v[52:55]
	v_mfma_f32_16x16x32_bf16 v[52:55], v[140:143], v[180:183], v[52:55]
	v_mfma_f32_16x16x32_bf16 v[44:47], v[144:147], v[176:179], v[44:47]
	v_mfma_f32_16x16x32_bf16 v[44:47], v[148:151], v[180:183], v[44:47]
	v_mfma_f32_16x16x32_bf16 v[36:39], v[136:139], v[184:187], v[36:39]
	v_mfma_f32_16x16x32_bf16 v[36:39], v[140:143], v[188:191], v[36:39]
	v_mfma_f32_16x16x32_bf16 v[28:31], v[144:147], v[184:187], v[28:31]
	v_mfma_f32_16x16x32_bf16 v[28:31], v[148:151], v[188:191], v[28:31]
	v_mfma_f32_16x16x32_bf16 v[20:23], v[136:139], v[192:195], v[20:23]
	v_mfma_f32_16x16x32_bf16 v[20:23], v[140:143], v[200:203], v[20:23]
	v_mfma_f32_16x16x32_bf16 v[12:15], v[144:147], v[192:195], v[12:15]
	v_mfma_f32_16x16x32_bf16 v[12:15], v[148:151], v[200:203], v[12:15]
	v_mfma_f32_16x16x32_bf16 v[48:51], v[152:155], v[168:171], v[48:51]
	v_mfma_f32_16x16x32_bf16 v[48:51], v[156:159], v[172:175], v[48:51]
	v_mfma_f32_16x16x32_bf16 v[40:43], v[160:163], v[168:171], v[40:43]
	v_mfma_f32_16x16x32_bf16 v[40:43], v[164:167], v[172:175], v[40:43]
	v_mfma_f32_16x16x32_bf16 v[32:35], v[152:155], v[176:179], v[32:35]
	v_mfma_f32_16x16x32_bf16 v[32:35], v[156:159], v[180:183], v[32:35]
	v_mfma_f32_16x16x32_bf16 v[24:27], v[160:163], v[176:179], v[24:27]
	v_mfma_f32_16x16x32_bf16 v[24:27], v[164:167], v[180:183], v[24:27]
	v_mfma_f32_16x16x32_bf16 v[16:19], v[152:155], v[184:187], v[16:19]
	v_mfma_f32_16x16x32_bf16 v[16:19], v[156:159], v[188:191], v[16:19]
	v_mfma_f32_16x16x32_bf16 v[8:11], v[160:163], v[184:187], v[8:11]
	v_mfma_f32_16x16x32_bf16 v[8:11], v[164:167], v[188:191], v[8:11]
	v_mfma_f32_16x16x32_bf16 v[4:7], v[152:155], v[192:195], v[4:7]
	v_mfma_f32_16x16x32_bf16 v[4:7], v[156:159], v[200:203], v[4:7]
	v_mfma_f32_16x16x32_bf16 v[0:3], v[160:163], v[192:195], v[0:3]
	v_mfma_f32_16x16x32_bf16 v[0:3], v[164:167], v[200:203], v[0:3]
	s_setprio 0
	s_barrier
	s_add_i32 s21, s21, 2
	s_add_u32 s4, s4, 0x100
	s_addc_u32 s5, s5, 0
	s_add_u32 s15, s15, 0x100
	s_addc_u32 s17, s17, 0
	s_add_u32 s34, s34, 0x100
	s_addc_u32 s35, s35, 0
	s_cmp_gt_u32 s21, 13
	s_cbranch_scc0 .LBB0_1290
	s_and_b64 vcc, exec, s[60:61]
	s_cbranch_vccz .LBB0_1293
	s_barrier

.LBB0_1425:
	s_cmpk_eq_i32 s80, 0x54
	s_cselect_b32 s56, s48, s4
	s_cselect_b32 s57, s49, s5
	s_cselect_b32 s74, s70, s15
	s_cselect_b32 s75, s71, s72
	s_add_u32 s16, s56, 0x80
	s_addc_u32 s17, s57, 0
	s_add_i32 s81, 0, 0x10000
	s_add_i32 vcc_lo, 0, 0x14000
	v_add_u32_e32 v136, s81, v172
	v_add_u32_e32 v156, vcc_lo, v172
	ds_read_b128 v[120:123], v136
	ds_read_b128 v[124:127], v136 offset:1024
	ds_read_b128 v[132:135], v136 offset:2048
	ds_read_b128 v[136:139], v136 offset:3072
	ds_read_b128 v[144:147], v156
	ds_read_b128 v[148:151], v156 offset:1024
	ds_read_b128 v[152:155], v156 offset:2048
	ds_read_b128 v[156:159], v156 offset:3072
	s_mov_b64 s[12:13], s[28:29]
	s_add_i32 m0, s2, 0xc000
	ds_read_b128 v[160:163], v173
	ds_read_b128 v[164:167], v173 offset:1024
	ds_read_b128 v[174:177], v173 offset:2048
	ds_read_b128 v[178:181], v173 offset:3072
	ds_read_b128 v[182:185], v173 offset:4096
	ds_read_b128 v[186:189], v173 offset:5120
	ds_read_b128 v[190:193], v173 offset:6144
	ds_read_b128 v[200:203], v173 offset:7168
	s_nop 0
	global_load_lds_dwordx4 v168, s[12:13]
	s_add_i32 m0, s2, 0xe000
	s_nop 0
	global_load_lds_dwordx4 v170, s[12:13]
	s_waitcnt vmcnt(8)
	s_waitcnt lgkmcnt(0)
	s_setprio 1
	s_barrier
	v_mfma_f32_16x16x32_bf16 v[140:143], v[120:123], v[160:163], v[140:143]
	v_mfma_f32_16x16x32_bf16 v[140:143], v[124:127], v[164:167], v[140:143]
	v_mfma_f32_16x16x32_bf16 v[128:131], v[132:135], v[160:163], v[128:131]
	v_mfma_f32_16x16x32_bf16 v[128:131], v[136:139], v[164:167], v[128:131]
	v_mfma_f32_16x16x32_bf16 v[116:119], v[120:123], v[174:177], v[116:119]
	v_mfma_f32_16x16x32_bf16 v[116:119], v[124:127], v[178:181], v[116:119]
	v_mfma_f32_16x16x32_bf16 v[104:107], v[132:135], v[174:177], v[104:107]
	v_mfma_f32_16x16x32_bf16 v[104:107], v[136:139], v[178:181], v[104:107]
	v_mfma_f32_16x16x32_bf16 v[96:99], v[120:123], v[182:185], v[96:99]
	v_mfma_f32_16x16x32_bf16 v[96:99], v[124:127], v[186:189], v[96:99]
	v_mfma_f32_16x16x32_bf16 v[88:91], v[132:135], v[182:185], v[88:91]
	v_mfma_f32_16x16x32_bf16 v[88:91], v[136:139], v[186:189], v[88:91]
	v_mfma_f32_16x16x32_bf16 v[84:87], v[120:123], v[190:193], v[84:87]
	v_mfma_f32_16x16x32_bf16 v[84:87], v[124:127], v[200:203], v[84:87]
	v_mfma_f32_16x16x32_bf16 v[72:75], v[132:135], v[190:193], v[72:75]
	v_mfma_f32_16x16x32_bf16 v[72:75], v[136:139], v[200:203], v[72:75]
	v_mfma_f32_16x16x32_bf16 v[112:115], v[144:147], v[160:163], v[112:115]
	v_mfma_f32_16x16x32_bf16 v[112:115], v[148:151], v[164:167], v[112:115]
	v_mfma_f32_16x16x32_bf16 v[108:111], v[152:155], v[160:163], v[108:111]
	v_mfma_f32_16x16x32_bf16 v[108:111], v[156:159], v[164:167], v[108:111]
	v_mfma_f32_16x16x32_bf16 v[100:103], v[144:147], v[174:177], v[100:103]
	v_mfma_f32_16x16x32_bf16 v[100:103], v[148:151], v[178:181], v[100:103]
	v_mfma_f32_16x16x32_bf16 v[92:95], v[152:155], v[174:177], v[92:95]
	v_mfma_f32_16x16x32_bf16 v[92:95], v[156:159], v[178:181], v[92:95]
	v_mfma_f32_16x16x32_bf16 v[80:83], v[144:147], v[182:185], v[80:83]
	v_mfma_f32_16x16x32_bf16 v[80:83], v[148:151], v[186:189], v[80:83]
	v_mfma_f32_16x16x32_bf16 v[76:79], v[152:155], v[182:185], v[76:79]
	v_mfma_f32_16x16x32_bf16 v[76:79], v[156:159], v[186:189], v[76:79]
	v_mfma_f32_16x16x32_bf16 v[68:71], v[144:147], v[190:193], v[68:71]
	v_mfma_f32_16x16x32_bf16 v[68:71], v[148:151], v[200:203], v[68:71]
	v_mfma_f32_16x16x32_bf16 v[64:67], v[152:155], v[190:193], v[64:67]
	v_mfma_f32_16x16x32_bf16 v[64:67], v[156:159], v[200:203], v[64:67]
	s_setprio 0
	s_barrier
	s_add_i32 s81, s81, s97
	s_mov_b64 s[12:13], s[74:75]
	s_mov_b32 m0, s81
	ds_read_b128 v[160:163], v173 offset:16384
	ds_read_b128 v[164:167], v173 offset:17408
	ds_read_b128 v[174:177], v173 offset:18432
	ds_read_b128 v[178:181], v173 offset:19456
	ds_read_b128 v[182:185], v173 offset:20480
	ds_read_b128 v[186:189], v173 offset:21504
	ds_read_b128 v[190:193], v173 offset:22528
	ds_read_b128 v[200:203], v173 offset:23552
	s_nop 0
	global_load_lds_dwordx4 v169, s[12:13]
	s_add_i32 m0, s81, 0x2000
	s_nop 0
	global_load_lds_dwordx4 v171, s[12:13]
	s_add_u32 s12, s74, 0x160000
	s_addc_u32 s13, s75, 0
	s_add_i32 s81, vcc_lo, s97
	s_mov_b32 m0, s81
	s_nop 0
	global_load_lds_dwordx4 v169, s[12:13]
	s_add_i32 m0, s81, 0x2000
	s_nop 0
	global_load_lds_dwordx4 v171, s[12:13]
	s_mov_b64 s[12:13], s[56:57]
	s_mov_b32 m0, s2
	s_nop 0
	global_load_lds_dwordx4 v168, s[12:13]
	s_mov_b32 m0, s65
	s_nop 0
	global_load_lds_dwordx4 v170, s[12:13]
	s_waitcnt vmcnt(8)
	s_waitcnt lgkmcnt(0)
	s_setprio 1
	s_barrier
	v_mfma_f32_16x16x32_bf16 v[60:63], v[120:123], v[160:163], v[60:63]
	v_mfma_f32_16x16x32_bf16 v[60:63], v[124:127], v[164:167], v[60:63]
	v_mfma_f32_16x16x32_bf16 v[56:59], v[132:135], v[160:163], v[56:59]
	v_mfma_f32_16x16x32_bf16 v[56:59], v[136:139], v[164:167], v[56:59]
	v_mfma_f32_16x16x32_bf16 v[48:51], v[120:123], v[174:177], v[48:51]
	v_mfma_f32_16x16x32_bf16 v[48:51], v[124:127], v[178:181], v[48:51]
	v_mfma_f32_16x16x32_bf16 v[40:43], v[132:135], v[174:177], v[40:43]
	v_mfma_f32_16x16x32_bf16 v[40:43], v[136:139], v[178:181], v[40:43]
	v_mfma_f32_16x16x32_bf16 v[32:35], v[120:123], v[182:185], v[32:35]
	v_mfma_f32_16x16x32_bf16 v[32:35], v[124:127], v[186:189], v[32:35]
	v_mfma_f32_16x16x32_bf16 v[24:27], v[132:135], v[182:185], v[24:27]
	v_mfma_f32_16x16x32_bf16 v[24:27], v[136:139], v[186:189], v[24:27]
	v_mfma_f32_16x16x32_bf16 v[16:19], v[120:123], v[190:193], v[16:19]
	v_mfma_f32_16x16x32_bf16 v[16:19], v[124:127], v[200:203], v[16:19]
	v_mfma_f32_16x16x32_bf16 v[8:11], v[132:135], v[190:193], v[8:11]
	v_mfma_f32_16x16x32_bf16 v[8:11], v[136:139], v[200:203], v[8:11]
	v_mfma_f32_16x16x32_bf16 v[52:55], v[144:147], v[160:163], v[52:55]
	v_mfma_f32_16x16x32_bf16 v[52:55], v[148:151], v[164:167], v[52:55]
	v_mfma_f32_16x16x32_bf16 v[44:47], v[152:155], v[160:163], v[44:47]
	v_mfma_f32_16x16x32_bf16 v[44:47], v[156:159], v[164:167], v[44:47]
	v_mfma_f32_16x16x32_bf16 v[36:39], v[144:147], v[174:177], v[36:39]
	v_mfma_f32_16x16x32_bf16 v[36:39], v[148:151], v[178:181], v[36:39]
	v_mfma_f32_16x16x32_bf16 v[28:31], v[152:155], v[174:177], v[28:31]
	v_mfma_f32_16x16x32_bf16 v[28:31], v[156:159], v[178:181], v[28:31]
	v_mfma_f32_16x16x32_bf16 v[20:23], v[144:147], v[182:185], v[20:23]
	v_mfma_f32_16x16x32_bf16 v[20:23], v[148:151], v[186:189], v[20:23]
	v_mfma_f32_16x16x32_bf16 v[12:15], v[152:155], v[182:185], v[12:15]
	v_mfma_f32_16x16x32_bf16 v[12:15], v[156:159], v[186:189], v[12:15]
	v_mfma_f32_16x16x32_bf16 v[4:7], v[144:147], v[190:193], v[4:7]
	v_mfma_f32_16x16x32_bf16 v[4:7], v[148:151], v[200:203], v[4:7]
	v_mfma_f32_16x16x32_bf16 v[0:3], v[152:155], v[190:193], v[0:3]
	v_mfma_f32_16x16x32_bf16 v[0:3], v[156:159], v[200:203], v[0:3]
	s_setprio 0
	s_barrier
	s_add_i32 s81, 0, 0x18000
	s_add_i32 vcc_lo, 0, 0x1c000
	v_add_u32_e32 v136, s81, v172
	v_add_u32_e32 v156, vcc_lo, v172
	ds_read_b128 v[120:123], v136
	ds_read_b128 v[124:127], v136 offset:1024
	ds_read_b128 v[132:135], v136 offset:2048
	ds_read_b128 v[136:139], v136 offset:3072
	ds_read_b128 v[144:147], v156
	ds_read_b128 v[148:151], v156 offset:1024
	ds_read_b128 v[152:155], v156 offset:2048
	ds_read_b128 v[156:159], v156 offset:3072
	s_add_u32 s12, s56, 0x160000
	s_addc_u32 s13, s57, 0
	s_mov_b32 m0, s93
	ds_read_b128 v[160:163], v173 offset:32768
	ds_read_b128 v[164:167], v173 offset:33792
	ds_read_b128 v[174:177], v173 offset:34816
	ds_read_b128 v[178:181], v173 offset:35840
	ds_read_b128 v[182:185], v173 offset:36864
	ds_read_b128 v[186:189], v173 offset:37888
	ds_read_b128 v[190:193], v173 offset:38912
	ds_read_b128 v[200:203], v173 offset:39936
	s_nop 0
	global_load_lds_dwordx4 v168, s[12:13]
	s_mov_b32 m0, s92
	s_nop 0
	global_load_lds_dwordx4 v170, s[12:13]
	s_waitcnt vmcnt(8)
	s_waitcnt lgkmcnt(0)
	s_setprio 1
	s_barrier
	v_mfma_f32_16x16x32_bf16 v[140:143], v[120:123], v[160:163], v[140:143]
	v_mfma_f32_16x16x32_bf16 v[140:143], v[124:127], v[164:167], v[140:143]
	v_mfma_f32_16x16x32_bf16 v[128:131], v[132:135], v[160:163], v[128:131]
	v_mfma_f32_16x16x32_bf16 v[128:131], v[136:139], v[164:167], v[128:131]
	v_mfma_f32_16x16x32_bf16 v[116:119], v[120:123], v[174:177], v[116:119]
	v_mfma_f32_16x16x32_bf16 v[116:119], v[124:127], v[178:181], v[116:119]
	v_mfma_f32_16x16x32_bf16 v[104:107], v[132:135], v[174:177], v[104:107]
	v_mfma_f32_16x16x32_bf16 v[104:107], v[136:139], v[178:181], v[104:107]
	v_mfma_f32_16x16x32_bf16 v[96:99], v[120:123], v[182:185], v[96:99]
	v_mfma_f32_16x16x32_bf16 v[96:99], v[124:127], v[186:189], v[96:99]
	v_mfma_f32_16x16x32_bf16 v[88:91], v[132:135], v[182:185], v[88:91]
	v_mfma_f32_16x16x32_bf16 v[88:91], v[136:139], v[186:189], v[88:91]
	v_mfma_f32_16x16x32_bf16 v[84:87], v[120:123], v[190:193], v[84:87]
	v_mfma_f32_16x16x32_bf16 v[84:87], v[124:127], v[200:203], v[84:87]
	v_mfma_f32_16x16x32_bf16 v[72:75], v[132:135], v[190:193], v[72:75]
	v_mfma_f32_16x16x32_bf16 v[72:75], v[136:139], v[200:203], v[72:75]
	v_mfma_f32_16x16x32_bf16 v[112:115], v[144:147], v[160:163], v[112:115]
	v_mfma_f32_16x16x32_bf16 v[112:115], v[148:151], v[164:167], v[112:115]
	v_mfma_f32_16x16x32_bf16 v[108:111], v[152:155], v[160:163], v[108:111]
	v_mfma_f32_16x16x32_bf16 v[108:111], v[156:159], v[164:167], v[108:111]
	v_mfma_f32_16x16x32_bf16 v[100:103], v[144:147], v[174:177], v[100:103]
	v_mfma_f32_16x16x32_bf16 v[100:103], v[148:151], v[178:181], v[100:103]
	v_mfma_f32_16x16x32_bf16 v[92:95], v[152:155], v[174:177], v[92:95]
	v_mfma_f32_16x16x32_bf16 v[92:95], v[156:159], v[178:181], v[92:95]
	v_mfma_f32_16x16x32_bf16 v[80:83], v[144:147], v[182:185], v[80:83]
	v_mfma_f32_16x16x32_bf16 v[80:83], v[148:151], v[186:189], v[80:83]
	v_mfma_f32_16x16x32_bf16 v[76:79], v[152:155], v[182:185], v[76:79]
	v_mfma_f32_16x16x32_bf16 v[76:79], v[156:159], v[186:189], v[76:79]
	v_mfma_f32_16x16x32_bf16 v[68:71], v[144:147], v[190:193], v[68:71]
	v_mfma_f32_16x16x32_bf16 v[68:71], v[148:151], v[200:203], v[68:71]
	v_mfma_f32_16x16x32_bf16 v[64:67], v[152:155], v[190:193], v[64:67]
	v_mfma_f32_16x16x32_bf16 v[64:67], v[156:159], v[200:203], v[64:67]
	s_setprio 0
	s_barrier
	s_add_u32 s12, s74, 0x80
	s_addc_u32 s13, s75, 0
	s_add_i32 s56, s81, s97
	s_mov_b32 m0, s56
	ds_read_b128 v[160:163], v173 offset:49152
	ds_read_b128 v[164:167], v173 offset:50176
	ds_read_b128 v[174:177], v173 offset:51200
	ds_read_b128 v[178:181], v173 offset:52224
	ds_read_b128 v[182:185], v173 offset:53248
	ds_read_b128 v[186:189], v173 offset:54272
	ds_read_b128 v[190:193], v173 offset:55296
	ds_read_b128 v[200:203], v173 offset:56320
	s_nop 0
	global_load_lds_dwordx4 v169, s[12:13]
	s_add_i32 m0, s56, 0x2000
	s_nop 0
	global_load_lds_dwordx4 v171, s[12:13]
	s_add_u32 s12, s74, 0x160080
	s_addc_u32 s13, s75, 0
	s_add_i32 s56, vcc_lo, s97
	s_mov_b32 m0, s56
	s_nop 0
	global_load_lds_dwordx4 v169, s[12:13]
	s_add_i32 m0, s56, 0x2000
	s_nop 0
	global_load_lds_dwordx4 v171, s[12:13]
	s_mov_b32 m0, s19
	s_nop 0
	global_load_lds_dwordx4 v168, s[16:17]
	s_mov_b32 m0, s89
	s_nop 0
	global_load_lds_dwordx4 v170, s[16:17]
	s_waitcnt vmcnt(8)
	s_waitcnt lgkmcnt(0)
	s_setprio 1
	s_barrier
	v_mfma_f32_16x16x32_bf16 v[60:63], v[120:123], v[160:163], v[60:63]
	v_mfma_f32_16x16x32_bf16 v[60:63], v[124:127], v[164:167], v[60:63]
	v_mfma_f32_16x16x32_bf16 v[56:59], v[132:135], v[160:163], v[56:59]
	v_mfma_f32_16x16x32_bf16 v[56:59], v[136:139], v[164:167], v[56:59]
	v_mfma_f32_16x16x32_bf16 v[48:51], v[120:123], v[174:177], v[48:51]
	v_mfma_f32_16x16x32_bf16 v[48:51], v[124:127], v[178:181], v[48:51]
	v_mfma_f32_16x16x32_bf16 v[40:43], v[132:135], v[174:177], v[40:43]
	v_mfma_f32_16x16x32_bf16 v[40:43], v[136:139], v[178:181], v[40:43]
	v_mfma_f32_16x16x32_bf16 v[32:35], v[120:123], v[182:185], v[32:35]
	v_mfma_f32_16x16x32_bf16 v[32:35], v[124:127], v[186:189], v[32:35]
	v_mfma_f32_16x16x32_bf16 v[24:27], v[132:135], v[182:185], v[24:27]
	v_mfma_f32_16x16x32_bf16 v[24:27], v[136:139], v[186:189], v[24:27]
	v_mfma_f32_16x16x32_bf16 v[16:19], v[120:123], v[190:193], v[16:19]
	v_mfma_f32_16x16x32_bf16 v[16:19], v[124:127], v[200:203], v[16:19]
	v_mfma_f32_16x16x32_bf16 v[8:11], v[132:135], v[190:193], v[8:11]
	v_mfma_f32_16x16x32_bf16 v[8:11], v[136:139], v[200:203], v[8:11]
	v_mfma_f32_16x16x32_bf16 v[52:55], v[144:147], v[160:163], v[52:55]
	v_mfma_f32_16x16x32_bf16 v[52:55], v[148:151], v[164:167], v[52:55]
	v_mfma_f32_16x16x32_bf16 v[44:47], v[152:155], v[160:163], v[44:47]
	v_mfma_f32_16x16x32_bf16 v[44:47], v[156:159], v[164:167], v[44:47]
	v_mfma_f32_16x16x32_bf16 v[36:39], v[144:147], v[174:177], v[36:39]
	v_mfma_f32_16x16x32_bf16 v[36:39], v[148:151], v[178:181], v[36:39]
	v_mfma_f32_16x16x32_bf16 v[28:31], v[152:155], v[174:177], v[28:31]
	v_mfma_f32_16x16x32_bf16 v[28:31], v[156:159], v[178:181], v[28:31]
	v_mfma_f32_16x16x32_bf16 v[20:23], v[144:147], v[182:185], v[20:23]
	v_mfma_f32_16x16x32_bf16 v[20:23], v[148:151], v[186:189], v[20:23]
	v_mfma_f32_16x16x32_bf16 v[12:15], v[152:155], v[182:185], v[12:15]
	v_mfma_f32_16x16x32_bf16 v[12:15], v[156:159], v[186:189], v[12:15]
	v_mfma_f32_16x16x32_bf16 v[4:7], v[144:147], v[190:193], v[4:7]
	v_mfma_f32_16x16x32_bf16 v[4:7], v[148:151], v[200:203], v[4:7]
	v_mfma_f32_16x16x32_bf16 v[0:3], v[152:155], v[190:193], v[0:3]
	v_mfma_f32_16x16x32_bf16 v[0:3], v[156:159], v[200:203], v[0:3]
	s_setprio 0
	s_barrier
	s_add_i32 s80, s80, 2
	s_add_u32 s4, s4, 0x100
	s_addc_u32 s5, s5, 0
	s_add_u32 s15, s15, 0x100
	s_addc_u32 s72, s72, 0
	s_add_u32 s28, s28, 0x100
	s_addc_u32 s29, s29, 0
	s_cmpk_gt_u32 s80, 0x55
	s_cbranch_scc0 .LBB0_1425
	s_and_b64 vcc, exec, s[60:61]
	s_cbranch_vccz .LBB0_1428
	s_barrier

.LBB0_1579:
	s_cmp_eq_u32 s49, 4
	s_cselect_b32 s26, s14, s13
	s_cselect_b32 s27, s15, s21
	s_cselect_b32 s24, s16, s47
	s_cselect_b32 s25, s17, s48
	s_add_u32 s22, s26, 0x80
	s_addc_u32 s23, s27, 0
	s_add_i32 s65, 0, 0x10000
	s_add_i32 s69, 0, 0x14000
	v_add_u32_e32 v132, s65, v154
	v_add_u32_e32 v148, s69, v154
	ds_read_b128 v[112:115], v132
	ds_read_b128 v[120:123], v132 offset:1024
	ds_read_b128 v[128:131], v132 offset:2048
	ds_read_b128 v[132:135], v132 offset:3072
	ds_read_b128 v[144:147], v148
	ds_read_b128 v[156:159], v148 offset:1024
	ds_read_b128 v[160:163], v148 offset:2048
	ds_read_b128 v[164:167], v148 offset:3072
	s_add_u32 s56, s13, 0x15ff80
	s_addc_u32 s57, s21, 0
	s_add_i32 m0, s31, 0xc000
	ds_read_b128 v[168:171], v155
	ds_read_b128 v[172:175], v155 offset:1024
	ds_read_b128 v[176:179], v155 offset:2048
	ds_read_b128 v[180:183], v155 offset:3072
	ds_read_b128 v[184:187], v155 offset:4096
	ds_read_b128 v[188:191], v155 offset:5120
	ds_read_b128 v[192:195], v155 offset:6144
	ds_read_b128 v[200:203], v155 offset:7168
	s_nop 0
	global_load_lds_dwordx4 v151, s[56:57]
	s_add_i32 m0, s31, 0xe000
	s_nop 0
	global_load_lds_dwordx4 v150, s[56:57]
	s_waitcnt vmcnt(8)
	s_waitcnt lgkmcnt(0)
	s_setprio 1
	s_barrier
	v_mfma_f32_16x16x32_bf16 v[140:143], v[112:115], v[168:171], v[140:143]
	v_mfma_f32_16x16x32_bf16 v[140:143], v[120:123], v[172:175], v[140:143]
	v_mfma_f32_16x16x32_bf16 v[136:139], v[128:131], v[168:171], v[136:139]
	v_mfma_f32_16x16x32_bf16 v[136:139], v[132:135], v[172:175], v[136:139]
	v_mfma_f32_16x16x32_bf16 v[108:111], v[112:115], v[176:179], v[108:111]
	v_mfma_f32_16x16x32_bf16 v[108:111], v[120:123], v[180:183], v[108:111]
	v_mfma_f32_16x16x32_bf16 v[104:107], v[128:131], v[176:179], v[104:107]
	v_mfma_f32_16x16x32_bf16 v[104:107], v[132:135], v[180:183], v[104:107]
	v_mfma_f32_16x16x32_bf16 v[92:95], v[112:115], v[184:187], v[92:95]
	v_mfma_f32_16x16x32_bf16 v[92:95], v[120:123], v[188:191], v[92:95]
	v_mfma_f32_16x16x32_bf16 v[88:91], v[128:131], v[184:187], v[88:91]
	v_mfma_f32_16x16x32_bf16 v[88:91], v[132:135], v[188:191], v[88:91]
	v_mfma_f32_16x16x32_bf16 v[76:79], v[112:115], v[192:195], v[76:79]
	v_mfma_f32_16x16x32_bf16 v[76:79], v[120:123], v[200:203], v[76:79]
	v_mfma_f32_16x16x32_bf16 v[72:75], v[128:131], v[192:195], v[72:75]
	v_mfma_f32_16x16x32_bf16 v[72:75], v[132:135], v[200:203], v[72:75]
	v_mfma_f32_16x16x32_bf16 v[124:127], v[144:147], v[168:171], v[124:127]
	v_mfma_f32_16x16x32_bf16 v[124:127], v[156:159], v[172:175], v[124:127]
	v_mfma_f32_16x16x32_bf16 v[116:119], v[160:163], v[168:171], v[116:119]
	v_mfma_f32_16x16x32_bf16 v[116:119], v[164:167], v[172:175], v[116:119]
	v_mfma_f32_16x16x32_bf16 v[100:103], v[144:147], v[176:179], v[100:103]
	v_mfma_f32_16x16x32_bf16 v[100:103], v[156:159], v[180:183], v[100:103]
	v_mfma_f32_16x16x32_bf16 v[96:99], v[160:163], v[176:179], v[96:99]
	v_mfma_f32_16x16x32_bf16 v[96:99], v[164:167], v[180:183], v[96:99]
	v_mfma_f32_16x16x32_bf16 v[84:87], v[144:147], v[184:187], v[84:87]
	v_mfma_f32_16x16x32_bf16 v[84:87], v[156:159], v[188:191], v[84:87]
	v_mfma_f32_16x16x32_bf16 v[80:83], v[160:163], v[184:187], v[80:83]
	v_mfma_f32_16x16x32_bf16 v[80:83], v[164:167], v[188:191], v[80:83]
	v_mfma_f32_16x16x32_bf16 v[68:71], v[144:147], v[192:195], v[68:71]
	v_mfma_f32_16x16x32_bf16 v[68:71], v[156:159], v[200:203], v[68:71]
	v_mfma_f32_16x16x32_bf16 v[64:67], v[160:163], v[192:195], v[64:67]
	v_mfma_f32_16x16x32_bf16 v[64:67], v[164:167], v[200:203], v[64:67]
	s_setprio 0
	s_barrier
	s_add_i32 s65, s65, s97
	s_mov_b64 s[56:57], s[24:25]
	s_mov_b32 m0, s65
	ds_read_b128 v[168:171], v155 offset:16384
	ds_read_b128 v[172:175], v155 offset:17408
	ds_read_b128 v[176:179], v155 offset:18432
	ds_read_b128 v[180:183], v155 offset:19456
	ds_read_b128 v[184:187], v155 offset:20480
	ds_read_b128 v[188:191], v155 offset:21504
	ds_read_b128 v[192:195], v155 offset:22528
	ds_read_b128 v[200:203], v155 offset:23552
	s_nop 0
	global_load_lds_dwordx4 v152, s[56:57]
	s_add_i32 m0, s65, 0x2000
	s_nop 0
	global_load_lds_dwordx4 v153, s[56:57]
	s_add_u32 s56, s24, 0x160000
	s_addc_u32 s57, s25, 0
	s_add_i32 s65, s69, s97
	s_mov_b32 m0, s65
	s_nop 0
	global_load_lds_dwordx4 v152, s[56:57]
	s_add_i32 m0, s65, 0x2000
	s_nop 0
	global_load_lds_dwordx4 v153, s[56:57]
	s_mov_b64 s[56:57], s[26:27]
	s_mov_b32 m0, s31
	s_nop 0
	global_load_lds_dwordx4 v151, s[56:57]
	s_mov_b32 m0, s34
	s_nop 0
	global_load_lds_dwordx4 v150, s[56:57]
	s_waitcnt vmcnt(8)
	s_waitcnt lgkmcnt(0)
	s_setprio 1
	s_barrier
	v_mfma_f32_16x16x32_bf16 v[60:63], v[112:115], v[168:171], v[60:63]
	v_mfma_f32_16x16x32_bf16 v[60:63], v[120:123], v[172:175], v[60:63]
	v_mfma_f32_16x16x32_bf16 v[56:59], v[128:131], v[168:171], v[56:59]
	v_mfma_f32_16x16x32_bf16 v[56:59], v[132:135], v[172:175], v[56:59]
	v_mfma_f32_16x16x32_bf16 v[52:55], v[112:115], v[176:179], v[52:55]
	v_mfma_f32_16x16x32_bf16 v[52:55], v[120:123], v[180:183], v[52:55]
	v_mfma_f32_16x16x32_bf16 v[44:47], v[128:131], v[176:179], v[44:47]
	v_mfma_f32_16x16x32_bf16 v[44:47], v[132:135], v[180:183], v[44:47]
	v_mfma_f32_16x16x32_bf16 v[36:39], v[112:115], v[184:187], v[36:39]
	v_mfma_f32_16x16x32_bf16 v[36:39], v[120:123], v[188:191], v[36:39]
	v_mfma_f32_16x16x32_bf16 v[28:31], v[128:131], v[184:187], v[28:31]
	v_mfma_f32_16x16x32_bf16 v[28:31], v[132:135], v[188:191], v[28:31]
	v_mfma_f32_16x16x32_bf16 v[20:23], v[112:115], v[192:195], v[20:23]
	v_mfma_f32_16x16x32_bf16 v[20:23], v[120:123], v[200:203], v[20:23]
	v_mfma_f32_16x16x32_bf16 v[8:11], v[128:131], v[192:195], v[8:11]
	v_mfma_f32_16x16x32_bf16 v[8:11], v[132:135], v[200:203], v[8:11]
	v_mfma_f32_16x16x32_bf16 v[48:51], v[144:147], v[168:171], v[48:51]
	v_mfma_f32_16x16x32_bf16 v[48:51], v[156:159], v[172:175], v[48:51]
	v_mfma_f32_16x16x32_bf16 v[40:43], v[160:163], v[168:171], v[40:43]
	v_mfma_f32_16x16x32_bf16 v[40:43], v[164:167], v[172:175], v[40:43]
	v_mfma_f32_16x16x32_bf16 v[32:35], v[144:147], v[176:179], v[32:35]
	v_mfma_f32_16x16x32_bf16 v[32:35], v[156:159], v[180:183], v[32:35]
	v_mfma_f32_16x16x32_bf16 v[24:27], v[160:163], v[176:179], v[24:27]
	v_mfma_f32_16x16x32_bf16 v[24:27], v[164:167], v[180:183], v[24:27]
	v_mfma_f32_16x16x32_bf16 v[16:19], v[144:147], v[184:187], v[16:19]
	v_mfma_f32_16x16x32_bf16 v[16:19], v[156:159], v[188:191], v[16:19]
	v_mfma_f32_16x16x32_bf16 v[12:15], v[160:163], v[184:187], v[12:15]
	v_mfma_f32_16x16x32_bf16 v[12:15], v[164:167], v[188:191], v[12:15]
	v_mfma_f32_16x16x32_bf16 v[4:7], v[144:147], v[192:195], v[4:7]
	v_mfma_f32_16x16x32_bf16 v[4:7], v[156:159], v[200:203], v[4:7]
	v_mfma_f32_16x16x32_bf16 v[0:3], v[160:163], v[192:195], v[0:3]
	v_mfma_f32_16x16x32_bf16 v[0:3], v[164:167], v[200:203], v[0:3]
	s_setprio 0
	s_barrier
	s_add_i32 s56, 0, 0x18000
	s_add_i32 s57, 0, 0x1c000
	v_add_u32_e32 v132, s56, v154
	v_add_u32_e32 v148, s57, v154
	ds_read_b128 v[112:115], v132
	ds_read_b128 v[120:123], v132 offset:1024
	ds_read_b128 v[128:131], v132 offset:2048
	ds_read_b128 v[132:135], v132 offset:3072
	ds_read_b128 v[144:147], v148
	ds_read_b128 v[156:159], v148 offset:1024
	ds_read_b128 v[160:163], v148 offset:2048
	ds_read_b128 v[164:167], v148 offset:3072
	s_add_u32 s26, s26, 0x160000
	s_addc_u32 s27, s27, 0
	s_mov_b32 m0, s35
	ds_read_b128 v[168:171], v155 offset:32768
	ds_read_b128 v[172:175], v155 offset:33792
	ds_read_b128 v[176:179], v155 offset:34816
	ds_read_b128 v[180:183], v155 offset:35840
	ds_read_b128 v[184:187], v155 offset:36864
	ds_read_b128 v[188:191], v155 offset:37888
	ds_read_b128 v[192:195], v155 offset:38912
	ds_read_b128 v[200:203], v155 offset:39936
	s_nop 0
	global_load_lds_dwordx4 v151, s[26:27]
	s_mov_b32 m0, s36
	s_nop 0
	global_load_lds_dwordx4 v150, s[26:27]
	s_waitcnt vmcnt(8)
	s_waitcnt lgkmcnt(0)
	s_setprio 1
	s_barrier
	v_mfma_f32_16x16x32_bf16 v[140:143], v[112:115], v[168:171], v[140:143]
	v_mfma_f32_16x16x32_bf16 v[140:143], v[120:123], v[172:175], v[140:143]
	v_mfma_f32_16x16x32_bf16 v[136:139], v[128:131], v[168:171], v[136:139]
	v_mfma_f32_16x16x32_bf16 v[136:139], v[132:135], v[172:175], v[136:139]
	v_mfma_f32_16x16x32_bf16 v[108:111], v[112:115], v[176:179], v[108:111]
	v_mfma_f32_16x16x32_bf16 v[108:111], v[120:123], v[180:183], v[108:111]
	v_mfma_f32_16x16x32_bf16 v[104:107], v[128:131], v[176:179], v[104:107]
	v_mfma_f32_16x16x32_bf16 v[104:107], v[132:135], v[180:183], v[104:107]
	v_mfma_f32_16x16x32_bf16 v[92:95], v[112:115], v[184:187], v[92:95]
	v_mfma_f32_16x16x32_bf16 v[92:95], v[120:123], v[188:191], v[92:95]
	v_mfma_f32_16x16x32_bf16 v[88:91], v[128:131], v[184:187], v[88:91]
	v_mfma_f32_16x16x32_bf16 v[88:91], v[132:135], v[188:191], v[88:91]
	v_mfma_f32_16x16x32_bf16 v[76:79], v[112:115], v[192:195], v[76:79]
	v_mfma_f32_16x16x32_bf16 v[76:79], v[120:123], v[200:203], v[76:79]
	v_mfma_f32_16x16x32_bf16 v[72:75], v[128:131], v[192:195], v[72:75]
	v_mfma_f32_16x16x32_bf16 v[72:75], v[132:135], v[200:203], v[72:75]
	v_mfma_f32_16x16x32_bf16 v[124:127], v[144:147], v[168:171], v[124:127]
	v_mfma_f32_16x16x32_bf16 v[124:127], v[156:159], v[172:175], v[124:127]
	v_mfma_f32_16x16x32_bf16 v[116:119], v[160:163], v[168:171], v[116:119]
	v_mfma_f32_16x16x32_bf16 v[116:119], v[164:167], v[172:175], v[116:119]
	v_mfma_f32_16x16x32_bf16 v[100:103], v[144:147], v[176:179], v[100:103]
	v_mfma_f32_16x16x32_bf16 v[100:103], v[156:159], v[180:183], v[100:103]
	v_mfma_f32_16x16x32_bf16 v[96:99], v[160:163], v[176:179], v[96:99]
	v_mfma_f32_16x16x32_bf16 v[96:99], v[164:167], v[180:183], v[96:99]
	v_mfma_f32_16x16x32_bf16 v[84:87], v[144:147], v[184:187], v[84:87]
	v_mfma_f32_16x16x32_bf16 v[84:87], v[156:159], v[188:191], v[84:87]
	v_mfma_f32_16x16x32_bf16 v[80:83], v[160:163], v[184:187], v[80:83]
	v_mfma_f32_16x16x32_bf16 v[80:83], v[164:167], v[188:191], v[80:83]
	v_mfma_f32_16x16x32_bf16 v[68:71], v[144:147], v[192:195], v[68:71]
	v_mfma_f32_16x16x32_bf16 v[68:71], v[156:159], v[200:203], v[68:71]
	v_mfma_f32_16x16x32_bf16 v[64:67], v[160:163], v[192:195], v[64:67]
	v_mfma_f32_16x16x32_bf16 v[64:67], v[164:167], v[200:203], v[64:67]
	s_setprio 0
	s_barrier
	s_add_u32 s26, s24, 0x80
	s_addc_u32 s27, s25, 0
	s_add_i32 s56, s56, s97
	s_mov_b32 m0, s56
	ds_read_b128 v[168:171], v155 offset:49152
	ds_read_b128 v[172:175], v155 offset:50176
	ds_read_b128 v[176:179], v155 offset:51200
	ds_read_b128 v[180:183], v155 offset:52224
	ds_read_b128 v[184:187], v155 offset:53248
	ds_read_b128 v[188:191], v155 offset:54272
	ds_read_b128 v[192:195], v155 offset:55296
	ds_read_b128 v[200:203], v155 offset:56320
	s_nop 0
	global_load_lds_dwordx4 v152, s[26:27]
	s_add_i32 m0, s56, 0x2000
	s_add_u32 s24, s24, 0x160080
	s_addc_u32 s25, s25, 0
	global_load_lds_dwordx4 v153, s[26:27]
	s_add_i32 s26, s57, s97
	s_mov_b32 m0, s26
	s_nop 0
	global_load_lds_dwordx4 v152, s[24:25]
	s_add_i32 m0, s26, 0x2000
	s_nop 0
	global_load_lds_dwordx4 v153, s[24:25]
	s_mov_b32 m0, s37
	s_nop 0
	global_load_lds_dwordx4 v151, s[22:23]
	s_mov_b32 m0, s38
	s_nop 0
	global_load_lds_dwordx4 v150, s[22:23]
	s_waitcnt vmcnt(8)
	s_waitcnt lgkmcnt(0)
	s_setprio 1
	s_barrier
	v_mfma_f32_16x16x32_bf16 v[60:63], v[112:115], v[168:171], v[60:63]
	v_mfma_f32_16x16x32_bf16 v[60:63], v[120:123], v[172:175], v[60:63]
	v_mfma_f32_16x16x32_bf16 v[56:59], v[128:131], v[168:171], v[56:59]
	v_mfma_f32_16x16x32_bf16 v[56:59], v[132:135], v[172:175], v[56:59]
	v_mfma_f32_16x16x32_bf16 v[52:55], v[112:115], v[176:179], v[52:55]
	v_mfma_f32_16x16x32_bf16 v[52:55], v[120:123], v[180:183], v[52:55]
	v_mfma_f32_16x16x32_bf16 v[44:47], v[128:131], v[176:179], v[44:47]
	v_mfma_f32_16x16x32_bf16 v[44:47], v[132:135], v[180:183], v[44:47]
	v_mfma_f32_16x16x32_bf16 v[36:39], v[112:115], v[184:187], v[36:39]
	v_mfma_f32_16x16x32_bf16 v[36:39], v[120:123], v[188:191], v[36:39]
	v_mfma_f32_16x16x32_bf16 v[28:31], v[128:131], v[184:187], v[28:31]
	v_mfma_f32_16x16x32_bf16 v[28:31], v[132:135], v[188:191], v[28:31]
	v_mfma_f32_16x16x32_bf16 v[20:23], v[112:115], v[192:195], v[20:23]
	v_mfma_f32_16x16x32_bf16 v[20:23], v[120:123], v[200:203], v[20:23]
	v_mfma_f32_16x16x32_bf16 v[8:11], v[128:131], v[192:195], v[8:11]
	v_mfma_f32_16x16x32_bf16 v[8:11], v[132:135], v[200:203], v[8:11]
	v_mfma_f32_16x16x32_bf16 v[48:51], v[144:147], v[168:171], v[48:51]
	v_mfma_f32_16x16x32_bf16 v[48:51], v[156:159], v[172:175], v[48:51]
	v_mfma_f32_16x16x32_bf16 v[40:43], v[160:163], v[168:171], v[40:43]
	v_mfma_f32_16x16x32_bf16 v[40:43], v[164:167], v[172:175], v[40:43]
	v_mfma_f32_16x16x32_bf16 v[32:35], v[144:147], v[176:179], v[32:35]
	v_mfma_f32_16x16x32_bf16 v[32:35], v[156:159], v[180:183], v[32:35]
	v_mfma_f32_16x16x32_bf16 v[24:27], v[160:163], v[176:179], v[24:27]
	v_mfma_f32_16x16x32_bf16 v[24:27], v[164:167], v[180:183], v[24:27]
	v_mfma_f32_16x16x32_bf16 v[16:19], v[144:147], v[184:187], v[16:19]
	v_mfma_f32_16x16x32_bf16 v[16:19], v[156:159], v[188:191], v[16:19]
	v_mfma_f32_16x16x32_bf16 v[12:15], v[160:163], v[184:187], v[12:15]
	v_mfma_f32_16x16x32_bf16 v[12:15], v[164:167], v[188:191], v[12:15]
	v_mfma_f32_16x16x32_bf16 v[4:7], v[144:147], v[192:195], v[4:7]
	v_mfma_f32_16x16x32_bf16 v[4:7], v[156:159], v[200:203], v[4:7]
	v_mfma_f32_16x16x32_bf16 v[0:3], v[160:163], v[192:195], v[0:3]
	v_mfma_f32_16x16x32_bf16 v[0:3], v[164:167], v[200:203], v[0:3]
	s_setprio 0
	s_barrier
	s_add_i32 s49, s49, 2
	s_add_u32 s13, s13, 0x100
	s_addc_u32 s21, s21, 0
	s_add_u32 s47, s47, 0x100
	s_addc_u32 s48, s48, 0
	s_cmp_gt_u32 s49, 5
	s_cbranch_scc0 .LBB0_1579
	s_and_b64 vcc, exec, s[60:61]
	s_cbranch_vccz .LBB0_1582
	s_barrier
